# skip the two protective-nothing vmcnt waits in K-iteration 0 of non-first tiles; attention group A LDS reads de-serialised
# baseline (speedup 1.0000x reference)
; #define STAGE(bufoff, GB) do { const char* g_ = (GB); \
;         _Pragma("unroll") for (int i_ = 0; i_ < 2; ++i_) __builtin_amdgcn_global_load_lds((const unsigned*)(g_ + voff[i_]), (LAS3 unsigned*)(L + (bufoff) + stoff + i_ * 8192), 16, 0, 0); } while (0)
; #define LDA(dst, b, h) do { _Pragma("unroll") for (int m = 0; m < 4; ++m) _Pragma("unroll") for (int k = 0; k < 2; ++k) dst[m][k] = *(const LAS3 bf16x8*)(L + SA(b, h) + aoff + m * 2048 + k * 1024); } while (0)
; #define LDB(dst, b, h) do { _Pragma("unroll") for (int n = 0; n < 2; ++n) _Pragma("unroll") for (int k = 0; k < 2; ++k) dst[n][k] = *(const LAS3 bf16x8*)(L + SB(b, h) + boff + n * 2048 + k * 1024); } while (0)
; #define WAIT_V(n) asm volatile("s_waitcnt vmcnt(" #n ")" ::: "memory")
; #define WAIT_L(n) asm volatile("s_waitcnt lgkmcnt(" #n ")" ::: "memory")
; #define BAR __builtin_amdgcn_s_barrier()
; #define SCHED __builtin_amdgcn_sched_barrier(0)
; template <int EPI>
; DI void gemm_phase(const bf16_t* __restrict__ A, const bf16_t* __restrict__ Bt, const int K, const int N, const Params& p, const int layer_j, char* lds) {
;     ...
;         for (int t = 0; t < nt; t += 2) {
;             const bool last = (t == nt - 2);
;             const char* a1 = cA + (size_t)(t + 1) * kstep;
;             const char* a2 = last ? nA : cA + (size_t)(t + 2) * kstep; const char* b2 = last ? nB : cB + (size_t)(t + 2) * kstep;
;             const char* a3 = a2 + kstep; const char* b3 = b2 + kstep;
;             LDB(B0, 0, 0); LDB(B1, 0, 1); SCHED; LDA(At, 0, 0); STAGE(SA(1, 1), a1 + hstep);
;             WAIT_V(8); WAIT_L(0); BAR; MMA(0, 0, At, B0); MMA(0, 1, At, B1); BAR; SCHED;
;             LDA(At, 0, 1); STAGE(SB(0, 0), b2); STAGE(SB(0, 1), b2 + hstep); STAGE(SA(0, 0), a2);
;             WAIT_V(8); WAIT_L(0); BAR; MMA(1, 0, At, B0); MMA(1, 1, At, B1); BAR; SCHED;
.LBB0_43:
	s_cmp_eq_u32 s87, 1
	s_cselect_b32 s100, 1, s28
	v_add_u32_e32 v164, 0x10000, v138
	v_add_u32_e32 v180, 0x14000, v138
	s_add_u32 s6, s38, s28
	ds_read_b128 v[152:155], v164
	ds_read_b128 v[156:159], v164 offset:1024
	ds_read_b128 v[160:163], v164 offset:2048
	ds_read_b128 v[164:167], v164 offset:3072
	ds_read_b128 v[168:171], v180
	ds_read_b128 v[172:175], v180 offset:1024
	ds_read_b128 v[176:179], v180 offset:2048
	ds_read_b128 v[180:183], v180 offset:3072
	s_addc_u32 s7, s39, s29
	s_add_u32 s6, s6, 0x6681100
	s_addc_u32 s7, s7, 0
	s_add_u32 s30, vcc_lo, s28
	s_addc_u32 s31, vcc_hi, s29
	s_cmpk_eq_i32 s28, 0x700
	s_cselect_b32 s35, s17, s7
	s_cselect_b32 s34, s13, s6
	s_cselect_b32 s31, s88, s31
	s_cselect_b32 s30, s25, s30
	v_add_u32_e32 v194, 0xc000, v136
	v_lshl_add_u64 v[192:193], v[134:135], 0, s[28:29]
	v_readfirstlane_b32 s6, v194
	v_add_u32_e32 v194, 0xe000, v136
	s_mov_b32 m0, s6
	v_readfirstlane_b32 s6, v194
	ds_read_b128 v[184:187], v137
	ds_read_b128 v[188:191], v137 offset:1024
	ds_read_b128 v[204:207], v137 offset:2048
	ds_read_b128 v[208:211], v137 offset:3072
	ds_read_b128 v[212:215], v137 offset:4096
	ds_read_b128 v[216:219], v137 offset:5120
	ds_read_b128 v[220:223], v137 offset:6144
	ds_read_b128 v[224:227], v137 offset:7168
	global_load_lds_dwordx4 v[192:193], off
	v_lshl_add_u64 v[192:193], v[132:133], 0, s[28:29]
	s_mov_b32 m0, s6
	s_nop 0
	global_load_lds_dwordx4 v[192:193], off
	s_cmp_eq_u32 s100, 0
	s_cbranch_scc1 .Lskipw_ffn_0
	s_waitcnt vmcnt(8)
.Lskipw_ffn_0:
	s_waitcnt lgkmcnt(0)
	s_barrier
	s_setprio 1
	s_waitcnt lgkmcnt(0)
	v_mfma_f32_16x16x32_bf16 v[126:129], v[152:155], v[184:187], v[126:129]
	v_mfma_f32_16x16x32_bf16 v[118:121], v[160:163], v[184:187], v[118:121]
	v_mfma_f32_16x16x32_bf16 v[110:113], v[152:155], v[204:207], v[110:113]
	v_mfma_f32_16x16x32_bf16 v[102:105], v[160:163], v[204:207], v[102:105]
	v_mfma_f32_16x16x32_bf16 v[94:97], v[152:155], v[212:215], v[94:97]
	v_mfma_f32_16x16x32_bf16 v[86:89], v[160:163], v[212:215], v[86:89]
	v_mfma_f32_16x16x32_bf16 v[78:81], v[152:155], v[220:223], v[78:81]
	v_mfma_f32_16x16x32_bf16 v[70:73], v[160:163], v[220:223], v[70:73]
	v_mfma_f32_16x16x32_bf16 v[126:129], v[156:159], v[188:191], v[126:129]
	v_mfma_f32_16x16x32_bf16 v[118:121], v[164:167], v[188:191], v[118:121]
	v_mfma_f32_16x16x32_bf16 v[110:113], v[156:159], v[208:211], v[110:113]
	v_mfma_f32_16x16x32_bf16 v[102:105], v[164:167], v[208:211], v[102:105]
	v_mfma_f32_16x16x32_bf16 v[94:97], v[156:159], v[216:219], v[94:97]
	v_mfma_f32_16x16x32_bf16 v[86:89], v[164:167], v[216:219], v[86:89]
	v_mfma_f32_16x16x32_bf16 v[78:81], v[156:159], v[224:227], v[78:81]
	v_mfma_f32_16x16x32_bf16 v[70:73], v[164:167], v[224:227], v[70:73]
	s_setprio 0
	s_setprio 1
	v_mfma_f32_16x16x32_bf16 v[122:125], v[168:171], v[184:187], v[122:125]
	v_mfma_f32_16x16x32_bf16 v[114:117], v[176:179], v[184:187], v[114:117]
	v_mfma_f32_16x16x32_bf16 v[106:109], v[168:171], v[204:207], v[106:109]
	v_mfma_f32_16x16x32_bf16 v[98:101], v[176:179], v[204:207], v[98:101]
	v_mfma_f32_16x16x32_bf16 v[90:93], v[168:171], v[212:215], v[90:93]
	v_mfma_f32_16x16x32_bf16 v[82:85], v[176:179], v[212:215], v[82:85]
	v_mfma_f32_16x16x32_bf16 v[74:77], v[168:171], v[220:223], v[74:77]
	v_mfma_f32_16x16x32_bf16 v[66:69], v[176:179], v[220:223], v[66:69]
	v_mfma_f32_16x16x32_bf16 v[122:125], v[172:175], v[188:191], v[122:125]
	v_mfma_f32_16x16x32_bf16 v[114:117], v[180:183], v[188:191], v[114:117]
	v_mfma_f32_16x16x32_bf16 v[106:109], v[172:175], v[208:211], v[106:109]
	v_mfma_f32_16x16x32_bf16 v[98:101], v[180:183], v[208:211], v[98:101]
	v_mfma_f32_16x16x32_bf16 v[90:93], v[172:175], v[216:219], v[90:93]
	v_mfma_f32_16x16x32_bf16 v[82:85], v[180:183], v[216:219], v[82:85]
	v_mfma_f32_16x16x32_bf16 v[74:77], v[172:175], v[224:227], v[74:77]
	v_mfma_f32_16x16x32_bf16 v[66:69], v[180:183], v[224:227], v[66:69]
	s_setprio 0
	s_barrier
	v_readfirstlane_b32 s6, v139
	v_lshl_add_u64 v[192:193], s[30:31], 0, v[32:33]
	s_mov_b32 m0, s6
	v_readfirstlane_b32 s6, v140
	ds_read_b128 v[184:187], v137 offset:16384
	ds_read_b128 v[188:191], v137 offset:17408
	ds_read_b128 v[204:207], v137 offset:18432
	ds_read_b128 v[208:211], v137 offset:19456
	ds_read_b128 v[212:215], v137 offset:20480
	ds_read_b128 v[216:219], v137 offset:21504
	ds_read_b128 v[220:223], v137 offset:22528
	ds_read_b128 v[224:227], v137 offset:23552
	global_load_lds_dwordx4 v[192:193], off
	s_mov_b32 m0, s6
	s_add_u32 s6, s30, 0x40000
	v_lshl_add_u64 v[194:195], s[30:31], 0, v[130:131]
	s_addc_u32 s7, s31, 0
	v_readfirstlane_b32 s10, v141
	global_load_lds_dwordx4 v[194:195], off
	v_lshl_add_u64 v[228:229], s[6:7], 0, v[32:33]
	s_mov_b32 m0, s10
	v_lshl_add_u64 v[230:231], s[34:35], 0, v[130:131]
	global_load_lds_dwordx4 v[228:229], off
	v_lshl_add_u64 v[228:229], s[6:7], 0, v[130:131]
	v_readfirstlane_b32 s6, v142
	s_mov_b32 m0, s6
	v_readfirstlane_b32 s6, v136
	global_load_lds_dwordx4 v[228:229], off
	v_lshl_add_u64 v[228:229], s[34:35], 0, v[32:33]
	s_mov_b32 m0, s6
	v_readfirstlane_b32 s6, v143
	global_load_lds_dwordx4 v[228:229], off
	s_mov_b32 m0, s6
	s_nop 0
	global_load_lds_dwordx4 v[230:231], off
	s_cmp_eq_u32 s100, 0
	s_cbranch_scc1 .Lskipw_ffn_1
	s_waitcnt vmcnt(8)
; #define STAGE(bufoff, GB) do { const char* g_ = (GB); \
;         _Pragma("unroll") for (int i_ = 0; i_ < 2; ++i_) __builtin_amdgcn_global_load_lds((const unsigned*)(g_ + voff[i_]), (LAS3 unsigned*)(L + (bufoff) + stoff + i_ * 8192), 16, 0, 0); } while (0)
; #define LDA(dst, b, h) do { _Pragma("unroll") for (int m = 0; m < 4; ++m) _Pragma("unroll") for (int k = 0; k < 2; ++k) dst[m][k] = *(const LAS3 bf16x8*)(L + SA(b, h) + aoff + m * 2048 + k * 1024); } while (0)
; #define LDB(dst, b, h) do { _Pragma("unroll") for (int n = 0; n < 2; ++n) _Pragma("unroll") for (int k = 0; k < 2; ++k) dst[n][k] = *(const LAS3 bf16x8*)(L + SB(b, h) + boff + n * 2048 + k * 1024); } while (0)
; #define WAIT_V(n) asm volatile("s_waitcnt vmcnt(" #n ")" ::: "memory")
; #define WAIT_L(n) asm volatile("s_waitcnt lgkmcnt(" #n ")" ::: "memory")
; #define BAR __builtin_amdgcn_s_barrier()
; #define SCHED __builtin_amdgcn_sched_barrier(0)
; template <int EPI>
; DI void gemm_phase(const bf16_t* __restrict__ A, const bf16_t* __restrict__ Bt, const int K, const int N, const Params& p, const int layer_j, char* lds) {
;     ...
;             WAIT_V(8); WAIT_L(0); BAR; MMA(1, 0, At, B0); MMA(1, 1, At, B1); BAR; SCHED;
;             LDB(B0, 1, 0); LDB(B1, 1, 1); SCHED; LDA(At, 1, 0); STAGE(SA(0, 1), a2 + hstep);
;             WAIT_V(8); WAIT_L(0); BAR; MMA(0, 0, At, B0); MMA(0, 1, At, B1); BAR; SCHED;
.Lskipw_ffn_1:
	s_waitcnt lgkmcnt(0)
	s_barrier
	s_setprio 1
	s_waitcnt lgkmcnt(0)
	v_mfma_f32_16x16x32_bf16 v[62:65], v[152:155], v[184:187], v[62:65]
	v_mfma_f32_16x16x32_bf16 v[54:57], v[160:163], v[184:187], v[54:57]
	v_mfma_f32_16x16x32_bf16 v[46:49], v[152:155], v[204:207], v[46:49]
	v_mfma_f32_16x16x32_bf16 v[38:41], v[160:163], v[204:207], v[38:41]
	v_mfma_f32_16x16x32_bf16 v[24:27], v[152:155], v[212:215], v[24:27]
	v_mfma_f32_16x16x32_bf16 v[16:19], v[160:163], v[212:215], v[16:19]
	v_mfma_f32_16x16x32_bf16 v[8:11], v[152:155], v[220:223], v[8:11]
	v_mfma_f32_16x16x32_bf16 v[0:3], v[160:163], v[220:223], v[0:3]
	v_mfma_f32_16x16x32_bf16 v[62:65], v[156:159], v[188:191], v[62:65]
	v_mfma_f32_16x16x32_bf16 v[54:57], v[164:167], v[188:191], v[54:57]
	v_mfma_f32_16x16x32_bf16 v[46:49], v[156:159], v[208:211], v[46:49]
	v_mfma_f32_16x16x32_bf16 v[38:41], v[164:167], v[208:211], v[38:41]
	v_mfma_f32_16x16x32_bf16 v[24:27], v[156:159], v[216:219], v[24:27]
	v_mfma_f32_16x16x32_bf16 v[16:19], v[164:167], v[216:219], v[16:19]
	v_mfma_f32_16x16x32_bf16 v[8:11], v[156:159], v[224:227], v[8:11]
	v_mfma_f32_16x16x32_bf16 v[0:3], v[164:167], v[224:227], v[0:3]
	s_setprio 0
	s_setprio 1
	v_mfma_f32_16x16x32_bf16 v[58:61], v[168:171], v[184:187], v[58:61]
	v_mfma_f32_16x16x32_bf16 v[50:53], v[176:179], v[184:187], v[50:53]
	v_mfma_f32_16x16x32_bf16 v[42:45], v[168:171], v[204:207], v[42:45]
	v_mfma_f32_16x16x32_bf16 v[28:31], v[176:179], v[204:207], v[28:31]
	v_mfma_f32_16x16x32_bf16 v[34:37], v[168:171], v[212:215], v[34:37]
	v_mfma_f32_16x16x32_bf16 v[20:23], v[176:179], v[212:215], v[20:23]
	v_mfma_f32_16x16x32_bf16 v[12:15], v[168:171], v[220:223], v[12:15]
	v_mfma_f32_16x16x32_bf16 v[4:7], v[176:179], v[220:223], v[4:7]
	v_mfma_f32_16x16x32_bf16 v[58:61], v[172:175], v[188:191], v[58:61]
	v_mfma_f32_16x16x32_bf16 v[50:53], v[180:183], v[188:191], v[50:53]
	v_mfma_f32_16x16x32_bf16 v[42:45], v[172:175], v[208:211], v[42:45]
	v_mfma_f32_16x16x32_bf16 v[28:31], v[180:183], v[208:211], v[28:31]
	v_mfma_f32_16x16x32_bf16 v[34:37], v[172:175], v[216:219], v[34:37]
	v_mfma_f32_16x16x32_bf16 v[20:23], v[180:183], v[216:219], v[20:23]
	v_mfma_f32_16x16x32_bf16 v[12:15], v[172:175], v[224:227], v[12:15]
	v_mfma_f32_16x16x32_bf16 v[4:7], v[180:183], v[224:227], v[4:7]
	s_setprio 0
	s_barrier
	v_add_u32_e32 v164, 0x18000, v138
	v_add_u32_e32 v180, 0x1c000, v138
	ds_read_b128 v[152:155], v164
	ds_read_b128 v[156:159], v164 offset:1024
	ds_read_b128 v[160:163], v164 offset:2048
	ds_read_b128 v[164:167], v164 offset:3072
	ds_read_b128 v[168:171], v180
	ds_read_b128 v[172:175], v180 offset:1024
	ds_read_b128 v[176:179], v180 offset:2048
	ds_read_b128 v[180:183], v180 offset:3072
	s_add_u32 s6, s34, 0x40000
	s_addc_u32 s7, s35, 0
	v_readfirstlane_b32 s10, v144
	v_lshl_add_u64 v[232:233], s[6:7], 0, v[32:33]
	s_mov_b32 m0, s10
	ds_read_b128 v[184:187], v137 offset:32768
	ds_read_b128 v[188:191], v137 offset:33792
	ds_read_b128 v[204:207], v137 offset:34816
	ds_read_b128 v[208:211], v137 offset:35840
	ds_read_b128 v[212:215], v137 offset:36864
	ds_read_b128 v[216:219], v137 offset:37888
	ds_read_b128 v[220:223], v137 offset:38912
	ds_read_b128 v[224:227], v137 offset:39936
	global_load_lds_dwordx4 v[232:233], off
	v_lshl_add_u64 v[232:233], s[6:7], 0, v[130:131]
	v_readfirstlane_b32 s6, v145
	s_mov_b32 m0, s6
	s_nop 0
	global_load_lds_dwordx4 v[232:233], off
	s_waitcnt vmcnt(8)
	s_waitcnt lgkmcnt(0)
	s_barrier
	s_setprio 1
	s_waitcnt lgkmcnt(0)
	v_mfma_f32_16x16x32_bf16 v[126:129], v[152:155], v[184:187], v[126:129]
	v_mfma_f32_16x16x32_bf16 v[118:121], v[160:163], v[184:187], v[118:121]
	v_mfma_f32_16x16x32_bf16 v[110:113], v[152:155], v[204:207], v[110:113]
	v_mfma_f32_16x16x32_bf16 v[102:105], v[160:163], v[204:207], v[102:105]
	v_mfma_f32_16x16x32_bf16 v[94:97], v[152:155], v[212:215], v[94:97]
	v_mfma_f32_16x16x32_bf16 v[86:89], v[160:163], v[212:215], v[86:89]
	v_mfma_f32_16x16x32_bf16 v[78:81], v[152:155], v[220:223], v[78:81]
	v_mfma_f32_16x16x32_bf16 v[70:73], v[160:163], v[220:223], v[70:73]
	v_mfma_f32_16x16x32_bf16 v[126:129], v[156:159], v[188:191], v[126:129]
	v_mfma_f32_16x16x32_bf16 v[118:121], v[164:167], v[188:191], v[118:121]
	v_mfma_f32_16x16x32_bf16 v[110:113], v[156:159], v[208:211], v[110:113]
	v_mfma_f32_16x16x32_bf16 v[102:105], v[164:167], v[208:211], v[102:105]
	v_mfma_f32_16x16x32_bf16 v[94:97], v[156:159], v[216:219], v[94:97]
	v_mfma_f32_16x16x32_bf16 v[86:89], v[164:167], v[216:219], v[86:89]
	v_mfma_f32_16x16x32_bf16 v[78:81], v[156:159], v[224:227], v[78:81]
	v_mfma_f32_16x16x32_bf16 v[70:73], v[164:167], v[224:227], v[70:73]
	s_setprio 0
	s_setprio 1
	v_mfma_f32_16x16x32_bf16 v[122:125], v[168:171], v[184:187], v[122:125]
	v_mfma_f32_16x16x32_bf16 v[114:117], v[176:179], v[184:187], v[114:117]
	v_mfma_f32_16x16x32_bf16 v[106:109], v[168:171], v[204:207], v[106:109]
	v_mfma_f32_16x16x32_bf16 v[98:101], v[176:179], v[204:207], v[98:101]
	v_mfma_f32_16x16x32_bf16 v[90:93], v[168:171], v[212:215], v[90:93]
	v_mfma_f32_16x16x32_bf16 v[82:85], v[176:179], v[212:215], v[82:85]
	v_mfma_f32_16x16x32_bf16 v[74:77], v[168:171], v[220:223], v[74:77]
	v_mfma_f32_16x16x32_bf16 v[66:69], v[176:179], v[220:223], v[66:69]
	v_mfma_f32_16x16x32_bf16 v[122:125], v[172:175], v[188:191], v[122:125]
	v_mfma_f32_16x16x32_bf16 v[114:117], v[180:183], v[188:191], v[114:117]
	v_mfma_f32_16x16x32_bf16 v[106:109], v[172:175], v[208:211], v[106:109]
	v_mfma_f32_16x16x32_bf16 v[98:101], v[180:183], v[208:211], v[98:101]
	v_mfma_f32_16x16x32_bf16 v[90:93], v[172:175], v[216:219], v[90:93]
	v_mfma_f32_16x16x32_bf16 v[82:85], v[180:183], v[216:219], v[82:85]
	v_mfma_f32_16x16x32_bf16 v[74:77], v[172:175], v[224:227], v[74:77]
	v_mfma_f32_16x16x32_bf16 v[66:69], v[180:183], v[224:227], v[66:69]
	s_setprio 0
	s_barrier
; #define STAGE(bufoff, GB) do { const char* g_ = (GB); \
;         _Pragma("unroll") for (int i_ = 0; i_ < 2; ++i_) __builtin_amdgcn_global_load_lds((const unsigned*)(g_ + voff[i_]), (LAS3 unsigned*)(L + (bufoff) + stoff + i_ * 8192), 16, 0, 0); } while (0)
; #define LDA(dst, b, h) do { _Pragma("unroll") for (int m = 0; m < 4; ++m) _Pragma("unroll") for (int k = 0; k < 2; ++k) dst[m][k] = *(const LAS3 bf16x8*)(L + SA(b, h) + aoff + m * 2048 + k * 1024); } while (0)
; #define WAIT_V(n) asm volatile("s_waitcnt vmcnt(" #n ")" ::: "memory")
; #define WAIT_L(n) asm volatile("s_waitcnt lgkmcnt(" #n ")" ::: "memory")
; #define BAR __builtin_amdgcn_s_barrier()
; #define SCHED __builtin_amdgcn_sched_barrier(0)
; template <int EPI>
; DI void gemm_phase(const bf16_t* __restrict__ A, const bf16_t* __restrict__ Bt, const int K, const int N, const Params& p, const int layer_j, char* lds) {
;     ...
;             LDA(At, 1, 1); STAGE(SB(1, 0), b3); STAGE(SB(1, 1), b3 + hstep); STAGE(SA(1, 0), a3);
;             WAIT_V(8); WAIT_L(0); BAR; MMA(1, 0, At, B0); MMA(1, 1, At, B1); BAR; SCHED;
;         }
	v_readfirstlane_b32 s6, v146
	v_lshl_add_u64 v[192:193], v[192:193], 0, s[94:95]
	s_mov_b32 m0, s6
	v_readfirstlane_b32 s6, v147
	ds_read_b128 v[184:187], v137 offset:49152
	ds_read_b128 v[188:191], v137 offset:50176
	ds_read_b128 v[204:207], v137 offset:51200
	ds_read_b128 v[208:211], v137 offset:52224
	ds_read_b128 v[212:215], v137 offset:53248
	ds_read_b128 v[216:219], v137 offset:54272
	ds_read_b128 v[220:223], v137 offset:55296
	ds_read_b128 v[224:227], v137 offset:56320
	global_load_lds_dwordx4 v[192:193], off
	s_mov_b32 m0, s6
	s_add_u32 s6, s30, 0x40080
	v_lshl_add_u64 v[192:193], v[194:195], 0, s[94:95]
	s_addc_u32 s7, s31, 0
	v_readfirstlane_b32 s10, v150
	global_load_lds_dwordx4 v[192:193], off
	v_lshl_add_u64 v[192:193], s[6:7], 0, v[32:33]
	s_mov_b32 m0, s10
	s_nop 0
	global_load_lds_dwordx4 v[192:193], off
	v_lshl_add_u64 v[192:193], s[6:7], 0, v[130:131]
	v_readfirstlane_b32 s6, v151
	s_mov_b32 m0, s6
	v_readfirstlane_b32 s6, v148
	global_load_lds_dwordx4 v[192:193], off
	v_lshl_add_u64 v[192:193], v[228:229], 0, s[94:95]
	s_mov_b32 m0, s6
	v_readfirstlane_b32 s6, v149
	global_load_lds_dwordx4 v[192:193], off
	v_lshl_add_u64 v[192:193], v[230:231], 0, s[94:95]
	s_mov_b32 m0, s6
	s_nop 0
	global_load_lds_dwordx4 v[192:193], off
	s_waitcnt vmcnt(8)
	s_waitcnt lgkmcnt(0)
	s_barrier
	s_setprio 1
	s_waitcnt lgkmcnt(0)
	v_mfma_f32_16x16x32_bf16 v[62:65], v[152:155], v[184:187], v[62:65]
	v_mfma_f32_16x16x32_bf16 v[54:57], v[160:163], v[184:187], v[54:57]
	v_mfma_f32_16x16x32_bf16 v[46:49], v[152:155], v[204:207], v[46:49]
	v_mfma_f32_16x16x32_bf16 v[38:41], v[160:163], v[204:207], v[38:41]
	v_mfma_f32_16x16x32_bf16 v[24:27], v[152:155], v[212:215], v[24:27]
	v_mfma_f32_16x16x32_bf16 v[16:19], v[160:163], v[212:215], v[16:19]
	v_mfma_f32_16x16x32_bf16 v[8:11], v[152:155], v[220:223], v[8:11]
	v_mfma_f32_16x16x32_bf16 v[0:3], v[160:163], v[220:223], v[0:3]
	v_mfma_f32_16x16x32_bf16 v[62:65], v[156:159], v[188:191], v[62:65]
	v_mfma_f32_16x16x32_bf16 v[54:57], v[164:167], v[188:191], v[54:57]
	v_mfma_f32_16x16x32_bf16 v[46:49], v[156:159], v[208:211], v[46:49]
	v_mfma_f32_16x16x32_bf16 v[38:41], v[164:167], v[208:211], v[38:41]
	v_mfma_f32_16x16x32_bf16 v[24:27], v[156:159], v[216:219], v[24:27]
	v_mfma_f32_16x16x32_bf16 v[16:19], v[164:167], v[216:219], v[16:19]
	v_mfma_f32_16x16x32_bf16 v[8:11], v[156:159], v[224:227], v[8:11]
	v_mfma_f32_16x16x32_bf16 v[0:3], v[164:167], v[224:227], v[0:3]
	s_setprio 0
	s_setprio 1
	v_mfma_f32_16x16x32_bf16 v[58:61], v[168:171], v[184:187], v[58:61]
	v_mfma_f32_16x16x32_bf16 v[50:53], v[176:179], v[184:187], v[50:53]
	v_mfma_f32_16x16x32_bf16 v[42:45], v[168:171], v[204:207], v[42:45]
	v_mfma_f32_16x16x32_bf16 v[28:31], v[176:179], v[204:207], v[28:31]
	v_mfma_f32_16x16x32_bf16 v[34:37], v[168:171], v[212:215], v[34:37]
	v_mfma_f32_16x16x32_bf16 v[20:23], v[176:179], v[212:215], v[20:23]
	v_mfma_f32_16x16x32_bf16 v[12:15], v[168:171], v[220:223], v[12:15]
	v_mfma_f32_16x16x32_bf16 v[4:7], v[176:179], v[220:223], v[4:7]
	v_mfma_f32_16x16x32_bf16 v[58:61], v[172:175], v[188:191], v[58:61]
	v_mfma_f32_16x16x32_bf16 v[50:53], v[180:183], v[188:191], v[50:53]
	v_mfma_f32_16x16x32_bf16 v[42:45], v[172:175], v[208:211], v[42:45]
	v_mfma_f32_16x16x32_bf16 v[28:31], v[180:183], v[208:211], v[28:31]
	v_mfma_f32_16x16x32_bf16 v[34:37], v[172:175], v[216:219], v[34:37]
	v_mfma_f32_16x16x32_bf16 v[20:23], v[180:183], v[216:219], v[20:23]
	v_mfma_f32_16x16x32_bf16 v[12:15], v[172:175], v[224:227], v[12:15]
	v_mfma_f32_16x16x32_bf16 v[4:7], v[180:183], v[224:227], v[4:7]
	s_setprio 0
	s_barrier
	s_add_i32 s37, s37, 2
	s_add_u32 s28, s28, 0x100
	s_addc_u32 s29, s29, 0
	s_cmp_gt_u32 s37, 13
	s_cbranch_scc0 .LBB0_43
	v_readlane_b32 s6, v254, 12
	v_readlane_b32 s7, v254, 13
	s_and_b64 vcc, exec, s[6:7]
	s_cbranch_vccz .LBB0_46
	s_barrier

; #define MFMA32(a, b, c) __builtin_amdgcn_mfma_f32_32x32x16_bf16((a), (b), (c), 0, 0, 0)
; template <int DV, bool MULT>
; DI void attn_pass(const bf16_t* __restrict__ Kg, const bf16_t* __restrict__ VTg, const bf16x8 (&qf)[4], const int q0, f32x16 (&O)[DV / 32], float& m_run, float& l_run, char* lds, const int gw) {
;     ...
;             float ps = 0.f;
; #pragma unroll
;             for (int k2 = 0; k2 < 2; ++k2)
; #pragma unroll
;                 for (int i = 0; i < 16; ++i) { const float pe = __builtin_amdgcn_exp2f(st[k2][i] - m_run); st[k2][i] = pe; ps += pe; }
;             l_run += ps;
; #pragma unroll
;             for (int ks2 = 0; ks2 < 4; ++ks2) {
;                 const bf16x8 pb = pack8(st[ks2 >> 1], ks2 & 1);
; #pragma unroll
;                 for (int dt = 0; dt < DV / 32; ++dt) {
;                     const bf16x8 a = *(const bf16x8*)(Vh + (32 * dt + l31) * LDV + 16 * ks2 + 8 * hh);
;                     O[dt] = MFMA32(a, pb, O[dt]);
;                 }
;             }
.LBB0_211:
	s_mul_i32 s14, s38, 0xffffdc80
	v_add3_u32 v244, v217, s14, v211
	ds_read_b128 v[72:75], v244 offset:18432
	ds_read_b128 v[88:91], v244 offset:27136
	ds_read_b128 v[92:95], v244 offset:27168
	ds_read_b128 v[76:79], v244 offset:18464
	ds_read_b128 v[80:83], v244 offset:18496
	ds_read_b128 v[236:239], v244 offset:27200
	ds_read_b128 v[84:87], v244 offset:18528
	ds_read_b128 v[240:243], v244 offset:27232
	v_sub_f32_e32 v0, v0, v66
	v_exp_f32_e32 v0, v0
	v_sub_f32_e32 v1, v1, v66
	v_exp_f32_e32 v1, v1
	v_sub_f32_e32 v2, v2, v66
	v_exp_f32_e32 v2, v2
	v_sub_f32_e32 v3, v3, v66
	v_exp_f32_e32 v3, v3
	v_sub_f32_e32 v4, v4, v66
	v_add_f32_e32 v67, 0, v0
	v_exp_f32_e32 v4, v4
	v_sub_f32_e32 v5, v5, v66
	v_add_f32_e32 v67, v1, v67
	v_exp_f32_e32 v5, v5
	v_sub_f32_e32 v6, v6, v66
	v_add_f32_e32 v67, v2, v67
	v_exp_f32_e32 v6, v6
	v_sub_f32_e32 v7, v7, v66
	v_add_f32_e32 v67, v3, v67
	v_exp_f32_e32 v7, v7
	v_sub_f32_e32 v8, v8, v66
	v_add_f32_e32 v67, v4, v67
	v_exp_f32_e32 v68, v8
	v_add_f32_e32 v67, v5, v67
	v_add_f32_e32 v67, v6, v67
	v_add_f32_e32 v67, v7, v67
	v_sub_f32_e32 v9, v9, v66
	v_add_f32_e32 v8, v68, v67
	v_exp_f32_e32 v67, v9
	v_sub_f32_e32 v9, v10, v66
	v_exp_f32_e32 v69, v9
	v_sub_f32_e32 v9, v11, v66
	v_exp_f32_e32 v70, v9
	v_sub_f32_e32 v9, v12, v66
	v_exp_f32_e32 v12, v9
	v_sub_f32_e32 v9, v13, v66
	v_add_f32_e32 v8, v67, v8
	v_exp_f32_e32 v13, v9
	v_sub_f32_e32 v9, v14, v66
	v_add_f32_e32 v8, v69, v8
	v_exp_f32_e32 v14, v9
	v_sub_f32_e32 v9, v15, v66
	v_add_f32_e32 v8, v70, v8
	v_exp_f32_e32 v15, v9
	v_sub_f32_e32 v9, v16, v66
	v_add_f32_e32 v8, v12, v8
	v_exp_f32_e32 v16, v9
	v_sub_f32_e32 v9, v17, v66
	v_add_f32_e32 v8, v13, v8
	v_exp_f32_e32 v17, v9
	v_sub_f32_e32 v9, v18, v66
	v_add_f32_e32 v8, v14, v8
	v_exp_f32_e32 v18, v9
	v_sub_f32_e32 v9, v19, v66
	v_add_f32_e32 v8, v15, v8
	v_exp_f32_e32 v19, v9
	v_sub_f32_e32 v9, v20, v66
	v_add_f32_e32 v8, v16, v8
	v_exp_f32_e32 v20, v9
	v_sub_f32_e32 v9, v21, v66
	v_add_f32_e32 v8, v17, v8
	v_exp_f32_e32 v21, v9
	v_sub_f32_e32 v9, v22, v66
	v_add_f32_e32 v8, v18, v8
	v_exp_f32_e32 v22, v9
	v_sub_f32_e32 v9, v23, v66
	v_add_f32_e32 v8, v19, v8
	v_exp_f32_e32 v23, v9
	v_sub_f32_e32 v9, v24, v66
	v_add_f32_e32 v8, v20, v8
	v_exp_f32_e32 v24, v9
	v_sub_f32_e32 v9, v25, v66
	v_add_f32_e32 v8, v21, v8
	v_exp_f32_e32 v25, v9
	v_sub_f32_e32 v9, v26, v66
	v_add_f32_e32 v8, v22, v8
	v_exp_f32_e32 v26, v9
	v_sub_f32_e32 v9, v27, v66
	v_add_f32_e32 v8, v23, v8
	v_exp_f32_e32 v27, v9
	v_sub_f32_e32 v9, v28, v66
	v_add_f32_e32 v8, v24, v8
	v_exp_f32_e32 v28, v9
	v_sub_f32_e32 v9, v29, v66
	v_add_f32_e32 v8, v25, v8
	v_exp_f32_e32 v29, v9
	v_sub_f32_e32 v9, v30, v66
	v_add_f32_e32 v8, v26, v8
	v_exp_f32_e32 v30, v9
	v_sub_f32_e32 v9, v31, v66
	v_add_f32_e32 v8, v27, v8
	v_exp_f32_e32 v31, v9
	v_add_f32_e32 v8, v28, v8
	v_add_f32_e32 v8, v29, v8
	v_add_f32_e32 v8, v30, v8
	s_mul_i32 s14, s38, 0xffffdc80
	v_add_f32_e32 v8, v31, v8
	v_add3_u32 v66, v217, s14, v211
	v_add_f32_e32 v209, v209, v8
	v_cvt_pk_bf16_f32 v0, v0, v1
	v_cvt_pk_bf16_f32 v1, v2, v3
	v_cvt_pk_bf16_f32 v2, v4, v5
	v_cvt_pk_bf16_f32 v3, v6, v7
	s_waitcnt lgkmcnt(0)
	s_nop 0
	v_mfma_f32_32x32x16_bf16 v[50:65], v[72:75], v[0:3], v[50:65]
	v_mfma_f32_32x32x16_bf16 v[34:49], v[88:91], v[0:3], v[34:49]
	v_cvt_pk_bf16_f32 v0, v68, v67
	v_cvt_pk_bf16_f32 v1, v69, v70
	v_cvt_pk_bf16_f32 v2, v12, v13
	v_cvt_pk_bf16_f32 v3, v14, v15
	s_nop 1
	v_mfma_f32_32x32x16_bf16 v[34:49], v[92:95], v[0:3], v[34:49]
	v_mfma_f32_32x32x16_bf16 v[50:65], v[76:79], v[0:3], v[50:65]
	v_cvt_pk_bf16_f32 v0, v16, v17
	v_cvt_pk_bf16_f32 v1, v18, v19
	v_cvt_pk_bf16_f32 v2, v20, v21
	v_cvt_pk_bf16_f32 v3, v22, v23
	s_nop 1
	v_mfma_f32_32x32x16_bf16 v[50:65], v[80:83], v[0:3], v[50:65]
	v_mfma_f32_32x32x16_bf16 v[34:49], v[236:239], v[0:3], v[34:49]
	v_cvt_pk_bf16_f32 v0, v24, v25
	v_cvt_pk_bf16_f32 v1, v26, v27
	v_cvt_pk_bf16_f32 v2, v28, v29
	v_cvt_pk_bf16_f32 v3, v30, v31
	s_nop 1
	v_mfma_f32_32x32x16_bf16 v[50:65], v[84:87], v[0:3], v[50:65]
	v_mfma_f32_32x32x16_bf16 v[34:49], v[240:243], v[0:3], v[34:49]

; #define MFMA32(a, b, c) __builtin_amdgcn_mfma_f32_32x32x16_bf16((a), (b), (c), 0, 0, 0)
; DI int crow(int i, int h) { return (i & 3) + 8 * (i >> 2) + 4 * h; }
; template <int DV, bool MULT>
; DI void attn_pass(const bf16_t* __restrict__ Kg, const bf16_t* __restrict__ VTg, const bf16x8 (&qf)[4], const int q0, f32x16 (&O)[DV / 32], float& m_run, float& l_run, char* lds, const int gw) {
;     ...
;         if (kb <= qhi) {
;             f32x16 st[2];
; #pragma unroll
;             for (int k2 = 0; k2 < 2; ++k2) {
; #pragma unroll
;                 for (int i = 0; i < 16; ++i) st[k2][i] = 0.f;
; #pragma unroll
;                 for (int ks = 0; ks < 4; ++ks) { const bf16x8 a = *(const bf16x8*)(Kh + (32 * k2 + l31) * LDK + ks * 16 + 8 * hh); st[k2] = MFMA32(a, qf[ks], st[k2]); }
;             }
;     ...
;             } else {
; #pragma unroll
;                 for (int k2 = 0; k2 < 2; ++k2)
; #pragma unroll
;                     for (int i = 0; i < 16; ++i) {
;                         const int key = kb + 32 * k2 + crow(i, hh); const int dl = qpos - key;
;                         float sv;
;                         if (MULT) {
;                             const int c = (dl >= 0) ? ((dl <= 128 ? 1 : 0) + (((dl & 3) == 0 && dl <= 512) ? 1 : 0) + (((dl & 15) == 0) ? 1 : 0)) : 0;
;                             const float adj = (c == 3) ? 1.5849625007211562f : ((c == 2) ? 1.0f : 0.0f);
;                             sv = (c > 0) ? st[k2][i] + adj : -1e30f;
;                         } else {
;                             sv = (dl >= 0) ? st[k2][i] : -1e30f;
;                         }
;                         st[k2][i] = sv; mx = fmaxf(mx, sv);
;                     }
.LBB0_213:
	s_lshl_b32 s14, s38, 6
	s_or_b32 s28, s14, s88
	v_cmp_le_i32_e32 vcc, s28, v205
	s_and_saveexec_b64 s[24:25], vcc
	s_cbranch_execz .LBB0_212
	s_mul_i32 s14, s38, 0x2400
	v_or_b32_e32 v217, s14, v206
	v_add_u32_e32 v245, v217, v210
	ds_read_b128 v[0:3], v245
	ds_read_b128 v[4:7], v245 offset:32
	ds_read_b128 v[8:11], v245 offset:64
	ds_read_b128 v[12:15], v245 offset:96
	ds_read_b128 v[16:19], v245 offset:4608
	ds_read_b128 v[20:23], v245 offset:4640
	ds_read_b128 v[24:27], v245 offset:4672
	ds_read_b128 v[28:31], v245 offset:4704
	s_add_i32 s14, s28, 0x23f
	v_cmp_ge_i32_e32 vcc, s14, v145
	s_waitcnt lgkmcnt(7)
	v_mfma_f32_32x32x16_bf16 v[82:97], v[0:3], v[98:101], 0
	s_waitcnt lgkmcnt(6)
	v_mfma_f32_32x32x16_bf16 v[82:97], v[4:7], v[102:105], v[82:97]
	s_waitcnt lgkmcnt(5)
	v_mfma_f32_32x32x16_bf16 v[82:97], v[8:11], v[106:109], v[82:97]
	s_waitcnt lgkmcnt(4)
	v_mfma_f32_32x32x16_bf16 v[82:97], v[12:15], v[110:113], v[82:97]
	s_waitcnt lgkmcnt(3)
	v_mfma_f32_32x32x16_bf16 v[66:81], v[16:19], v[98:101], 0
	s_waitcnt lgkmcnt(2)
	v_mfma_f32_32x32x16_bf16 v[66:81], v[20:23], v[102:105], v[66:81]
	s_waitcnt lgkmcnt(1)
	v_mfma_f32_32x32x16_bf16 v[66:81], v[24:27], v[106:109], v[66:81]
	s_waitcnt lgkmcnt(0)
	v_mfma_f32_32x32x16_bf16 v[66:81], v[28:31], v[110:113], v[66:81]
	s_and_saveexec_b64 s[14:15], vcc
	s_xor_b64 s[26:27], exec, s[14:15]
	s_cbranch_execz .LBB0_284
	v_subrev_u32_e32 v0, s28, v207
	v_cmp_gt_i32_e32 vcc, s76, v0
	v_subrev_u32_e32 v0, s28, v205
	s_movk_i32 s14, 0x200
	v_cmp_lt_i32_e64 s[14:15], s14, v0
	s_or_b64 s[14:15], vcc, s[14:15]
	s_and_saveexec_b64 s[64:65], s[14:15]
	s_xor_b64 s[14:15], exec, s[64:65]
	s_cbranch_execz .LBB0_281
	v_subrev_u32_e32 v17, s28, v208
	v_sub_u32_e32 v16, v17, v146
	v_cmp_lt_i32_e32 vcc, -1, v16
	v_mov_b32_e32 v1, 0
	v_and_b32_e32 v18, 15, v16
	v_mov_b32_e32 v0, 0
	s_and_saveexec_b64 s[28:29], vcc
	v_cmp_gt_u32_e32 vcc, s76, v16
	s_nop 1
	v_cndmask_b32_e64 v0, 0, 1, vcc
	v_cmp_gt_u32_e32 vcc, s80, v16
	s_and_b64 s[64:65], s[4:5], vcc
	v_cndmask_b32_e64 v2, 0, 1, s[64:65]
	v_cmp_eq_u32_e32 vcc, 0, v18
	s_nop 1
	v_addc_co_u32_e32 v0, vcc, v2, v0, vcc
	s_or_b64 exec, exec, s[28:29]
	v_sub_u32_e32 v31, v17, v149
	v_cmp_lt_i32_e32 vcc, -1, v31
	v_and_b32_e32 v19, 15, v31
	s_and_saveexec_b64 s[28:29], vcc
	v_cmp_gt_u32_e32 vcc, s76, v31
	s_nop 1
	v_cndmask_b32_e64 v1, 0, 1, vcc
	v_cmp_gt_u32_e32 vcc, s80, v31
	s_and_b64 s[64:65], s[6:7], vcc
	v_cndmask_b32_e64 v2, 0, 1, s[64:65]
	v_cmp_eq_u32_e32 vcc, 0, v19
	s_nop 1
	v_addc_co_u32_e32 v1, vcc, v2, v1, vcc
	s_or_b64 exec, exec, s[28:29]
	v_sub_u32_e32 v219, v17, v152
	v_cmp_lt_i32_e32 vcc, -1, v219
	v_mov_b32_e32 v3, 0
	v_and_b32_e32 v20, 15, v219
	v_mov_b32_e32 v2, 0
	s_and_saveexec_b64 s[28:29], vcc
	v_cmp_gt_u32_e32 vcc, s76, v219
	s_nop 1
	v_cndmask_b32_e64 v2, 0, 1, vcc
	v_cmp_gt_u32_e32 vcc, s80, v219
	s_and_b64 s[64:65], s[8:9], vcc
	v_cndmask_b32_e64 v4, 0, 1, s[64:65]
	v_cmp_eq_u32_e32 vcc, 0, v20
	s_nop 1
	v_addc_co_u32_e32 v2, vcc, v4, v2, vcc
	s_or_b64 exec, exec, s[28:29]
	v_sub_u32_e32 v221, v17, v155
	v_cmp_lt_i32_e32 vcc, -1, v221
	v_and_b32_e32 v21, 15, v221
	s_and_saveexec_b64 s[28:29], vcc
	v_cmp_gt_u32_e32 vcc, s76, v221
	s_nop 1
	v_cndmask_b32_e64 v3, 0, 1, vcc
	v_cmp_gt_u32_e32 vcc, s80, v221
	s_and_b64 s[64:65], s[10:11], vcc
	v_cndmask_b32_e64 v4, 0, 1, s[64:65]
	v_cmp_eq_u32_e32 vcc, 0, v21
	s_nop 1
	v_addc_co_u32_e32 v3, vcc, v4, v3, vcc
	s_or_b64 exec, exec, s[28:29]
	v_sub_u32_e32 v223, v17, v158
	v_cmp_lt_i32_e32 vcc, -1, v223
	v_mov_b32_e32 v5, 0
	v_and_b32_e32 v22, 15, v223
	v_mov_b32_e32 v4, 0
	s_and_saveexec_b64 s[28:29], vcc
	v_cmp_gt_u32_e32 vcc, s76, v223
	s_nop 1
	v_cndmask_b32_e64 v4, 0, 1, vcc
	v_cmp_gt_u32_e32 vcc, s80, v223
	s_and_b64 s[64:65], s[4:5], vcc
	v_cndmask_b32_e64 v6, 0, 1, s[64:65]
	v_cmp_eq_u32_e32 vcc, 0, v22
	s_nop 1
	v_addc_co_u32_e32 v4, vcc, v6, v4, vcc
	s_or_b64 exec, exec, s[28:29]
	v_sub_u32_e32 v224, v17, v164
	v_cmp_lt_i32_e32 vcc, -1, v224
	v_and_b32_e32 v23, 15, v224
	s_and_saveexec_b64 s[28:29], vcc
	v_cmp_gt_u32_e32 vcc, s76, v224
	s_nop 1
	v_cndmask_b32_e64 v5, 0, 1, vcc
	v_cmp_gt_u32_e32 vcc, s80, v224
	s_and_b64 s[64:65], s[6:7], vcc
	v_cndmask_b32_e64 v6, 0, 1, s[64:65]
	v_cmp_eq_u32_e32 vcc, 0, v23
	s_nop 1
	v_addc_co_u32_e32 v5, vcc, v6, v5, vcc
	s_or_b64 exec, exec, s[28:29]
	v_sub_u32_e32 v225, v17, v167
	v_cmp_lt_i32_e32 vcc, -1, v225
	v_mov_b32_e32 v7, 0
	v_and_b32_e32 v24, 15, v225
	v_mov_b32_e32 v6, 0
	s_and_saveexec_b64 s[28:29], vcc
	v_cmp_gt_u32_e32 vcc, s76, v225
	s_nop 1
	v_cndmask_b32_e64 v6, 0, 1, vcc
	v_cmp_gt_u32_e32 vcc, s80, v225
	s_and_b64 s[64:65], s[8:9], vcc
	v_cndmask_b32_e64 v8, 0, 1, s[64:65]
	v_cmp_eq_u32_e32 vcc, 0, v24
	s_nop 1
	v_addc_co_u32_e32 v6, vcc, v8, v6, vcc
	s_or_b64 exec, exec, s[28:29]
	v_sub_u32_e32 v226, v17, v170
	v_cmp_lt_i32_e32 vcc, -1, v226
	v_and_b32_e32 v25, 15, v226
	s_and_saveexec_b64 s[28:29], vcc
	v_cmp_gt_u32_e32 vcc, s76, v226
	s_nop 1
	v_cndmask_b32_e64 v7, 0, 1, vcc
	v_cmp_gt_u32_e32 vcc, s80, v226
	s_and_b64 s[64:65], s[10:11], vcc
	v_cndmask_b32_e64 v8, 0, 1, s[64:65]
	v_cmp_eq_u32_e32 vcc, 0, v25
	s_nop 1
	v_addc_co_u32_e32 v7, vcc, v8, v7, vcc
	s_or_b64 exec, exec, s[28:29]
	v_sub_u32_e32 v227, v17, v173
	v_cmp_lt_i32_e32 vcc, -1, v227
	v_mov_b32_e32 v9, 0
	v_and_b32_e32 v26, 15, v227
	v_mov_b32_e32 v8, 0
	s_and_saveexec_b64 s[28:29], vcc
	v_cmp_gt_u32_e32 vcc, s76, v227
	s_nop 1
	v_cndmask_b32_e64 v8, 0, 1, vcc
	v_cmp_gt_u32_e32 vcc, s80, v227
	s_and_b64 s[64:65], s[4:5], vcc
	v_cndmask_b32_e64 v10, 0, 1, s[64:65]
	v_cmp_eq_u32_e32 vcc, 0, v26
	s_nop 1
	v_addc_co_u32_e32 v8, vcc, v10, v8, vcc
; DI int crow(int i, int h) { return (i & 3) + 8 * (i >> 2) + 4 * h; }
; template <int DV, bool MULT>
; DI void attn_pass(const bf16_t* __restrict__ Kg, const bf16_t* __restrict__ VTg, const bf16x8 (&qf)[4], const int q0, f32x16 (&O)[DV / 32], float& m_run, float& l_run, char* lds, const int gw) {
;     ...
;             } else {
; #pragma unroll
;                 for (int k2 = 0; k2 < 2; ++k2)
; #pragma unroll
;                     for (int i = 0; i < 16; ++i) {
;                         const int key = kb + 32 * k2 + crow(i, hh); const int dl = qpos - key;
;                         float sv;
;                         if (MULT) {
;                             const int c = (dl >= 0) ? ((dl <= 128 ? 1 : 0) + (((dl & 3) == 0 && dl <= 512) ? 1 : 0) + (((dl & 15) == 0) ? 1 : 0)) : 0;
;                             const float adj = (c == 3) ? 1.5849625007211562f : ((c == 2) ? 1.0f : 0.0f);
;                             sv = (c > 0) ? st[k2][i] + adj : -1e30f;
;                         } else {
;                             sv = (dl >= 0) ? st[k2][i] : -1e30f;
;                         }
;                         st[k2][i] = sv; mx = fmaxf(mx, sv);
;                     }
	s_or_b64 exec, exec, s[28:29]
	v_sub_u32_e32 v228, v17, v174
	v_cmp_lt_i32_e32 vcc, -1, v228
	v_and_b32_e32 v27, 15, v228
	s_and_saveexec_b64 s[28:29], vcc
	v_cmp_gt_u32_e32 vcc, s76, v228
	s_nop 1
	v_cndmask_b32_e64 v9, 0, 1, vcc
	v_cmp_gt_u32_e32 vcc, s80, v228
	s_and_b64 s[64:65], s[6:7], vcc
	v_cndmask_b32_e64 v10, 0, 1, s[64:65]
	v_cmp_eq_u32_e32 vcc, 0, v27
	s_nop 1
	v_addc_co_u32_e32 v9, vcc, v10, v9, vcc
	s_or_b64 exec, exec, s[28:29]
	v_sub_u32_e32 v229, v17, v177
	v_cmp_lt_i32_e32 vcc, -1, v229
	v_mov_b32_e32 v11, 0
	v_and_b32_e32 v28, 15, v229
	v_mov_b32_e32 v10, 0
	s_and_saveexec_b64 s[28:29], vcc
	v_cmp_gt_u32_e32 vcc, s76, v229
	s_nop 1
	v_cndmask_b32_e64 v10, 0, 1, vcc
	v_cmp_gt_u32_e32 vcc, s80, v229
	s_and_b64 s[64:65], s[8:9], vcc
	v_cndmask_b32_e64 v12, 0, 1, s[64:65]
	v_cmp_eq_u32_e32 vcc, 0, v28
	s_nop 1
	v_addc_co_u32_e32 v10, vcc, v12, v10, vcc
	s_or_b64 exec, exec, s[28:29]
	v_sub_u32_e32 v230, v17, v180
	v_cmp_lt_i32_e32 vcc, -1, v230
	v_and_b32_e32 v29, 15, v230
	s_and_saveexec_b64 s[28:29], vcc
	v_cmp_gt_u32_e32 vcc, s76, v230
	s_nop 1
	v_cndmask_b32_e64 v11, 0, 1, vcc
	v_cmp_gt_u32_e32 vcc, s80, v230
	s_and_b64 s[64:65], s[10:11], vcc
	v_cndmask_b32_e64 v12, 0, 1, s[64:65]
	v_cmp_eq_u32_e32 vcc, 0, v29
	s_nop 1
	v_addc_co_u32_e32 v11, vcc, v12, v11, vcc
	s_or_b64 exec, exec, s[28:29]
	v_sub_u32_e32 v231, v17, v183
	v_cmp_lt_i32_e32 vcc, -1, v231
	v_mov_b32_e32 v13, 0
	v_and_b32_e32 v30, 15, v231
	v_mov_b32_e32 v12, 0
	s_and_saveexec_b64 s[28:29], vcc
	v_cmp_gt_u32_e32 vcc, s76, v231
	s_nop 1
	v_cndmask_b32_e64 v12, 0, 1, vcc
	v_cmp_gt_u32_e32 vcc, s80, v231
	s_and_b64 s[64:65], s[4:5], vcc
	v_cndmask_b32_e64 v14, 0, 1, s[64:65]
	v_cmp_eq_u32_e32 vcc, 0, v30
	s_nop 1
	v_addc_co_u32_e32 v12, vcc, v14, v12, vcc
	s_or_b64 exec, exec, s[28:29]
	v_sub_u32_e32 v232, v17, v188
	v_cmp_lt_i32_e32 vcc, -1, v232
	v_and_b32_e32 v218, 15, v232
	s_and_saveexec_b64 s[28:29], vcc
	v_cmp_gt_u32_e32 vcc, s76, v232
	s_nop 1
	v_cndmask_b32_e64 v13, 0, 1, vcc
	v_cmp_gt_u32_e32 vcc, s80, v232
	s_and_b64 s[64:65], s[6:7], vcc
	v_cndmask_b32_e64 v14, 0, 1, s[64:65]
	v_cmp_eq_u32_e32 vcc, 0, v218
	s_nop 1
	v_addc_co_u32_e32 v13, vcc, v14, v13, vcc
	s_or_b64 exec, exec, s[28:29]
	v_sub_u32_e32 v233, v17, v191
	v_cmp_lt_i32_e32 vcc, -1, v233
	v_mov_b32_e32 v15, 0
	v_and_b32_e32 v220, 15, v233
	v_mov_b32_e32 v14, 0
	s_and_saveexec_b64 s[28:29], vcc
	v_cmp_gt_u32_e32 vcc, s76, v233
	s_nop 1
	v_cndmask_b32_e64 v14, 0, 1, vcc
	v_cmp_gt_u32_e32 vcc, s80, v233
	s_and_b64 s[64:65], s[8:9], vcc
	v_cndmask_b32_e64 v193, 0, 1, s[64:65]
	v_cmp_eq_u32_e32 vcc, 0, v220
	s_nop 1
	v_addc_co_u32_e32 v14, vcc, v193, v14, vcc
	s_or_b64 exec, exec, s[28:29]
	v_sub_u32_e32 v234, v17, v195
	v_cmp_lt_i32_e32 vcc, -1, v234
	v_and_b32_e32 v222, 15, v234
	s_and_saveexec_b64 s[28:29], vcc
	v_cmp_gt_u32_e32 vcc, s76, v234
	s_nop 1
	v_cndmask_b32_e64 v15, 0, 1, vcc
	v_cmp_gt_u32_e32 vcc, s80, v234
	s_and_b64 s[64:65], s[10:11], vcc
	v_cndmask_b32_e64 v17, 0, 1, s[64:65]
	v_cmp_eq_u32_e32 vcc, 0, v222
	s_nop 1
	v_addc_co_u32_e32 v15, vcc, v17, v15, vcc
	s_or_b64 exec, exec, s[28:29]
	v_subrev_u32_e32 v235, 32, v16
	v_cmp_lt_i32_e32 vcc, -1, v235
	v_mov_b32_e32 v17, 0
	v_mov_b32_e32 v16, 0
	s_and_saveexec_b64 s[28:29], vcc
	v_cmp_gt_u32_e32 vcc, s76, v235
	s_nop 1
	v_cndmask_b32_e64 v16, 0, 1, vcc
	v_cmp_gt_u32_e32 vcc, s80, v235
	s_and_b64 s[64:65], s[4:5], vcc
	v_cndmask_b32_e64 v193, 0, 1, s[64:65]
	v_cmp_eq_u32_e32 vcc, 0, v18
	s_nop 1
	v_addc_co_u32_e32 v16, vcc, v193, v16, vcc
	s_or_b64 exec, exec, s[28:29]
	v_subrev_u32_e32 v18, 32, v31
	v_cmp_lt_i32_e32 vcc, -1, v18
	s_and_saveexec_b64 s[28:29], vcc
	v_cmp_gt_u32_e32 vcc, s76, v18
	s_nop 1
	v_cndmask_b32_e64 v17, 0, 1, vcc
	v_cmp_gt_u32_e32 vcc, s80, v18
	s_and_b64 s[64:65], s[6:7], vcc
	v_cndmask_b32_e64 v18, 0, 1, s[64:65]
	v_cmp_eq_u32_e32 vcc, 0, v19
	s_nop 1
	v_addc_co_u32_e32 v17, vcc, v18, v17, vcc
	s_or_b64 exec, exec, s[28:29]
	v_subrev_u32_e32 v31, 32, v219
	v_cmp_lt_i32_e32 vcc, -1, v31
	v_mov_b32_e32 v19, 0
	v_mov_b32_e32 v18, 0
	s_and_saveexec_b64 s[28:29], vcc
	v_cmp_gt_u32_e32 vcc, s76, v31
	s_nop 1
	v_cndmask_b32_e64 v18, 0, 1, vcc
	v_cmp_gt_u32_e32 vcc, s80, v31
	s_and_b64 s[64:65], s[8:9], vcc
	v_cndmask_b32_e64 v31, 0, 1, s[64:65]
	v_cmp_eq_u32_e32 vcc, 0, v20
	s_nop 1
	v_addc_co_u32_e32 v18, vcc, v31, v18, vcc
	s_or_b64 exec, exec, s[28:29]
	v_subrev_u32_e32 v20, 32, v221
	v_cmp_lt_i32_e32 vcc, -1, v20
	s_and_saveexec_b64 s[28:29], vcc
	v_cmp_gt_u32_e32 vcc, s76, v20
	s_nop 1
	v_cndmask_b32_e64 v19, 0, 1, vcc
	v_cmp_gt_u32_e32 vcc, s80, v20
	s_and_b64 s[64:65], s[10:11], vcc
	v_cndmask_b32_e64 v20, 0, 1, s[64:65]
	v_cmp_eq_u32_e32 vcc, 0, v21
	s_nop 1
	v_addc_co_u32_e32 v19, vcc, v20, v19, vcc
	s_or_b64 exec, exec, s[28:29]
	v_subrev_u32_e32 v31, 32, v223
	v_cmp_lt_i32_e32 vcc, -1, v31
	v_mov_b32_e32 v21, 0
	v_mov_b32_e32 v20, 0
	s_and_saveexec_b64 s[28:29], vcc
	v_cmp_gt_u32_e32 vcc, s76, v31
	s_nop 1
	v_cndmask_b32_e64 v20, 0, 1, vcc
	v_cmp_gt_u32_e32 vcc, s80, v31
	s_and_b64 s[64:65], s[4:5], vcc
	v_cndmask_b32_e64 v31, 0, 1, s[64:65]
	v_cmp_eq_u32_e32 vcc, 0, v22
	s_nop 1
	v_addc_co_u32_e32 v20, vcc, v31, v20, vcc
	s_or_b64 exec, exec, s[28:29]
	v_subrev_u32_e32 v22, 32, v224
	v_cmp_lt_i32_e32 vcc, -1, v22
	s_and_saveexec_b64 s[28:29], vcc
	v_cmp_gt_u32_e32 vcc, s76, v22
	s_nop 1
	v_cndmask_b32_e64 v21, 0, 1, vcc
	v_cmp_gt_u32_e32 vcc, s80, v22
	s_and_b64 s[64:65], s[6:7], vcc
	v_cndmask_b32_e64 v22, 0, 1, s[64:65]
	v_cmp_eq_u32_e32 vcc, 0, v23
	s_nop 1
	v_addc_co_u32_e32 v21, vcc, v22, v21, vcc
	s_or_b64 exec, exec, s[28:29]
	v_subrev_u32_e32 v31, 32, v225
	v_cmp_lt_i32_e32 vcc, -1, v31
; DI int crow(int i, int h) { return (i & 3) + 8 * (i >> 2) + 4 * h; }
; template <int DV, bool MULT>
; DI void attn_pass(const bf16_t* __restrict__ Kg, const bf16_t* __restrict__ VTg, const bf16x8 (&qf)[4], const int q0, f32x16 (&O)[DV / 32], float& m_run, float& l_run, char* lds, const int gw) {
;     ...
;             } else {
; #pragma unroll
;                 for (int k2 = 0; k2 < 2; ++k2)
; #pragma unroll
;                     for (int i = 0; i < 16; ++i) {
;                         const int key = kb + 32 * k2 + crow(i, hh); const int dl = qpos - key;
;                         float sv;
;                         if (MULT) {
;                             const int c = (dl >= 0) ? ((dl <= 128 ? 1 : 0) + (((dl & 3) == 0 && dl <= 512) ? 1 : 0) + (((dl & 15) == 0) ? 1 : 0)) : 0;
;                             const float adj = (c == 3) ? 1.5849625007211562f : ((c == 2) ? 1.0f : 0.0f);
;                             sv = (c > 0) ? st[k2][i] + adj : -1e30f;
;                         } else {
;                             sv = (dl >= 0) ? st[k2][i] : -1e30f;
;                         }
;                         st[k2][i] = sv; mx = fmaxf(mx, sv);
;                     }
	v_mov_b32_e32 v23, 0
	v_mov_b32_e32 v22, 0
	s_and_saveexec_b64 s[28:29], vcc
	v_cmp_gt_u32_e32 vcc, s76, v31
	s_nop 1
	v_cndmask_b32_e64 v22, 0, 1, vcc
	v_cmp_gt_u32_e32 vcc, s80, v31
	s_and_b64 s[64:65], s[8:9], vcc
	v_cndmask_b32_e64 v31, 0, 1, s[64:65]
	v_cmp_eq_u32_e32 vcc, 0, v24
	s_nop 1
	v_addc_co_u32_e32 v22, vcc, v31, v22, vcc
	s_or_b64 exec, exec, s[28:29]
	v_subrev_u32_e32 v24, 32, v226
	v_cmp_lt_i32_e32 vcc, -1, v24
	s_and_saveexec_b64 s[28:29], vcc
	v_cmp_gt_u32_e32 vcc, s76, v24
	s_nop 1
	v_cndmask_b32_e64 v23, 0, 1, vcc
	v_cmp_gt_u32_e32 vcc, s80, v24
	s_and_b64 s[64:65], s[10:11], vcc
	v_cndmask_b32_e64 v24, 0, 1, s[64:65]
	v_cmp_eq_u32_e32 vcc, 0, v25
	s_nop 1
	v_addc_co_u32_e32 v23, vcc, v24, v23, vcc
	s_or_b64 exec, exec, s[28:29]
	v_subrev_u32_e32 v31, 32, v227
	v_cmp_lt_i32_e32 vcc, -1, v31
	v_mov_b32_e32 v25, 0
	v_mov_b32_e32 v24, 0
	s_and_saveexec_b64 s[28:29], vcc
	v_cmp_gt_u32_e32 vcc, s76, v31
	s_nop 1
	v_cndmask_b32_e64 v24, 0, 1, vcc
	v_cmp_gt_u32_e32 vcc, s80, v31
	s_and_b64 s[64:65], s[4:5], vcc
	v_cndmask_b32_e64 v31, 0, 1, s[64:65]
	v_cmp_eq_u32_e32 vcc, 0, v26
	s_nop 1
	v_addc_co_u32_e32 v24, vcc, v31, v24, vcc
	s_or_b64 exec, exec, s[28:29]
	v_subrev_u32_e32 v26, 32, v228
	v_cmp_lt_i32_e32 vcc, -1, v26
	s_and_saveexec_b64 s[28:29], vcc
	v_cmp_gt_u32_e32 vcc, s76, v26
	s_nop 1
	v_cndmask_b32_e64 v25, 0, 1, vcc
	v_cmp_gt_u32_e32 vcc, s80, v26
	s_and_b64 s[64:65], s[6:7], vcc
	v_cndmask_b32_e64 v26, 0, 1, s[64:65]
	v_cmp_eq_u32_e32 vcc, 0, v27
	s_nop 1
	v_addc_co_u32_e32 v25, vcc, v26, v25, vcc
	s_or_b64 exec, exec, s[28:29]
	v_subrev_u32_e32 v31, 32, v229
	v_cmp_lt_i32_e32 vcc, -1, v31
	v_mov_b32_e32 v27, 0
	v_mov_b32_e32 v26, 0
	s_and_saveexec_b64 s[28:29], vcc
	v_cmp_gt_u32_e32 vcc, s76, v31
	s_nop 1
	v_cndmask_b32_e64 v26, 0, 1, vcc
	v_cmp_gt_u32_e32 vcc, s80, v31
	s_and_b64 s[64:65], s[8:9], vcc
	v_cndmask_b32_e64 v31, 0, 1, s[64:65]
	v_cmp_eq_u32_e32 vcc, 0, v28
	s_nop 1
	v_addc_co_u32_e32 v26, vcc, v31, v26, vcc
	s_or_b64 exec, exec, s[28:29]
	v_subrev_u32_e32 v28, 32, v230
	v_cmp_lt_i32_e32 vcc, -1, v28
	s_and_saveexec_b64 s[28:29], vcc
	v_cmp_gt_u32_e32 vcc, s76, v28
	s_nop 1
	v_cndmask_b32_e64 v27, 0, 1, vcc
	v_cmp_gt_u32_e32 vcc, s80, v28
	s_and_b64 s[64:65], s[10:11], vcc
	v_cndmask_b32_e64 v28, 0, 1, s[64:65]
	v_cmp_eq_u32_e32 vcc, 0, v29
	s_nop 1
	v_addc_co_u32_e32 v27, vcc, v28, v27, vcc
	s_or_b64 exec, exec, s[28:29]
	v_subrev_u32_e32 v31, 32, v231
	v_cmp_lt_i32_e32 vcc, -1, v31
	v_mov_b32_e32 v29, 0
	v_mov_b32_e32 v28, 0
	s_and_saveexec_b64 s[28:29], vcc
	v_cmp_gt_u32_e32 vcc, s76, v31
	s_nop 1
	v_cndmask_b32_e64 v28, 0, 1, vcc
	v_cmp_gt_u32_e32 vcc, s80, v31
	s_and_b64 s[64:65], s[4:5], vcc
	v_cndmask_b32_e64 v31, 0, 1, s[64:65]
	v_cmp_eq_u32_e32 vcc, 0, v30
	s_nop 1
	v_addc_co_u32_e32 v28, vcc, v31, v28, vcc
	s_or_b64 exec, exec, s[28:29]
	v_subrev_u32_e32 v30, 32, v232
	v_cmp_lt_i32_e32 vcc, -1, v30
	s_and_saveexec_b64 s[28:29], vcc
	v_cmp_gt_u32_e32 vcc, s76, v30
	s_nop 1
	v_cndmask_b32_e64 v29, 0, 1, vcc
	v_cmp_gt_u32_e32 vcc, s80, v30
	s_and_b64 s[64:65], s[6:7], vcc
	v_cndmask_b32_e64 v30, 0, 1, s[64:65]
	v_cmp_eq_u32_e32 vcc, 0, v218
	s_nop 1
	v_addc_co_u32_e32 v29, vcc, v30, v29, vcc
	s_or_b64 exec, exec, s[28:29]
	v_subrev_u32_e32 v218, 32, v233
	v_cmp_lt_i32_e32 vcc, -1, v218
	v_mov_b32_e32 v31, 0
	v_mov_b32_e32 v30, 0
	s_and_saveexec_b64 s[28:29], vcc
	v_cmp_gt_u32_e32 vcc, s76, v218
	s_nop 1
	v_cndmask_b32_e64 v30, 0, 1, vcc
	v_cmp_gt_u32_e32 vcc, s80, v218
	s_and_b64 s[64:65], s[8:9], vcc
	v_cndmask_b32_e64 v193, 0, 1, s[64:65]
	v_cmp_eq_u32_e32 vcc, 0, v220
	s_nop 1
	v_addc_co_u32_e32 v30, vcc, v193, v30, vcc
	s_or_b64 exec, exec, s[28:29]
	v_subrev_u32_e32 v218, 32, v234
	v_cmp_lt_i32_e32 vcc, -1, v218
	s_and_saveexec_b64 s[28:29], vcc
	v_cmp_gt_u32_e32 vcc, s76, v218
	s_nop 1
	v_cndmask_b32_e64 v31, 0, 1, vcc
	v_cmp_gt_u32_e32 vcc, s80, v218
	s_and_b64 s[64:65], s[10:11], vcc
	v_cndmask_b32_e64 v193, 0, 1, s[64:65]
	v_cmp_eq_u32_e32 vcc, 0, v222
	s_nop 1
	v_addc_co_u32_e32 v31, vcc, v193, v31, vcc
	s_or_b64 exec, exec, s[28:29]
	v_cmp_eq_u32_e32 vcc, 2, v0
	s_nop 1
	v_cndmask_b32_e64 v193, 0, 1.0, vcc
	v_cmp_ne_u32_e32 vcc, 3, v0
	s_nop 1
	v_cndmask_b32_e32 v193, v202, v193, vcc
	v_add_f32_e32 v82, v82, v193
	v_cmp_ne_u32_e32 vcc, 0, v0
	s_nop 1
	v_cndmask_b32_e32 v0, v201, v82, vcc
	v_cmp_eq_u32_e32 vcc, 2, v1
	s_nop 1
	v_cndmask_b32_e64 v82, 0, 1.0, vcc
	v_cmp_ne_u32_e32 vcc, 3, v1
	s_nop 1
	v_cndmask_b32_e32 v82, v202, v82, vcc
	v_add_f32_e32 v82, v83, v82
	v_cmp_ne_u32_e32 vcc, 0, v1
	s_nop 1
	v_cndmask_b32_e32 v1, v201, v82, vcc
	v_cmp_eq_u32_e32 vcc, 2, v2
	v_max3_f32 v82, v0, s85, v1
	s_nop 0
	v_cndmask_b32_e64 v83, 0, 1.0, vcc
	v_cmp_ne_u32_e32 vcc, 3, v2
	s_nop 1
	v_cndmask_b32_e32 v83, v202, v83, vcc
	v_add_f32_e32 v83, v84, v83
	v_cmp_ne_u32_e32 vcc, 0, v2
	s_nop 1
	v_cndmask_b32_e32 v2, v201, v83, vcc
	v_cmp_eq_u32_e32 vcc, 2, v3
	s_nop 1
	v_cndmask_b32_e64 v83, 0, 1.0, vcc
	v_cmp_ne_u32_e32 vcc, 3, v3
	s_nop 1
	v_cndmask_b32_e32 v83, v202, v83, vcc
	v_add_f32_e32 v83, v85, v83
	v_cmp_ne_u32_e32 vcc, 0, v3
	s_nop 1
	v_cndmask_b32_e32 v3, v201, v83, vcc
	v_cmp_eq_u32_e32 vcc, 2, v4
	v_max3_f32 v82, v82, v2, v3
	s_nop 0
	v_cndmask_b32_e64 v83, 0, 1.0, vcc
	v_cmp_ne_u32_e32 vcc, 3, v4
	s_nop 1
	v_cndmask_b32_e32 v83, v202, v83, vcc
	v_add_f32_e32 v83, v86, v83
	v_cmp_ne_u32_e32 vcc, 0, v4
	s_nop 1
	v_cndmask_b32_e32 v4, v201, v83, vcc
	v_cmp_eq_u32_e32 vcc, 2, v5
	s_nop 1
	v_cndmask_b32_e64 v83, 0, 1.0, vcc
	v_cmp_ne_u32_e32 vcc, 3, v5
	s_nop 1
	v_cndmask_b32_e32 v83, v202, v83, vcc
	v_add_f32_e32 v83, v87, v83
	v_cmp_ne_u32_e32 vcc, 0, v5
	s_nop 1
; DI int crow(int i, int h) { return (i & 3) + 8 * (i >> 2) + 4 * h; }
; template <int DV, bool MULT>
; DI void attn_pass(const bf16_t* __restrict__ Kg, const bf16_t* __restrict__ VTg, const bf16x8 (&qf)[4], const int q0, f32x16 (&O)[DV / 32], float& m_run, float& l_run, char* lds, const int gw) {
;     ...
; #pragma unroll
;                 for (int k2 = 0; k2 < 2; ++k2)
; #pragma unroll
;                     for (int i = 0; i < 16; ++i) {
;                         const int key = kb + 32 * k2 + crow(i, hh); const int dl = qpos - key;
;                         float sv;
;                         if (MULT) {
;                             const int c = (dl >= 0) ? ((dl <= 128 ? 1 : 0) + (((dl & 3) == 0 && dl <= 512) ? 1 : 0) + (((dl & 15) == 0) ? 1 : 0)) : 0;
;                             const float adj = (c == 3) ? 1.5849625007211562f : ((c == 2) ? 1.0f : 0.0f);
;                             sv = (c > 0) ? st[k2][i] + adj : -1e30f;
;                         } else {
;                             sv = (dl >= 0) ? st[k2][i] : -1e30f;
;                         }
;                         st[k2][i] = sv; mx = fmaxf(mx, sv);
;                     }
	v_cndmask_b32_e32 v5, v201, v83, vcc
	v_cmp_eq_u32_e32 vcc, 2, v6
	v_max3_f32 v82, v82, v4, v5
	s_nop 0
	v_cndmask_b32_e64 v83, 0, 1.0, vcc
	v_cmp_ne_u32_e32 vcc, 3, v6
	s_nop 1
	v_cndmask_b32_e32 v83, v202, v83, vcc
	v_add_f32_e32 v83, v88, v83
	v_cmp_ne_u32_e32 vcc, 0, v6
	s_nop 1
	v_cndmask_b32_e32 v6, v201, v83, vcc
	v_cmp_eq_u32_e32 vcc, 2, v7
	s_nop 1
	v_cndmask_b32_e64 v83, 0, 1.0, vcc
	v_cmp_ne_u32_e32 vcc, 3, v7
	s_nop 1
	v_cndmask_b32_e32 v83, v202, v83, vcc
	v_add_f32_e32 v83, v89, v83
	v_cmp_ne_u32_e32 vcc, 0, v7
	s_nop 1
	v_cndmask_b32_e32 v7, v201, v83, vcc
	v_cmp_eq_u32_e32 vcc, 2, v8
	v_max3_f32 v82, v82, v6, v7
	s_nop 0
	v_cndmask_b32_e64 v83, 0, 1.0, vcc
	v_cmp_ne_u32_e32 vcc, 3, v8
	s_nop 1
	v_cndmask_b32_e32 v83, v202, v83, vcc
	v_add_f32_e32 v83, v90, v83
	v_cmp_ne_u32_e32 vcc, 0, v8
	s_nop 1
	v_cndmask_b32_e32 v8, v201, v83, vcc
	v_cmp_eq_u32_e32 vcc, 2, v9
	s_nop 1
	v_cndmask_b32_e64 v83, 0, 1.0, vcc
	v_cmp_ne_u32_e32 vcc, 3, v9
	s_nop 1
	v_cndmask_b32_e32 v83, v202, v83, vcc
	v_add_f32_e32 v83, v91, v83
	v_cmp_ne_u32_e32 vcc, 0, v9
	s_nop 1
	v_cndmask_b32_e32 v9, v201, v83, vcc
	v_cmp_eq_u32_e32 vcc, 2, v10
	v_max3_f32 v82, v82, v8, v9
	s_nop 0
	v_cndmask_b32_e64 v83, 0, 1.0, vcc
	v_cmp_ne_u32_e32 vcc, 3, v10
	s_nop 1
	v_cndmask_b32_e32 v83, v202, v83, vcc
	v_add_f32_e32 v83, v92, v83
	v_cmp_ne_u32_e32 vcc, 0, v10
	s_nop 1
	v_cndmask_b32_e32 v10, v201, v83, vcc
	v_cmp_eq_u32_e32 vcc, 2, v11
	s_nop 1
	v_cndmask_b32_e64 v83, 0, 1.0, vcc
	v_cmp_ne_u32_e32 vcc, 3, v11
	s_nop 1
	v_cndmask_b32_e32 v83, v202, v83, vcc
	v_add_f32_e32 v83, v93, v83
	v_cmp_ne_u32_e32 vcc, 0, v11
	s_nop 1
	v_cndmask_b32_e32 v11, v201, v83, vcc
	v_cmp_eq_u32_e32 vcc, 2, v12
	v_max3_f32 v82, v82, v10, v11
	s_nop 0
	v_cndmask_b32_e64 v83, 0, 1.0, vcc
	v_cmp_ne_u32_e32 vcc, 3, v12
	s_nop 1
	v_cndmask_b32_e32 v83, v202, v83, vcc
	v_add_f32_e32 v83, v94, v83
	v_cmp_ne_u32_e32 vcc, 0, v12
	s_nop 1
	v_cndmask_b32_e32 v12, v201, v83, vcc
	v_cmp_eq_u32_e32 vcc, 2, v13
	s_nop 1
	v_cndmask_b32_e64 v83, 0, 1.0, vcc
	v_cmp_ne_u32_e32 vcc, 3, v13
	s_nop 1
	v_cndmask_b32_e32 v83, v202, v83, vcc
	v_add_f32_e32 v83, v95, v83
	v_cmp_ne_u32_e32 vcc, 0, v13
	s_nop 1
	v_cndmask_b32_e32 v13, v201, v83, vcc
	v_cmp_eq_u32_e32 vcc, 2, v14
	v_max3_f32 v82, v82, v12, v13
	s_nop 0
	v_cndmask_b32_e64 v83, 0, 1.0, vcc
	v_cmp_ne_u32_e32 vcc, 3, v14
	s_nop 1
	v_cndmask_b32_e32 v83, v202, v83, vcc
	v_add_f32_e32 v83, v96, v83
	v_cmp_ne_u32_e32 vcc, 0, v14
	s_nop 1
	v_cndmask_b32_e32 v14, v201, v83, vcc
	v_cmp_eq_u32_e32 vcc, 2, v15
	s_nop 1
	v_cndmask_b32_e64 v83, 0, 1.0, vcc
	v_cmp_ne_u32_e32 vcc, 3, v15
	s_nop 1
	v_cndmask_b32_e32 v83, v202, v83, vcc
	v_add_f32_e32 v83, v97, v83
	v_cmp_ne_u32_e32 vcc, 0, v15
	s_nop 1
	v_cndmask_b32_e32 v15, v201, v83, vcc
	v_cmp_eq_u32_e32 vcc, 2, v16
	v_max3_f32 v82, v82, v14, v15
	s_nop 0
	v_cndmask_b32_e64 v83, 0, 1.0, vcc
	v_cmp_ne_u32_e32 vcc, 3, v16
	s_nop 1
	v_cndmask_b32_e32 v83, v202, v83, vcc
	v_add_f32_e32 v66, v66, v83
	v_cmp_ne_u32_e32 vcc, 0, v16
	s_nop 1
	v_cndmask_b32_e32 v16, v201, v66, vcc
	v_cmp_eq_u32_e32 vcc, 2, v17
	s_nop 1
	v_cndmask_b32_e64 v66, 0, 1.0, vcc
	v_cmp_ne_u32_e32 vcc, 3, v17
	s_nop 1
	v_cndmask_b32_e32 v66, v202, v66, vcc
	v_add_f32_e32 v66, v67, v66
	v_cmp_ne_u32_e32 vcc, 0, v17
	s_nop 1
	v_cndmask_b32_e32 v17, v201, v66, vcc
	v_cmp_eq_u32_e32 vcc, 2, v18
	v_max3_f32 v66, v82, v16, v17
	s_nop 0
	v_cndmask_b32_e64 v67, 0, 1.0, vcc
	v_cmp_ne_u32_e32 vcc, 3, v18
	s_nop 1
	v_cndmask_b32_e32 v67, v202, v67, vcc
	v_add_f32_e32 v67, v68, v67
	v_cmp_ne_u32_e32 vcc, 0, v18
	s_nop 1
	v_cndmask_b32_e32 v18, v201, v67, vcc
; DI int crow(int i, int h) { return (i & 3) + 8 * (i >> 2) + 4 * h; }
; template <int DV, bool MULT>
; DI void attn_pass(const bf16_t* __restrict__ Kg, const bf16_t* __restrict__ VTg, const bf16x8 (&qf)[4], const int q0, f32x16 (&O)[DV / 32], float& m_run, float& l_run, char* lds, const int gw) {
;     ...
; #pragma unroll
;                 for (int k2 = 0; k2 < 2; ++k2)
; #pragma unroll
;                     for (int i = 0; i < 16; ++i) {
;                         const int key = kb + 32 * k2 + crow(i, hh); const int dl = qpos - key;
;                         float sv;
;                         if (MULT) {
;                             const int c = (dl >= 0) ? ((dl <= 128 ? 1 : 0) + (((dl & 3) == 0 && dl <= 512) ? 1 : 0) + (((dl & 15) == 0) ? 1 : 0)) : 0;
;                             const float adj = (c == 3) ? 1.5849625007211562f : ((c == 2) ? 1.0f : 0.0f);
;                             sv = (c > 0) ? st[k2][i] + adj : -1e30f;
;                         } else {
;                             sv = (dl >= 0) ? st[k2][i] : -1e30f;
;                         }
;                         st[k2][i] = sv; mx = fmaxf(mx, sv);
;                     }
	v_cmp_eq_u32_e32 vcc, 2, v19
	s_nop 1
	v_cndmask_b32_e64 v67, 0, 1.0, vcc
	v_cmp_ne_u32_e32 vcc, 3, v19
	s_nop 1
	v_cndmask_b32_e32 v67, v202, v67, vcc
	v_add_f32_e32 v67, v69, v67
	v_cmp_ne_u32_e32 vcc, 0, v19
	s_nop 1
	v_cndmask_b32_e32 v19, v201, v67, vcc
	v_cmp_eq_u32_e32 vcc, 2, v20
	v_max3_f32 v66, v66, v18, v19
	s_nop 0
	v_cndmask_b32_e64 v67, 0, 1.0, vcc
	v_cmp_ne_u32_e32 vcc, 3, v20
	s_nop 1
	v_cndmask_b32_e32 v67, v202, v67, vcc
	v_add_f32_e32 v67, v70, v67
	v_cmp_ne_u32_e32 vcc, 0, v20
	s_nop 1
	v_cndmask_b32_e32 v20, v201, v67, vcc
	v_cmp_eq_u32_e32 vcc, 2, v21
	s_nop 1
	v_cndmask_b32_e64 v67, 0, 1.0, vcc
	v_cmp_ne_u32_e32 vcc, 3, v21
	s_nop 1
	v_cndmask_b32_e32 v67, v202, v67, vcc
	v_add_f32_e32 v67, v71, v67
	v_cmp_ne_u32_e32 vcc, 0, v21
	s_nop 1
	v_cndmask_b32_e32 v21, v201, v67, vcc
	v_cmp_eq_u32_e32 vcc, 2, v22
	v_max3_f32 v66, v66, v20, v21
	s_nop 0
	v_cndmask_b32_e64 v67, 0, 1.0, vcc
	v_cmp_ne_u32_e32 vcc, 3, v22
	s_nop 1
	v_cndmask_b32_e32 v67, v202, v67, vcc
	v_add_f32_e32 v67, v72, v67
	v_cmp_ne_u32_e32 vcc, 0, v22
	s_nop 1
	v_cndmask_b32_e32 v22, v201, v67, vcc
	v_cmp_eq_u32_e32 vcc, 2, v23
	s_nop 1
	v_cndmask_b32_e64 v67, 0, 1.0, vcc
	v_cmp_ne_u32_e32 vcc, 3, v23
	s_nop 1
	v_cndmask_b32_e32 v67, v202, v67, vcc
	v_add_f32_e32 v67, v73, v67
	v_cmp_ne_u32_e32 vcc, 0, v23
	s_nop 1
	v_cndmask_b32_e32 v23, v201, v67, vcc
	v_cmp_eq_u32_e32 vcc, 2, v24
	v_max3_f32 v66, v66, v22, v23
	s_nop 0
	v_cndmask_b32_e64 v67, 0, 1.0, vcc
	v_cmp_ne_u32_e32 vcc, 3, v24
	s_nop 1
	v_cndmask_b32_e32 v67, v202, v67, vcc
	v_add_f32_e32 v67, v74, v67
	v_cmp_ne_u32_e32 vcc, 0, v24
	s_nop 1
	v_cndmask_b32_e32 v24, v201, v67, vcc
	v_cmp_eq_u32_e32 vcc, 2, v25
	s_nop 1
	v_cndmask_b32_e64 v67, 0, 1.0, vcc
	v_cmp_ne_u32_e32 vcc, 3, v25
	s_nop 1
	v_cndmask_b32_e32 v67, v202, v67, vcc
	v_add_f32_e32 v67, v75, v67
	v_cmp_ne_u32_e32 vcc, 0, v25
	s_nop 1
	v_cndmask_b32_e32 v25, v201, v67, vcc
	v_cmp_eq_u32_e32 vcc, 2, v26
	v_max3_f32 v66, v66, v24, v25
	s_nop 0
	v_cndmask_b32_e64 v67, 0, 1.0, vcc
	v_cmp_ne_u32_e32 vcc, 3, v26
	s_nop 1
	v_cndmask_b32_e32 v67, v202, v67, vcc
	v_add_f32_e32 v67, v76, v67
	v_cmp_ne_u32_e32 vcc, 0, v26
	s_nop 1
	v_cndmask_b32_e32 v26, v201, v67, vcc
	v_cmp_eq_u32_e32 vcc, 2, v27
	s_nop 1
	v_cndmask_b32_e64 v67, 0, 1.0, vcc
	v_cmp_ne_u32_e32 vcc, 3, v27
	s_nop 1
	v_cndmask_b32_e32 v67, v202, v67, vcc
	v_add_f32_e32 v67, v77, v67
	v_cmp_ne_u32_e32 vcc, 0, v27
	s_nop 1
	v_cndmask_b32_e32 v27, v201, v67, vcc
	v_cmp_eq_u32_e32 vcc, 2, v28
	v_max3_f32 v66, v66, v26, v27
	s_nop 0
	v_cndmask_b32_e64 v67, 0, 1.0, vcc
	v_cmp_ne_u32_e32 vcc, 3, v28
	s_nop 1
	v_cndmask_b32_e32 v67, v202, v67, vcc
	v_add_f32_e32 v67, v78, v67
	v_cmp_ne_u32_e32 vcc, 0, v28
	s_nop 1
	v_cndmask_b32_e32 v28, v201, v67, vcc
	v_cmp_eq_u32_e32 vcc, 2, v29
	s_nop 1
	v_cndmask_b32_e64 v67, 0, 1.0, vcc
	v_cmp_ne_u32_e32 vcc, 3, v29
	s_nop 1
	v_cndmask_b32_e32 v67, v202, v67, vcc
	v_add_f32_e32 v67, v79, v67
	v_cmp_ne_u32_e32 vcc, 0, v29
	s_nop 1
	v_cndmask_b32_e32 v29, v201, v67, vcc
	v_cmp_eq_u32_e32 vcc, 2, v30
	v_max3_f32 v66, v66, v28, v29
	s_nop 0
	v_cndmask_b32_e64 v67, 0, 1.0, vcc
	v_cmp_ne_u32_e32 vcc, 3, v30
	s_nop 1
	v_cndmask_b32_e32 v67, v202, v67, vcc
	v_add_f32_e32 v67, v80, v67
	v_cmp_ne_u32_e32 vcc, 0, v30
	s_nop 1
	v_cndmask_b32_e32 v30, v201, v67, vcc
	v_cmp_eq_u32_e32 vcc, 2, v31
	s_nop 1
	v_cndmask_b32_e64 v67, 0, 1.0, vcc
	v_cmp_ne_u32_e32 vcc, 3, v31
	s_nop 1
	v_cndmask_b32_e32 v67, v202, v67, vcc
	v_add_f32_e32 v67, v81, v67
	v_cmp_ne_u32_e32 vcc, 0, v31
	s_nop 1
	v_cndmask_b32_e32 v31, v201, v67, vcc
	v_max3_f32 v218, v66, v30, v31

; #define STAGE(bufoff, GB) do { const char* g_ = (GB); \
;         _Pragma("unroll") for (int i_ = 0; i_ < 2; ++i_) __builtin_amdgcn_global_load_lds((const unsigned*)(g_ + voff[i_]), (LAS3 unsigned*)(L + (bufoff) + stoff + i_ * 8192), 16, 0, 0); } while (0)
; #define LDA(dst, b, h) do { _Pragma("unroll") for (int m = 0; m < 4; ++m) _Pragma("unroll") for (int k = 0; k < 2; ++k) dst[m][k] = *(const LAS3 bf16x8*)(L + SA(b, h) + aoff + m * 2048 + k * 1024); } while (0)
; #define LDB(dst, b, h) do { _Pragma("unroll") for (int n = 0; n < 2; ++n) _Pragma("unroll") for (int k = 0; k < 2; ++k) dst[n][k] = *(const LAS3 bf16x8*)(L + SB(b, h) + boff + n * 2048 + k * 1024); } while (0)
; #define WAIT_V(n) asm volatile("s_waitcnt vmcnt(" #n ")" ::: "memory")
; #define WAIT_L(n) asm volatile("s_waitcnt lgkmcnt(" #n ")" ::: "memory")
; #define BAR __builtin_amdgcn_s_barrier()
; #define SCHED __builtin_amdgcn_sched_barrier(0)
; template <int EPI>
; DI void gemm_phase(const bf16_t* __restrict__ A, const bf16_t* __restrict__ Bt, const int K, const int N, const Params& p, const int layer_j, char* lds) {
;     ...
;         for (int t = 0; t < nt; t += 2) {
;             const bool last = (t == nt - 2);
;             const char* a1 = cA + (size_t)(t + 1) * kstep;
;             const char* a2 = last ? nA : cA + (size_t)(t + 2) * kstep; const char* b2 = last ? nB : cB + (size_t)(t + 2) * kstep;
;             const char* a3 = a2 + kstep; const char* b3 = b2 + kstep;
;             LDB(B0, 0, 0); LDB(B1, 0, 1); SCHED; LDA(At, 0, 0); STAGE(SA(1, 1), a1 + hstep);
;             WAIT_V(8); WAIT_L(0); BAR; MMA(0, 0, At, B0); MMA(0, 1, At, B1); BAR; SCHED;
;             LDA(At, 0, 1); STAGE(SB(0, 0), b2); STAGE(SB(0, 1), b2 + hstep); STAGE(SA(0, 0), a2);
;             WAIT_V(8); WAIT_L(0); BAR; MMA(1, 0, At, B0); MMA(1, 1, At, B1); BAR; SCHED;
.LBB0_338:
	s_cmp_eq_u32 s66, 1
	s_cselect_b32 s100, 1, s28
	v_add_u32_e32 v148, 0x10000, v186
	v_add_u32_e32 v164, 0x14000, v186
	s_add_u32 s16, s87, s28
	ds_read_b128 v[136:139], v148
	ds_read_b128 v[140:143], v148 offset:1024
	ds_read_b128 v[144:147], v148 offset:2048
	ds_read_b128 v[148:151], v148 offset:3072
	ds_read_b128 v[152:155], v164
	ds_read_b128 v[156:159], v164 offset:1024
	ds_read_b128 v[160:163], v164 offset:2048
	ds_read_b128 v[164:167], v164 offset:3072
	s_addc_u32 s17, s88, s29
	s_add_u32 s16, s16, 0x6681100
	s_addc_u32 s17, s17, 0
	s_add_u32 s30, s67, s28
	s_addc_u32 s31, s86, s29
	s_cmpk_eq_i32 s28, 0x700
	s_cselect_b32 s35, s9, s17
	s_cselect_b32 s34, s5, s16
	s_cselect_b32 s31, s23, s31
	s_cselect_b32 s30, s21, s30
	v_add_u32_e32 v192, 0xc000, v184
	v_lshl_add_u64 v[194:195], v[134:135], 0, s[28:29]
	v_readfirstlane_b32 s16, v192
	v_add_u32_e32 v192, 0xe000, v184
	s_mov_b32 m0, s16
	v_readfirstlane_b32 s16, v192
	ds_read_b128 v[168:171], v185
	ds_read_b128 v[172:175], v185 offset:1024
	ds_read_b128 v[176:179], v185 offset:2048
	ds_read_b128 v[180:183], v185 offset:3072
	ds_read_b128 v[212:215], v185 offset:4096
	ds_read_b128 v[216:219], v185 offset:5120
	ds_read_b128 v[220:223], v185 offset:6144
	ds_read_b128 v[224:227], v185 offset:7168
	global_load_lds_dwordx4 v[194:195], off
	v_lshl_add_u64 v[194:195], v[132:133], 0, s[28:29]
	s_mov_b32 m0, s16
	s_nop 0
	global_load_lds_dwordx4 v[194:195], off
	s_cmp_eq_u32 s100, 0
	s_cbranch_scc1 .Lskipw_rec_0
	s_waitcnt vmcnt(8)
.Lskipw_rec_0:
	s_waitcnt lgkmcnt(0)
	s_barrier
	s_setprio 1
	s_waitcnt lgkmcnt(0)
	v_mfma_f32_16x16x32_bf16 v[126:129], v[136:139], v[168:171], v[126:129]
	v_mfma_f32_16x16x32_bf16 v[122:125], v[144:147], v[168:171], v[122:125]
	v_mfma_f32_16x16x32_bf16 v[110:113], v[136:139], v[176:179], v[110:113]
	v_mfma_f32_16x16x32_bf16 v[106:109], v[144:147], v[176:179], v[106:109]
	v_mfma_f32_16x16x32_bf16 v[94:97], v[136:139], v[212:215], v[94:97]
	v_mfma_f32_16x16x32_bf16 v[90:93], v[144:147], v[212:215], v[90:93]
	v_mfma_f32_16x16x32_bf16 v[78:81], v[136:139], v[220:223], v[78:81]
	v_mfma_f32_16x16x32_bf16 v[74:77], v[144:147], v[220:223], v[74:77]
	v_mfma_f32_16x16x32_bf16 v[126:129], v[140:143], v[172:175], v[126:129]
	v_mfma_f32_16x16x32_bf16 v[122:125], v[148:151], v[172:175], v[122:125]
	v_mfma_f32_16x16x32_bf16 v[110:113], v[140:143], v[180:183], v[110:113]
	v_mfma_f32_16x16x32_bf16 v[106:109], v[148:151], v[180:183], v[106:109]
	v_mfma_f32_16x16x32_bf16 v[94:97], v[140:143], v[216:219], v[94:97]
	v_mfma_f32_16x16x32_bf16 v[90:93], v[148:151], v[216:219], v[90:93]
	v_mfma_f32_16x16x32_bf16 v[78:81], v[140:143], v[224:227], v[78:81]
	v_mfma_f32_16x16x32_bf16 v[74:77], v[148:151], v[224:227], v[74:77]
	s_setprio 0
	s_setprio 1
	v_mfma_f32_16x16x32_bf16 v[118:121], v[152:155], v[168:171], v[118:121]
	v_mfma_f32_16x16x32_bf16 v[114:117], v[160:163], v[168:171], v[114:117]
	v_mfma_f32_16x16x32_bf16 v[102:105], v[152:155], v[176:179], v[102:105]
	v_mfma_f32_16x16x32_bf16 v[98:101], v[160:163], v[176:179], v[98:101]
	v_mfma_f32_16x16x32_bf16 v[86:89], v[152:155], v[212:215], v[86:89]
	v_mfma_f32_16x16x32_bf16 v[82:85], v[160:163], v[212:215], v[82:85]
	v_mfma_f32_16x16x32_bf16 v[38:41], v[152:155], v[220:223], v[38:41]
	v_mfma_f32_16x16x32_bf16 v[16:19], v[160:163], v[220:223], v[16:19]
	v_mfma_f32_16x16x32_bf16 v[118:121], v[156:159], v[172:175], v[118:121]
	v_mfma_f32_16x16x32_bf16 v[114:117], v[164:167], v[172:175], v[114:117]
	v_mfma_f32_16x16x32_bf16 v[102:105], v[156:159], v[180:183], v[102:105]
	v_mfma_f32_16x16x32_bf16 v[98:101], v[164:167], v[180:183], v[98:101]
	v_mfma_f32_16x16x32_bf16 v[86:89], v[156:159], v[216:219], v[86:89]
	v_mfma_f32_16x16x32_bf16 v[82:85], v[164:167], v[216:219], v[82:85]
	v_mfma_f32_16x16x32_bf16 v[38:41], v[156:159], v[224:227], v[38:41]
	v_mfma_f32_16x16x32_bf16 v[16:19], v[164:167], v[224:227], v[16:19]
	s_setprio 0
	s_barrier
	v_readfirstlane_b32 s16, v187
	v_lshl_add_u64 v[194:195], s[30:31], 0, v[32:33]
	s_mov_b32 m0, s16
	v_readfirstlane_b32 s16, v188
	ds_read_b128 v[168:171], v185 offset:16384
	ds_read_b128 v[172:175], v185 offset:17408
	ds_read_b128 v[176:179], v185 offset:18432
	ds_read_b128 v[180:183], v185 offset:19456
	ds_read_b128 v[212:215], v185 offset:20480
	ds_read_b128 v[216:219], v185 offset:21504
	ds_read_b128 v[220:223], v185 offset:22528
	ds_read_b128 v[224:227], v185 offset:23552
	global_load_lds_dwordx4 v[194:195], off
	s_mov_b32 m0, s16
	s_add_u32 s16, s30, 0x40000
	v_lshl_add_u64 v[228:229], s[30:31], 0, v[130:131]
	s_addc_u32 s17, s31, 0
	v_readfirstlane_b32 s6, v189
	global_load_lds_dwordx4 v[228:229], off
	v_lshl_add_u64 v[230:231], s[16:17], 0, v[32:33]
	s_mov_b32 m0, s6
	v_readfirstlane_b32 s6, v190
	global_load_lds_dwordx4 v[230:231], off
	v_lshl_add_u64 v[230:231], s[16:17], 0, v[130:131]
	s_mov_b32 m0, s6
	v_readfirstlane_b32 s6, v184
	global_load_lds_dwordx4 v[230:231], off
	v_lshl_add_u64 v[230:231], s[34:35], 0, v[32:33]
	s_mov_b32 m0, s6
	v_readfirstlane_b32 s6, v191
	global_load_lds_dwordx4 v[230:231], off
	v_lshl_add_u64 v[232:233], s[34:35], 0, v[130:131]
	s_mov_b32 m0, s6
	s_nop 0
	global_load_lds_dwordx4 v[232:233], off
	s_cmp_eq_u32 s100, 0
	s_cbranch_scc1 .Lskipw_rec_1
	s_waitcnt vmcnt(8)
; #define STAGE(bufoff, GB) do { const char* g_ = (GB); \
;         _Pragma("unroll") for (int i_ = 0; i_ < 2; ++i_) __builtin_amdgcn_global_load_lds((const unsigned*)(g_ + voff[i_]), (LAS3 unsigned*)(L + (bufoff) + stoff + i_ * 8192), 16, 0, 0); } while (0)
; #define LDA(dst, b, h) do { _Pragma("unroll") for (int m = 0; m < 4; ++m) _Pragma("unroll") for (int k = 0; k < 2; ++k) dst[m][k] = *(const LAS3 bf16x8*)(L + SA(b, h) + aoff + m * 2048 + k * 1024); } while (0)
; #define LDB(dst, b, h) do { _Pragma("unroll") for (int n = 0; n < 2; ++n) _Pragma("unroll") for (int k = 0; k < 2; ++k) dst[n][k] = *(const LAS3 bf16x8*)(L + SB(b, h) + boff + n * 2048 + k * 1024); } while (0)
; #define WAIT_V(n) asm volatile("s_waitcnt vmcnt(" #n ")" ::: "memory")
; #define WAIT_L(n) asm volatile("s_waitcnt lgkmcnt(" #n ")" ::: "memory")
; #define BAR __builtin_amdgcn_s_barrier()
; #define SCHED __builtin_amdgcn_sched_barrier(0)
; template <int EPI>
; DI void gemm_phase(const bf16_t* __restrict__ A, const bf16_t* __restrict__ Bt, const int K, const int N, const Params& p, const int layer_j, char* lds) {
;     ...
;             WAIT_V(8); WAIT_L(0); BAR; MMA(1, 0, At, B0); MMA(1, 1, At, B1); BAR; SCHED;
;             LDB(B0, 1, 0); LDB(B1, 1, 1); SCHED; LDA(At, 1, 0); STAGE(SA(0, 1), a2 + hstep);
;             WAIT_V(8); WAIT_L(0); BAR; MMA(0, 0, At, B0); MMA(0, 1, At, B1); BAR; SCHED;
;             LDA(At, 1, 1); STAGE(SB(1, 0), b3); STAGE(SB(1, 1), b3 + hstep); STAGE(SA(1, 0), a3);
;             WAIT_V(8); WAIT_L(0); BAR; MMA(1, 0, At, B0); MMA(1, 1, At, B1); BAR; SCHED;
.Lskipw_rec_1:
	s_waitcnt lgkmcnt(0)
	s_barrier
	s_setprio 1
	s_waitcnt lgkmcnt(0)
	v_mfma_f32_16x16x32_bf16 v[70:73], v[136:139], v[168:171], v[70:73]
	v_mfma_f32_16x16x32_bf16 v[54:57], v[144:147], v[168:171], v[54:57]
	v_mfma_f32_16x16x32_bf16 v[66:69], v[136:139], v[176:179], v[66:69]
	v_mfma_f32_16x16x32_bf16 v[50:53], v[144:147], v[176:179], v[50:53]
	v_mfma_f32_16x16x32_bf16 v[62:65], v[136:139], v[212:215], v[62:65]
	v_mfma_f32_16x16x32_bf16 v[46:49], v[144:147], v[212:215], v[46:49]
	v_mfma_f32_16x16x32_bf16 v[58:61], v[136:139], v[220:223], v[58:61]
	v_mfma_f32_16x16x32_bf16 v[42:45], v[144:147], v[220:223], v[42:45]
	v_mfma_f32_16x16x32_bf16 v[70:73], v[140:143], v[172:175], v[70:73]
	v_mfma_f32_16x16x32_bf16 v[54:57], v[148:151], v[172:175], v[54:57]
	v_mfma_f32_16x16x32_bf16 v[66:69], v[140:143], v[180:183], v[66:69]
	v_mfma_f32_16x16x32_bf16 v[50:53], v[148:151], v[180:183], v[50:53]
	v_mfma_f32_16x16x32_bf16 v[62:65], v[140:143], v[216:219], v[62:65]
	v_mfma_f32_16x16x32_bf16 v[46:49], v[148:151], v[216:219], v[46:49]
	v_mfma_f32_16x16x32_bf16 v[58:61], v[140:143], v[224:227], v[58:61]
	v_mfma_f32_16x16x32_bf16 v[42:45], v[148:151], v[224:227], v[42:45]
	s_setprio 0
	s_setprio 1
	v_mfma_f32_16x16x32_bf16 v[34:37], v[152:155], v[168:171], v[34:37]
	v_mfma_f32_16x16x32_bf16 v[12:15], v[160:163], v[168:171], v[12:15]
	v_mfma_f32_16x16x32_bf16 v[28:31], v[152:155], v[176:179], v[28:31]
	v_mfma_f32_16x16x32_bf16 v[8:11], v[160:163], v[176:179], v[8:11]
	v_mfma_f32_16x16x32_bf16 v[24:27], v[152:155], v[212:215], v[24:27]
	v_mfma_f32_16x16x32_bf16 v[4:7], v[160:163], v[212:215], v[4:7]
	v_mfma_f32_16x16x32_bf16 v[20:23], v[152:155], v[220:223], v[20:23]
	v_mfma_f32_16x16x32_bf16 v[0:3], v[160:163], v[220:223], v[0:3]
	v_mfma_f32_16x16x32_bf16 v[34:37], v[156:159], v[172:175], v[34:37]
	v_mfma_f32_16x16x32_bf16 v[12:15], v[164:167], v[172:175], v[12:15]
	v_mfma_f32_16x16x32_bf16 v[28:31], v[156:159], v[180:183], v[28:31]
	v_mfma_f32_16x16x32_bf16 v[8:11], v[164:167], v[180:183], v[8:11]
	v_mfma_f32_16x16x32_bf16 v[24:27], v[156:159], v[216:219], v[24:27]
	v_mfma_f32_16x16x32_bf16 v[4:7], v[164:167], v[216:219], v[4:7]
	v_mfma_f32_16x16x32_bf16 v[20:23], v[156:159], v[224:227], v[20:23]
	v_mfma_f32_16x16x32_bf16 v[0:3], v[164:167], v[224:227], v[0:3]
	s_setprio 0
	s_barrier
	v_add_u32_e32 v148, 0x18000, v186
	v_add_u32_e32 v164, 0x1c000, v186
	ds_read_b128 v[136:139], v148
	ds_read_b128 v[140:143], v148 offset:1024
	ds_read_b128 v[144:147], v148 offset:2048
	ds_read_b128 v[148:151], v148 offset:3072
	ds_read_b128 v[152:155], v164
	ds_read_b128 v[156:159], v164 offset:1024
	ds_read_b128 v[160:163], v164 offset:2048
	ds_read_b128 v[164:167], v164 offset:3072
	s_add_u32 s16, s34, 0x40000
	s_addc_u32 s17, s35, 0
	v_readfirstlane_b32 s6, v204
	v_lshl_add_u64 v[234:235], s[16:17], 0, v[32:33]
	s_mov_b32 m0, s6
	v_readfirstlane_b32 s6, v205
	ds_read_b128 v[168:171], v185 offset:32768
	ds_read_b128 v[172:175], v185 offset:33792
	ds_read_b128 v[176:179], v185 offset:34816
	ds_read_b128 v[180:183], v185 offset:35840
	ds_read_b128 v[212:215], v185 offset:36864
	ds_read_b128 v[216:219], v185 offset:37888
	ds_read_b128 v[220:223], v185 offset:38912
	ds_read_b128 v[224:227], v185 offset:39936
	global_load_lds_dwordx4 v[234:235], off
	v_lshl_add_u64 v[234:235], s[16:17], 0, v[130:131]
	s_mov_b32 m0, s6
	s_nop 0
	global_load_lds_dwordx4 v[234:235], off
	s_waitcnt vmcnt(8)
	s_waitcnt lgkmcnt(0)
	s_barrier
	s_setprio 1
	s_waitcnt lgkmcnt(0)
	v_mfma_f32_16x16x32_bf16 v[126:129], v[136:139], v[168:171], v[126:129]
	v_mfma_f32_16x16x32_bf16 v[122:125], v[144:147], v[168:171], v[122:125]
	v_mfma_f32_16x16x32_bf16 v[110:113], v[136:139], v[176:179], v[110:113]
	v_mfma_f32_16x16x32_bf16 v[106:109], v[144:147], v[176:179], v[106:109]
	v_mfma_f32_16x16x32_bf16 v[94:97], v[136:139], v[212:215], v[94:97]
	v_mfma_f32_16x16x32_bf16 v[90:93], v[144:147], v[212:215], v[90:93]
	v_mfma_f32_16x16x32_bf16 v[78:81], v[136:139], v[220:223], v[78:81]
	v_mfma_f32_16x16x32_bf16 v[74:77], v[144:147], v[220:223], v[74:77]
	v_mfma_f32_16x16x32_bf16 v[126:129], v[140:143], v[172:175], v[126:129]
	v_mfma_f32_16x16x32_bf16 v[122:125], v[148:151], v[172:175], v[122:125]
	v_mfma_f32_16x16x32_bf16 v[110:113], v[140:143], v[180:183], v[110:113]
	v_mfma_f32_16x16x32_bf16 v[106:109], v[148:151], v[180:183], v[106:109]
	v_mfma_f32_16x16x32_bf16 v[94:97], v[140:143], v[216:219], v[94:97]
	v_mfma_f32_16x16x32_bf16 v[90:93], v[148:151], v[216:219], v[90:93]
	v_mfma_f32_16x16x32_bf16 v[78:81], v[140:143], v[224:227], v[78:81]
	v_mfma_f32_16x16x32_bf16 v[74:77], v[148:151], v[224:227], v[74:77]
	s_setprio 0
	s_setprio 1
	v_mfma_f32_16x16x32_bf16 v[118:121], v[152:155], v[168:171], v[118:121]
	v_mfma_f32_16x16x32_bf16 v[114:117], v[160:163], v[168:171], v[114:117]
	v_mfma_f32_16x16x32_bf16 v[102:105], v[152:155], v[176:179], v[102:105]
	v_mfma_f32_16x16x32_bf16 v[98:101], v[160:163], v[176:179], v[98:101]
	v_mfma_f32_16x16x32_bf16 v[86:89], v[152:155], v[212:215], v[86:89]
	v_mfma_f32_16x16x32_bf16 v[82:85], v[160:163], v[212:215], v[82:85]
	v_mfma_f32_16x16x32_bf16 v[38:41], v[152:155], v[220:223], v[38:41]
	v_mfma_f32_16x16x32_bf16 v[16:19], v[160:163], v[220:223], v[16:19]
	v_mfma_f32_16x16x32_bf16 v[118:121], v[156:159], v[172:175], v[118:121]
	v_mfma_f32_16x16x32_bf16 v[114:117], v[164:167], v[172:175], v[114:117]
	v_mfma_f32_16x16x32_bf16 v[102:105], v[156:159], v[180:183], v[102:105]
	v_mfma_f32_16x16x32_bf16 v[98:101], v[164:167], v[180:183], v[98:101]
	v_mfma_f32_16x16x32_bf16 v[86:89], v[156:159], v[216:219], v[86:89]
	v_mfma_f32_16x16x32_bf16 v[82:85], v[164:167], v[216:219], v[82:85]
	v_mfma_f32_16x16x32_bf16 v[38:41], v[156:159], v[224:227], v[38:41]
	v_mfma_f32_16x16x32_bf16 v[16:19], v[164:167], v[224:227], v[16:19]
	s_setprio 0
	s_barrier
; #define STAGE(bufoff, GB) do { const char* g_ = (GB); \
;         _Pragma("unroll") for (int i_ = 0; i_ < 2; ++i_) __builtin_amdgcn_global_load_lds((const unsigned*)(g_ + voff[i_]), (LAS3 unsigned*)(L + (bufoff) + stoff + i_ * 8192), 16, 0, 0); } while (0)
; #define LDA(dst, b, h) do { _Pragma("unroll") for (int m = 0; m < 4; ++m) _Pragma("unroll") for (int k = 0; k < 2; ++k) dst[m][k] = *(const LAS3 bf16x8*)(L + SA(b, h) + aoff + m * 2048 + k * 1024); } while (0)
; #define WAIT_V(n) asm volatile("s_waitcnt vmcnt(" #n ")" ::: "memory")
; #define WAIT_L(n) asm volatile("s_waitcnt lgkmcnt(" #n ")" ::: "memory")
; #define BAR __builtin_amdgcn_s_barrier()
; #define SCHED __builtin_amdgcn_sched_barrier(0)
; template <int EPI>
; DI void gemm_phase(const bf16_t* __restrict__ A, const bf16_t* __restrict__ Bt, const int K, const int N, const Params& p, const int layer_j, char* lds) {
;     ...
;             LDA(At, 1, 1); STAGE(SB(1, 0), b3); STAGE(SB(1, 1), b3 + hstep); STAGE(SA(1, 0), a3);
;             WAIT_V(8); WAIT_L(0); BAR; MMA(1, 0, At, B0); MMA(1, 1, At, B1); BAR; SCHED;
;         }
	v_readfirstlane_b32 s6, v206
	v_lshl_add_u64 v[194:195], v[194:195], 0, s[94:95]
	s_mov_b32 m0, s6
	v_readfirstlane_b32 s6, v207
	s_add_u32 s16, s30, 0x40080
	ds_read_b128 v[168:171], v185 offset:49152
	ds_read_b128 v[172:175], v185 offset:50176
	ds_read_b128 v[176:179], v185 offset:51200
	ds_read_b128 v[180:183], v185 offset:52224
	ds_read_b128 v[212:215], v185 offset:53248
	ds_read_b128 v[216:219], v185 offset:54272
	ds_read_b128 v[220:223], v185 offset:55296
	ds_read_b128 v[224:227], v185 offset:56320
	global_load_lds_dwordx4 v[194:195], off
	v_lshl_add_u64 v[194:195], v[228:229], 0, s[94:95]
	s_mov_b32 m0, s6
	s_addc_u32 s17, s31, 0
	v_readfirstlane_b32 s6, v210
	global_load_lds_dwordx4 v[194:195], off
	v_lshl_add_u64 v[194:195], s[16:17], 0, v[32:33]
	s_mov_b32 m0, s6
	v_readfirstlane_b32 s6, v211
	global_load_lds_dwordx4 v[194:195], off
	v_lshl_add_u64 v[194:195], s[16:17], 0, v[130:131]
	s_mov_b32 m0, s6
	v_readfirstlane_b32 s6, v208
	global_load_lds_dwordx4 v[194:195], off
	v_lshl_add_u64 v[194:195], v[230:231], 0, s[94:95]
	s_mov_b32 m0, s6
	v_readfirstlane_b32 s6, v209
	global_load_lds_dwordx4 v[194:195], off
	v_lshl_add_u64 v[194:195], v[232:233], 0, s[94:95]
	s_mov_b32 m0, s6
	s_nop 0
	global_load_lds_dwordx4 v[194:195], off
	s_waitcnt vmcnt(8)
	s_waitcnt lgkmcnt(0)
	s_barrier
	s_setprio 1
	s_waitcnt lgkmcnt(0)
	v_mfma_f32_16x16x32_bf16 v[70:73], v[136:139], v[168:171], v[70:73]
	v_mfma_f32_16x16x32_bf16 v[54:57], v[144:147], v[168:171], v[54:57]
	v_mfma_f32_16x16x32_bf16 v[66:69], v[136:139], v[176:179], v[66:69]
	v_mfma_f32_16x16x32_bf16 v[50:53], v[144:147], v[176:179], v[50:53]
	v_mfma_f32_16x16x32_bf16 v[62:65], v[136:139], v[212:215], v[62:65]
	v_mfma_f32_16x16x32_bf16 v[46:49], v[144:147], v[212:215], v[46:49]
	v_mfma_f32_16x16x32_bf16 v[58:61], v[136:139], v[220:223], v[58:61]
	v_mfma_f32_16x16x32_bf16 v[42:45], v[144:147], v[220:223], v[42:45]
	v_mfma_f32_16x16x32_bf16 v[70:73], v[140:143], v[172:175], v[70:73]
	v_mfma_f32_16x16x32_bf16 v[54:57], v[148:151], v[172:175], v[54:57]
	v_mfma_f32_16x16x32_bf16 v[66:69], v[140:143], v[180:183], v[66:69]
	v_mfma_f32_16x16x32_bf16 v[50:53], v[148:151], v[180:183], v[50:53]
	v_mfma_f32_16x16x32_bf16 v[62:65], v[140:143], v[216:219], v[62:65]
	v_mfma_f32_16x16x32_bf16 v[46:49], v[148:151], v[216:219], v[46:49]
	v_mfma_f32_16x16x32_bf16 v[58:61], v[140:143], v[224:227], v[58:61]
	v_mfma_f32_16x16x32_bf16 v[42:45], v[148:151], v[224:227], v[42:45]
	s_setprio 0
	s_setprio 1
	v_mfma_f32_16x16x32_bf16 v[34:37], v[152:155], v[168:171], v[34:37]
	v_mfma_f32_16x16x32_bf16 v[12:15], v[160:163], v[168:171], v[12:15]
	v_mfma_f32_16x16x32_bf16 v[28:31], v[152:155], v[176:179], v[28:31]
	v_mfma_f32_16x16x32_bf16 v[8:11], v[160:163], v[176:179], v[8:11]
	v_mfma_f32_16x16x32_bf16 v[24:27], v[152:155], v[212:215], v[24:27]
	v_mfma_f32_16x16x32_bf16 v[4:7], v[160:163], v[212:215], v[4:7]
	v_mfma_f32_16x16x32_bf16 v[20:23], v[152:155], v[220:223], v[20:23]
	v_mfma_f32_16x16x32_bf16 v[0:3], v[160:163], v[220:223], v[0:3]
	v_mfma_f32_16x16x32_bf16 v[34:37], v[156:159], v[172:175], v[34:37]
	v_mfma_f32_16x16x32_bf16 v[12:15], v[164:167], v[172:175], v[12:15]
	v_mfma_f32_16x16x32_bf16 v[28:31], v[156:159], v[180:183], v[28:31]
	v_mfma_f32_16x16x32_bf16 v[8:11], v[164:167], v[180:183], v[8:11]
	v_mfma_f32_16x16x32_bf16 v[24:27], v[156:159], v[216:219], v[24:27]
	v_mfma_f32_16x16x32_bf16 v[4:7], v[164:167], v[216:219], v[4:7]
	v_mfma_f32_16x16x32_bf16 v[20:23], v[156:159], v[224:227], v[20:23]
	v_mfma_f32_16x16x32_bf16 v[0:3], v[164:167], v[224:227], v[0:3]
	s_setprio 0
	s_barrier
	s_add_i32 vcc_lo, vcc_lo, 2
	s_add_u32 s28, s28, 0x100
	s_addc_u32 s29, s29, 0
	s_cmp_gt_u32 vcc_lo, 13
	s_cbranch_scc0 .LBB0_338
	s_branch .Lrec_kloop_done

; #define STAGE(bufoff, GB) do { const char* g_ = (GB); \
;         _Pragma("unroll") for (int i_ = 0; i_ < 2; ++i_) __builtin_amdgcn_global_load_lds((const unsigned*)(g_ + voff[i_]), (LAS3 unsigned*)(L + (bufoff) + stoff + i_ * 8192), 16, 0, 0); } while (0)
; #define LDA(dst, b, h) do { _Pragma("unroll") for (int m = 0; m < 4; ++m) _Pragma("unroll") for (int k = 0; k < 2; ++k) dst[m][k] = *(const LAS3 bf16x8*)(L + SA(b, h) + aoff + m * 2048 + k * 1024); } while (0)
; #define LDB(dst, b, h) do { _Pragma("unroll") for (int n = 0; n < 2; ++n) _Pragma("unroll") for (int k = 0; k < 2; ++k) dst[n][k] = *(const LAS3 bf16x8*)(L + SB(b, h) + boff + n * 2048 + k * 1024); } while (0)
; #define WAIT_V(n) asm volatile("s_waitcnt vmcnt(" #n ")" ::: "memory")
; #define WAIT_L(n) asm volatile("s_waitcnt lgkmcnt(" #n ")" ::: "memory")
; #define BAR __builtin_amdgcn_s_barrier()
; #define SCHED __builtin_amdgcn_sched_barrier(0)
; template <int EPI>
; DI void gemm_phase(const bf16_t* __restrict__ A, const bf16_t* __restrict__ Bt, const int K, const int N, const Params& p, const int layer_j, char* lds) {
;     ...
;             WAIT_V(8); WAIT_L(0); BAR; MMA(0, 0, At, B0); MMA(0, 1, At, B1); BAR; SCHED;
;             LDA(At, 0, 1); STAGE(SB(0, 0), b2); STAGE(SB(0, 1), b2 + hstep); STAGE(SA(0, 0), a2);
;             WAIT_V(8); WAIT_L(0); BAR; MMA(1, 0, At, B0); MMA(1, 1, At, B1); BAR; SCHED;
;             LDB(B0, 1, 0); LDB(B1, 1, 1); SCHED; LDA(At, 1, 0); STAGE(SA(0, 1), a2 + hstep);
;             WAIT_V(8); WAIT_L(0); BAR; MMA(0, 0, At, B0); MMA(0, 1, At, B1); BAR; SCHED;
.Lskipw_recns_0:
	s_waitcnt lgkmcnt(0)
	s_barrier
	s_setprio 1
	s_waitcnt lgkmcnt(0)
	v_mfma_f32_16x16x32_bf16 v[126:129], v[168:171], v[136:139], v[126:129]
	v_mfma_f32_16x16x32_bf16 v[122:125], v[168:171], v[144:147], v[122:125]
	v_mfma_f32_16x16x32_bf16 v[110:113], v[176:179], v[136:139], v[110:113]
	v_mfma_f32_16x16x32_bf16 v[106:109], v[176:179], v[144:147], v[106:109]
	v_mfma_f32_16x16x32_bf16 v[94:97], v[212:215], v[136:139], v[94:97]
	v_mfma_f32_16x16x32_bf16 v[90:93], v[212:215], v[144:147], v[90:93]
	v_mfma_f32_16x16x32_bf16 v[78:81], v[220:223], v[136:139], v[78:81]
	v_mfma_f32_16x16x32_bf16 v[74:77], v[220:223], v[144:147], v[74:77]
	v_mfma_f32_16x16x32_bf16 v[126:129], v[172:175], v[140:143], v[126:129]
	v_mfma_f32_16x16x32_bf16 v[122:125], v[172:175], v[148:151], v[122:125]
	v_mfma_f32_16x16x32_bf16 v[110:113], v[180:183], v[140:143], v[110:113]
	v_mfma_f32_16x16x32_bf16 v[106:109], v[180:183], v[148:151], v[106:109]
	v_mfma_f32_16x16x32_bf16 v[94:97], v[216:219], v[140:143], v[94:97]
	v_mfma_f32_16x16x32_bf16 v[90:93], v[216:219], v[148:151], v[90:93]
	v_mfma_f32_16x16x32_bf16 v[78:81], v[224:227], v[140:143], v[78:81]
	v_mfma_f32_16x16x32_bf16 v[74:77], v[224:227], v[148:151], v[74:77]
	s_setprio 0
	s_setprio 1
	v_mfma_f32_16x16x32_bf16 v[118:121], v[168:171], v[152:155], v[118:121]
	v_mfma_f32_16x16x32_bf16 v[114:117], v[168:171], v[160:163], v[114:117]
	v_mfma_f32_16x16x32_bf16 v[102:105], v[176:179], v[152:155], v[102:105]
	v_mfma_f32_16x16x32_bf16 v[98:101], v[176:179], v[160:163], v[98:101]
	v_mfma_f32_16x16x32_bf16 v[86:89], v[212:215], v[152:155], v[86:89]
	v_mfma_f32_16x16x32_bf16 v[82:85], v[212:215], v[160:163], v[82:85]
	v_mfma_f32_16x16x32_bf16 v[38:41], v[220:223], v[152:155], v[38:41]
	v_mfma_f32_16x16x32_bf16 v[16:19], v[220:223], v[160:163], v[16:19]
	v_mfma_f32_16x16x32_bf16 v[118:121], v[172:175], v[156:159], v[118:121]
	v_mfma_f32_16x16x32_bf16 v[114:117], v[172:175], v[164:167], v[114:117]
	v_mfma_f32_16x16x32_bf16 v[102:105], v[180:183], v[156:159], v[102:105]
	v_mfma_f32_16x16x32_bf16 v[98:101], v[180:183], v[164:167], v[98:101]
	v_mfma_f32_16x16x32_bf16 v[86:89], v[216:219], v[156:159], v[86:89]
	v_mfma_f32_16x16x32_bf16 v[82:85], v[216:219], v[164:167], v[82:85]
	v_mfma_f32_16x16x32_bf16 v[38:41], v[224:227], v[156:159], v[38:41]
	v_mfma_f32_16x16x32_bf16 v[16:19], v[224:227], v[164:167], v[16:19]
	s_setprio 0
	s_barrier
	v_readfirstlane_b32 s16, v187
	v_lshl_add_u64 v[194:195], s[30:31], 0, v[32:33]
	s_mov_b32 m0, s16
	v_readfirstlane_b32 s16, v188
	ds_read_b128 v[168:171], v185 offset:16384
	ds_read_b128 v[172:175], v185 offset:17408
	ds_read_b128 v[176:179], v185 offset:18432
	ds_read_b128 v[180:183], v185 offset:19456
	ds_read_b128 v[212:215], v185 offset:20480
	ds_read_b128 v[216:219], v185 offset:21504
	ds_read_b128 v[220:223], v185 offset:22528
	ds_read_b128 v[224:227], v185 offset:23552
	global_load_lds_dwordx4 v[194:195], off
	s_mov_b32 m0, s16
	s_add_u32 s16, s30, 0x40000
	v_lshl_add_u64 v[228:229], s[30:31], 0, v[130:131]
	s_addc_u32 s17, s31, 0
	v_readfirstlane_b32 s6, v189
	global_load_lds_dwordx4 v[228:229], off
	v_lshl_add_u64 v[230:231], s[16:17], 0, v[32:33]
	s_mov_b32 m0, s6
	v_readfirstlane_b32 s6, v190
	global_load_lds_dwordx4 v[230:231], off
	v_lshl_add_u64 v[230:231], s[16:17], 0, v[130:131]
	s_mov_b32 m0, s6
	v_readfirstlane_b32 s6, v184
	global_load_lds_dwordx4 v[230:231], off
	v_lshl_add_u64 v[230:231], s[34:35], 0, v[32:33]
	s_mov_b32 m0, s6
	v_readfirstlane_b32 s6, v191
	global_load_lds_dwordx4 v[230:231], off
	v_lshl_add_u64 v[232:233], s[34:35], 0, v[130:131]
	s_mov_b32 m0, s6
	s_nop 0
	global_load_lds_dwordx4 v[232:233], off
	s_cmp_eq_u32 s100, 0
	s_cbranch_scc1 .Lskipw_recns_1
	s_waitcnt vmcnt(8)
.Lskipw_recns_1:
	s_waitcnt lgkmcnt(0)
	s_barrier
	s_setprio 1
	s_waitcnt lgkmcnt(0)
	v_mfma_f32_16x16x32_bf16 v[70:73], v[168:171], v[136:139], v[70:73]
	v_mfma_f32_16x16x32_bf16 v[54:57], v[168:171], v[144:147], v[54:57]
	v_mfma_f32_16x16x32_bf16 v[66:69], v[176:179], v[136:139], v[66:69]
	v_mfma_f32_16x16x32_bf16 v[50:53], v[176:179], v[144:147], v[50:53]
	v_mfma_f32_16x16x32_bf16 v[62:65], v[212:215], v[136:139], v[62:65]
	v_mfma_f32_16x16x32_bf16 v[46:49], v[212:215], v[144:147], v[46:49]
	v_mfma_f32_16x16x32_bf16 v[58:61], v[220:223], v[136:139], v[58:61]
	v_mfma_f32_16x16x32_bf16 v[42:45], v[220:223], v[144:147], v[42:45]
	v_mfma_f32_16x16x32_bf16 v[70:73], v[172:175], v[140:143], v[70:73]
	v_mfma_f32_16x16x32_bf16 v[54:57], v[172:175], v[148:151], v[54:57]
	v_mfma_f32_16x16x32_bf16 v[66:69], v[180:183], v[140:143], v[66:69]
	v_mfma_f32_16x16x32_bf16 v[50:53], v[180:183], v[148:151], v[50:53]
	v_mfma_f32_16x16x32_bf16 v[62:65], v[216:219], v[140:143], v[62:65]
	v_mfma_f32_16x16x32_bf16 v[46:49], v[216:219], v[148:151], v[46:49]
	v_mfma_f32_16x16x32_bf16 v[58:61], v[224:227], v[140:143], v[58:61]
	v_mfma_f32_16x16x32_bf16 v[42:45], v[224:227], v[148:151], v[42:45]
	s_setprio 0
	s_setprio 1
	v_mfma_f32_16x16x32_bf16 v[34:37], v[168:171], v[152:155], v[34:37]
	v_mfma_f32_16x16x32_bf16 v[12:15], v[168:171], v[160:163], v[12:15]
	v_mfma_f32_16x16x32_bf16 v[28:31], v[176:179], v[152:155], v[28:31]
	v_mfma_f32_16x16x32_bf16 v[8:11], v[176:179], v[160:163], v[8:11]
	v_mfma_f32_16x16x32_bf16 v[24:27], v[212:215], v[152:155], v[24:27]
	v_mfma_f32_16x16x32_bf16 v[4:7], v[212:215], v[160:163], v[4:7]
	v_mfma_f32_16x16x32_bf16 v[20:23], v[220:223], v[152:155], v[20:23]
	v_mfma_f32_16x16x32_bf16 v[0:3], v[220:223], v[160:163], v[0:3]
	v_mfma_f32_16x16x32_bf16 v[34:37], v[172:175], v[156:159], v[34:37]
	v_mfma_f32_16x16x32_bf16 v[12:15], v[172:175], v[164:167], v[12:15]
	v_mfma_f32_16x16x32_bf16 v[28:31], v[180:183], v[156:159], v[28:31]
	v_mfma_f32_16x16x32_bf16 v[8:11], v[180:183], v[164:167], v[8:11]
	v_mfma_f32_16x16x32_bf16 v[24:27], v[216:219], v[156:159], v[24:27]
	v_mfma_f32_16x16x32_bf16 v[4:7], v[216:219], v[164:167], v[4:7]
	v_mfma_f32_16x16x32_bf16 v[20:23], v[224:227], v[156:159], v[20:23]
	v_mfma_f32_16x16x32_bf16 v[0:3], v[224:227], v[164:167], v[0:3]
	s_setprio 0
	s_barrier
; #define STAGE(bufoff, GB) do { const char* g_ = (GB); \
;         _Pragma("unroll") for (int i_ = 0; i_ < 2; ++i_) __builtin_amdgcn_global_load_lds((const unsigned*)(g_ + voff[i_]), (LAS3 unsigned*)(L + (bufoff) + stoff + i_ * 8192), 16, 0, 0); } while (0)
; #define LDA(dst, b, h) do { _Pragma("unroll") for (int m = 0; m < 4; ++m) _Pragma("unroll") for (int k = 0; k < 2; ++k) dst[m][k] = *(const LAS3 bf16x8*)(L + SA(b, h) + aoff + m * 2048 + k * 1024); } while (0)
; #define LDB(dst, b, h) do { _Pragma("unroll") for (int n = 0; n < 2; ++n) _Pragma("unroll") for (int k = 0; k < 2; ++k) dst[n][k] = *(const LAS3 bf16x8*)(L + SB(b, h) + boff + n * 2048 + k * 1024); } while (0)
; #define WAIT_V(n) asm volatile("s_waitcnt vmcnt(" #n ")" ::: "memory")
; #define WAIT_L(n) asm volatile("s_waitcnt lgkmcnt(" #n ")" ::: "memory")
; #define BAR __builtin_amdgcn_s_barrier()
; #define SCHED __builtin_amdgcn_sched_barrier(0)
; template <int EPI>
; DI void gemm_phase(const bf16_t* __restrict__ A, const bf16_t* __restrict__ Bt, const int K, const int N, const Params& p, const int layer_j, char* lds) {
;     ...
;             LDB(B0, 1, 0); LDB(B1, 1, 1); SCHED; LDA(At, 1, 0); STAGE(SA(0, 1), a2 + hstep);
;             WAIT_V(8); WAIT_L(0); BAR; MMA(0, 0, At, B0); MMA(0, 1, At, B1); BAR; SCHED;
	v_add_u32_e32 v148, 0x18000, v186
	v_add_u32_e32 v164, 0x1c000, v186
	ds_read_b128 v[136:139], v148
	ds_read_b128 v[140:143], v148 offset:1024
	ds_read_b128 v[144:147], v148 offset:2048
	ds_read_b128 v[148:151], v148 offset:3072
	ds_read_b128 v[152:155], v164
	ds_read_b128 v[156:159], v164 offset:1024
	ds_read_b128 v[160:163], v164 offset:2048
	ds_read_b128 v[164:167], v164 offset:3072
	s_add_u32 s16, s34, 0x40000
	s_addc_u32 s17, s35, 0
	v_readfirstlane_b32 s6, v204
	v_lshl_add_u64 v[234:235], s[16:17], 0, v[32:33]
	s_mov_b32 m0, s6
	v_readfirstlane_b32 s6, v205
	ds_read_b128 v[168:171], v185 offset:32768
	ds_read_b128 v[172:175], v185 offset:33792
	ds_read_b128 v[176:179], v185 offset:34816
	ds_read_b128 v[180:183], v185 offset:35840
	ds_read_b128 v[212:215], v185 offset:36864
	ds_read_b128 v[216:219], v185 offset:37888
	ds_read_b128 v[220:223], v185 offset:38912
	ds_read_b128 v[224:227], v185 offset:39936
	global_load_lds_dwordx4 v[234:235], off
	v_lshl_add_u64 v[234:235], s[16:17], 0, v[130:131]
	s_mov_b32 m0, s6
	s_nop 0
	global_load_lds_dwordx4 v[234:235], off
	s_waitcnt vmcnt(8)
	s_waitcnt lgkmcnt(0)
	s_barrier
	s_setprio 1
	s_waitcnt lgkmcnt(0)
	v_mfma_f32_16x16x32_bf16 v[126:129], v[168:171], v[136:139], v[126:129]
	v_mfma_f32_16x16x32_bf16 v[122:125], v[168:171], v[144:147], v[122:125]
	v_mfma_f32_16x16x32_bf16 v[110:113], v[176:179], v[136:139], v[110:113]
	v_mfma_f32_16x16x32_bf16 v[106:109], v[176:179], v[144:147], v[106:109]
	v_mfma_f32_16x16x32_bf16 v[94:97], v[212:215], v[136:139], v[94:97]
	v_mfma_f32_16x16x32_bf16 v[90:93], v[212:215], v[144:147], v[90:93]
	v_mfma_f32_16x16x32_bf16 v[78:81], v[220:223], v[136:139], v[78:81]
	v_mfma_f32_16x16x32_bf16 v[74:77], v[220:223], v[144:147], v[74:77]
	v_mfma_f32_16x16x32_bf16 v[126:129], v[172:175], v[140:143], v[126:129]
	v_mfma_f32_16x16x32_bf16 v[122:125], v[172:175], v[148:151], v[122:125]
	v_mfma_f32_16x16x32_bf16 v[110:113], v[180:183], v[140:143], v[110:113]
	v_mfma_f32_16x16x32_bf16 v[106:109], v[180:183], v[148:151], v[106:109]
	v_mfma_f32_16x16x32_bf16 v[94:97], v[216:219], v[140:143], v[94:97]
	v_mfma_f32_16x16x32_bf16 v[90:93], v[216:219], v[148:151], v[90:93]
	v_mfma_f32_16x16x32_bf16 v[78:81], v[224:227], v[140:143], v[78:81]
	v_mfma_f32_16x16x32_bf16 v[74:77], v[224:227], v[148:151], v[74:77]
	s_setprio 0
	s_setprio 1
	v_mfma_f32_16x16x32_bf16 v[118:121], v[168:171], v[152:155], v[118:121]
	v_mfma_f32_16x16x32_bf16 v[114:117], v[168:171], v[160:163], v[114:117]
	v_mfma_f32_16x16x32_bf16 v[102:105], v[176:179], v[152:155], v[102:105]
	v_mfma_f32_16x16x32_bf16 v[98:101], v[176:179], v[160:163], v[98:101]
	v_mfma_f32_16x16x32_bf16 v[86:89], v[212:215], v[152:155], v[86:89]
	v_mfma_f32_16x16x32_bf16 v[82:85], v[212:215], v[160:163], v[82:85]
	v_mfma_f32_16x16x32_bf16 v[38:41], v[220:223], v[152:155], v[38:41]
	v_mfma_f32_16x16x32_bf16 v[16:19], v[220:223], v[160:163], v[16:19]
	v_mfma_f32_16x16x32_bf16 v[118:121], v[172:175], v[156:159], v[118:121]
	v_mfma_f32_16x16x32_bf16 v[114:117], v[172:175], v[164:167], v[114:117]
	v_mfma_f32_16x16x32_bf16 v[102:105], v[180:183], v[156:159], v[102:105]
	v_mfma_f32_16x16x32_bf16 v[98:101], v[180:183], v[164:167], v[98:101]
	v_mfma_f32_16x16x32_bf16 v[86:89], v[216:219], v[156:159], v[86:89]
	v_mfma_f32_16x16x32_bf16 v[82:85], v[216:219], v[164:167], v[82:85]
	v_mfma_f32_16x16x32_bf16 v[38:41], v[224:227], v[156:159], v[38:41]
	v_mfma_f32_16x16x32_bf16 v[16:19], v[224:227], v[164:167], v[16:19]
	s_setprio 0
	s_barrier
; #define STAGE(bufoff, GB) do { const char* g_ = (GB); \
;         _Pragma("unroll") for (int i_ = 0; i_ < 2; ++i_) __builtin_amdgcn_global_load_lds((const unsigned*)(g_ + voff[i_]), (LAS3 unsigned*)(L + (bufoff) + stoff + i_ * 8192), 16, 0, 0); } while (0)
; #define LDA(dst, b, h) do { _Pragma("unroll") for (int m = 0; m < 4; ++m) _Pragma("unroll") for (int k = 0; k < 2; ++k) dst[m][k] = *(const LAS3 bf16x8*)(L + SA(b, h) + aoff + m * 2048 + k * 1024); } while (0)
; #define WAIT_V(n) asm volatile("s_waitcnt vmcnt(" #n ")" ::: "memory")
; #define WAIT_L(n) asm volatile("s_waitcnt lgkmcnt(" #n ")" ::: "memory")
; #define BAR __builtin_amdgcn_s_barrier()
; #define SCHED __builtin_amdgcn_sched_barrier(0)
; template <int EPI>
; DI void gemm_phase(const bf16_t* __restrict__ A, const bf16_t* __restrict__ Bt, const int K, const int N, const Params& p, const int layer_j, char* lds) {
;     ...
;             LDA(At, 1, 1); STAGE(SB(1, 0), b3); STAGE(SB(1, 1), b3 + hstep); STAGE(SA(1, 0), a3);
;             WAIT_V(8); WAIT_L(0); BAR; MMA(1, 0, At, B0); MMA(1, 1, At, B1); BAR; SCHED;
;         }
	v_readfirstlane_b32 s6, v206
	v_lshl_add_u64 v[194:195], v[194:195], 0, s[94:95]
	s_mov_b32 m0, s6
	v_readfirstlane_b32 s6, v207
	s_add_u32 s16, s30, 0x40080
	ds_read_b128 v[168:171], v185 offset:49152
	ds_read_b128 v[172:175], v185 offset:50176
	ds_read_b128 v[176:179], v185 offset:51200
	ds_read_b128 v[180:183], v185 offset:52224
	ds_read_b128 v[212:215], v185 offset:53248
	ds_read_b128 v[216:219], v185 offset:54272
	ds_read_b128 v[220:223], v185 offset:55296
	ds_read_b128 v[224:227], v185 offset:56320
	global_load_lds_dwordx4 v[194:195], off
	v_lshl_add_u64 v[194:195], v[228:229], 0, s[94:95]
	s_mov_b32 m0, s6
	s_addc_u32 s17, s31, 0
	v_readfirstlane_b32 s6, v210
	global_load_lds_dwordx4 v[194:195], off
	v_lshl_add_u64 v[194:195], s[16:17], 0, v[32:33]
	s_mov_b32 m0, s6
	v_readfirstlane_b32 s6, v211
	global_load_lds_dwordx4 v[194:195], off
	v_lshl_add_u64 v[194:195], s[16:17], 0, v[130:131]
	s_mov_b32 m0, s6
	v_readfirstlane_b32 s6, v208
	global_load_lds_dwordx4 v[194:195], off
	v_lshl_add_u64 v[194:195], v[230:231], 0, s[94:95]
	s_mov_b32 m0, s6
	v_readfirstlane_b32 s6, v209
	global_load_lds_dwordx4 v[194:195], off
	v_lshl_add_u64 v[194:195], v[232:233], 0, s[94:95]
	s_mov_b32 m0, s6
	s_nop 0
	global_load_lds_dwordx4 v[194:195], off
	s_waitcnt vmcnt(8)
	s_waitcnt lgkmcnt(0)
	s_barrier
	s_setprio 1
	s_waitcnt lgkmcnt(0)
	v_mfma_f32_16x16x32_bf16 v[70:73], v[168:171], v[136:139], v[70:73]
	v_mfma_f32_16x16x32_bf16 v[54:57], v[168:171], v[144:147], v[54:57]
	v_mfma_f32_16x16x32_bf16 v[66:69], v[176:179], v[136:139], v[66:69]
	v_mfma_f32_16x16x32_bf16 v[50:53], v[176:179], v[144:147], v[50:53]
	v_mfma_f32_16x16x32_bf16 v[62:65], v[212:215], v[136:139], v[62:65]
	v_mfma_f32_16x16x32_bf16 v[46:49], v[212:215], v[144:147], v[46:49]
	v_mfma_f32_16x16x32_bf16 v[58:61], v[220:223], v[136:139], v[58:61]
	v_mfma_f32_16x16x32_bf16 v[42:45], v[220:223], v[144:147], v[42:45]
	v_mfma_f32_16x16x32_bf16 v[70:73], v[172:175], v[140:143], v[70:73]
	v_mfma_f32_16x16x32_bf16 v[54:57], v[172:175], v[148:151], v[54:57]
	v_mfma_f32_16x16x32_bf16 v[66:69], v[180:183], v[140:143], v[66:69]
	v_mfma_f32_16x16x32_bf16 v[50:53], v[180:183], v[148:151], v[50:53]
	v_mfma_f32_16x16x32_bf16 v[62:65], v[216:219], v[140:143], v[62:65]
	v_mfma_f32_16x16x32_bf16 v[46:49], v[216:219], v[148:151], v[46:49]
	v_mfma_f32_16x16x32_bf16 v[58:61], v[224:227], v[140:143], v[58:61]
	v_mfma_f32_16x16x32_bf16 v[42:45], v[224:227], v[148:151], v[42:45]
	s_setprio 0
	s_setprio 1
	v_mfma_f32_16x16x32_bf16 v[34:37], v[168:171], v[152:155], v[34:37]
	v_mfma_f32_16x16x32_bf16 v[12:15], v[168:171], v[160:163], v[12:15]
	v_mfma_f32_16x16x32_bf16 v[28:31], v[176:179], v[152:155], v[28:31]
	v_mfma_f32_16x16x32_bf16 v[8:11], v[176:179], v[160:163], v[8:11]
	v_mfma_f32_16x16x32_bf16 v[24:27], v[212:215], v[152:155], v[24:27]
	v_mfma_f32_16x16x32_bf16 v[4:7], v[212:215], v[160:163], v[4:7]
	v_mfma_f32_16x16x32_bf16 v[20:23], v[220:223], v[152:155], v[20:23]
	v_mfma_f32_16x16x32_bf16 v[0:3], v[220:223], v[160:163], v[0:3]
	v_mfma_f32_16x16x32_bf16 v[34:37], v[172:175], v[156:159], v[34:37]
	v_mfma_f32_16x16x32_bf16 v[12:15], v[172:175], v[164:167], v[12:15]
	v_mfma_f32_16x16x32_bf16 v[28:31], v[180:183], v[156:159], v[28:31]
	v_mfma_f32_16x16x32_bf16 v[8:11], v[180:183], v[164:167], v[8:11]
	v_mfma_f32_16x16x32_bf16 v[24:27], v[216:219], v[156:159], v[24:27]
	v_mfma_f32_16x16x32_bf16 v[4:7], v[216:219], v[164:167], v[4:7]
	v_mfma_f32_16x16x32_bf16 v[20:23], v[224:227], v[156:159], v[20:23]
	v_mfma_f32_16x16x32_bf16 v[0:3], v[224:227], v[164:167], v[0:3]
	s_setprio 0
	s_barrier
	s_add_i32 vcc_lo, vcc_lo, 2
	s_add_u32 s28, s28, 0x100
	s_addc_u32 s29, s29, 0
	s_cmp_gt_u32 vcc_lo, 13
	s_cbranch_scc0 .Lrec_kloop_ns

; DI bf16_t f2bf(float a) { return (bf16_t)(pk_bf16(a, 0.f) & 0xffffu); }
; DI float silu_f(float x) { return x * __builtin_amdgcn_rcpf(1.f + __expf(-x)); }
; template <int EPI>
; DI void gemm_phase(const bf16_t* __restrict__ A, const bf16_t* __restrict__ Bt, const int K, const int N, const Params& p, const int layer_j, char* lds) {
;     ...
;             } else {
;                 const int dc0 = (region == 0) ? col0 : (col0 - 3072 + 2048);
;                 const float sc = (region == 0) ? 0.08838834764831845f : 1.0f;
;                 bf16_t* dst = PROJ + (size_t)row0 * ATT_IN + dc0 + fr;
; #pragma unroll
;                 for (int ai = 0; ai < 2; ++ai)
; #pragma unroll
;                     for (int m = 0; m < 4; ++m)
; #pragma unroll
;                         for (int j = 0; j < 4; ++j)
; #pragma unroll
;                             for (int bj = 0; bj < 2; ++bj)
; #pragma unroll
;                                 for (int n = 0; n < 2; ++n) dst[(size_t)(ai * 128 + m * 16 + j) * ATT_IN + bj * 32 + n * 16] = f2bf(silu_f(acc[ai][bj][m][n][j]) * sc);
;             }
.Lrec_epi_silu:
	v_mbcnt_lo_u32_b32 v212, -1, 0
	v_mbcnt_hi_u32_b32 v212, -1, v212
	s_mul_i32 s16, s71, 34
	s_add_i32 s16, s16, 0x20100
	v_and_b32_e32 v213, 15, v212
	v_lshrrev_b32_e32 v214, 4, v212
	v_mul_u32_u24_e32 v213, 136, v213
	v_lshl_add_u32 v213, v214, 3, v213
	v_add_u32_e32 v213, s16, v213
	v_lshrrev_b32_e32 v215, 3, v212
	v_and_b32_e32 v216, 7, v212
	v_mul_u32_u24_e32 v214, 136, v215
	v_lshl_add_u32 v214, v216, 4, v214
	v_add_u32_e32 v214, s16, v214
	v_readlane_b32 s16, v254, 7
	v_readlane_b32 s17, v254, 14
	v_lshlrev_b32_e32 v216, 4, v216
	v_add_u32_e32 v215, s16, v215
	s_lshl_b32 s17, s17, 1
	s_mov_b32 s16, 6144
	v_mad_u32_u24 v215, v215, s16, v216
	v_add_u32_e32 v215, s17, v215
	v_add_u32_e32 v216, 0xc000, v215
	s_mul_i32 s16, s8, 0x180000
	s_mul_hi_u32 s17, s8, 0x180000
	s_lshl_b32 s28, s4, 9
	s_cmp_eq_u32 s5, 0
	s_cselect_b32 s29, 0, 0xfffff800
	s_cselect_b32 s35, 0x3db504f3, 1.0
	s_add_i32 s28, s28, s29
	s_add_u32 s16, s16, s28
	s_addc_u32 s17, s17, 0
	s_add_u32 s16, s16, s10
	s_addc_u32 s17, s17, s11
	v_mul_f32_e32 v136, 0xbfb8aa3b, v126
	v_mul_f32_e32 v137, 0xbfb8aa3b, v127
	v_mul_f32_e32 v138, 0xbfb8aa3b, v128
	v_mul_f32_e32 v139, 0xbfb8aa3b, v129
	v_mul_f32_e32 v140, 0xbfb8aa3b, v122
	v_mul_f32_e32 v141, 0xbfb8aa3b, v123
	v_mul_f32_e32 v142, 0xbfb8aa3b, v124
	v_mul_f32_e32 v143, 0xbfb8aa3b, v125
	v_mul_f32_e32 v144, 0xbfb8aa3b, v118
	v_mul_f32_e32 v145, 0xbfb8aa3b, v119
	v_mul_f32_e32 v146, 0xbfb8aa3b, v120
	v_mul_f32_e32 v147, 0xbfb8aa3b, v121
	v_mul_f32_e32 v148, 0xbfb8aa3b, v114
	v_mul_f32_e32 v149, 0xbfb8aa3b, v115
	v_mul_f32_e32 v150, 0xbfb8aa3b, v116
	v_mul_f32_e32 v151, 0xbfb8aa3b, v117
	v_exp_f32_e32 v136, v136
	v_exp_f32_e32 v137, v137
	v_exp_f32_e32 v138, v138
	v_exp_f32_e32 v139, v139
	v_exp_f32_e32 v140, v140
	v_exp_f32_e32 v141, v141
	v_exp_f32_e32 v142, v142
	v_exp_f32_e32 v143, v143
	v_exp_f32_e32 v144, v144
	v_exp_f32_e32 v145, v145
	v_exp_f32_e32 v146, v146
	v_exp_f32_e32 v147, v147
	v_exp_f32_e32 v148, v148
	v_exp_f32_e32 v149, v149
	v_exp_f32_e32 v150, v150
	v_exp_f32_e32 v151, v151
	v_add_f32_e32 v136, 1.0, v136
	v_add_f32_e32 v137, 1.0, v137
	v_add_f32_e32 v138, 1.0, v138
	v_add_f32_e32 v139, 1.0, v139
	v_add_f32_e32 v140, 1.0, v140
	v_add_f32_e32 v141, 1.0, v141
	v_add_f32_e32 v142, 1.0, v142
	v_add_f32_e32 v143, 1.0, v143
	v_add_f32_e32 v144, 1.0, v144
	v_add_f32_e32 v145, 1.0, v145
	v_add_f32_e32 v146, 1.0, v146
	v_add_f32_e32 v147, 1.0, v147
	v_add_f32_e32 v148, 1.0, v148
	v_add_f32_e32 v149, 1.0, v149
	v_add_f32_e32 v150, 1.0, v150
	v_add_f32_e32 v151, 1.0, v151
	v_rcp_f32_e32 v136, v136
	v_rcp_f32_e32 v137, v137
	v_rcp_f32_e32 v138, v138
	v_rcp_f32_e32 v139, v139
	v_rcp_f32_e32 v140, v140
	v_rcp_f32_e32 v141, v141
	v_rcp_f32_e32 v142, v142
	v_rcp_f32_e32 v143, v143
	v_rcp_f32_e32 v144, v144
	v_rcp_f32_e32 v145, v145
	v_rcp_f32_e32 v146, v146
	v_rcp_f32_e32 v147, v147
	v_rcp_f32_e32 v148, v148
	v_rcp_f32_e32 v149, v149
	v_rcp_f32_e32 v150, v150
	v_rcp_f32_e32 v151, v151
	v_mul_f32_e32 v126, v126, v136
	v_mul_f32_e32 v127, v127, v137
	v_mul_f32_e32 v128, v128, v138
	v_mul_f32_e32 v129, v129, v139
	v_mul_f32_e32 v122, v122, v140
	v_mul_f32_e32 v123, v123, v141
	v_mul_f32_e32 v124, v124, v142
	v_mul_f32_e32 v125, v125, v143
	v_mul_f32_e32 v118, v118, v144
	v_mul_f32_e32 v119, v119, v145
	v_mul_f32_e32 v120, v120, v146
	v_mul_f32_e32 v121, v121, v147
	v_mul_f32_e32 v114, v114, v148
	v_mul_f32_e32 v115, v115, v149
	v_mul_f32_e32 v116, v116, v150
	v_mul_f32_e32 v117, v117, v151
	v_mul_f32_e32 v126, s35, v126
	v_mul_f32_e32 v127, s35, v127
	v_mul_f32_e32 v128, s35, v128
	v_mul_f32_e32 v129, s35, v129
	v_mul_f32_e32 v122, s35, v122
	v_mul_f32_e32 v123, s35, v123
	v_mul_f32_e32 v124, s35, v124
	v_mul_f32_e32 v125, s35, v125
	v_mul_f32_e32 v118, s35, v118
	v_mul_f32_e32 v119, s35, v119
	v_mul_f32_e32 v120, s35, v120
	v_mul_f32_e32 v121, s35, v121
	v_mul_f32_e32 v114, s35, v114
	v_mul_f32_e32 v115, s35, v115
	v_mul_f32_e32 v116, s35, v116
	v_mul_f32_e32 v117, s35, v117
	v_cvt_pk_bf16_f32 v160, v126, v127
	v_cvt_pk_bf16_f32 v161, v128, v129
	v_cvt_pk_bf16_f32 v162, v122, v123
	v_cvt_pk_bf16_f32 v163, v124, v125
	v_cvt_pk_bf16_f32 v164, v118, v119
	v_cvt_pk_bf16_f32 v165, v120, v121
	v_cvt_pk_bf16_f32 v166, v114, v115
	v_cvt_pk_bf16_f32 v167, v116, v117
	ds_write_b64 v213, v[160:161]
	ds_write_b64 v213, v[162:163] offset:32
	ds_write_b64 v213, v[164:165] offset:64
	ds_write_b64 v213, v[166:167] offset:96
	ds_read2_b64 v[168:171], v214 offset1:1
	ds_read2_b64 v[172:175], v214 offset0:136 offset1:137
	s_waitcnt lgkmcnt(0)
; DI bf16_t f2bf(float a) { return (bf16_t)(pk_bf16(a, 0.f) & 0xffffu); }
; DI float silu_f(float x) { return x * __builtin_amdgcn_rcpf(1.f + __expf(-x)); }
; template <int EPI>
; DI void gemm_phase(const bf16_t* __restrict__ A, const bf16_t* __restrict__ Bt, const int K, const int N, const Params& p, const int layer_j, char* lds) {
;     ...
;             } else {
;                 const int dc0 = (region == 0) ? col0 : (col0 - 3072 + 2048);
;                 const float sc = (region == 0) ? 0.08838834764831845f : 1.0f;
;                 bf16_t* dst = PROJ + (size_t)row0 * ATT_IN + dc0 + fr;
; #pragma unroll
;                 for (int ai = 0; ai < 2; ++ai)
; #pragma unroll
;                     for (int m = 0; m < 4; ++m)
; #pragma unroll
;                         for (int j = 0; j < 4; ++j)
; #pragma unroll
;                             for (int bj = 0; bj < 2; ++bj)
; #pragma unroll
;                                 for (int n = 0; n < 2; ++n) dst[(size_t)(ai * 128 + m * 16 + j) * ATT_IN + bj * 32 + n * 16] = f2bf(silu_f(acc[ai][bj][m][n][j]) * sc);
;             }
	global_store_dwordx4 v215, v[168:171], s[16:17]
	global_store_dwordx4 v216, v[172:175], s[16:17]
	v_mul_f32_e32 v136, 0xbfb8aa3b, v110
	v_mul_f32_e32 v137, 0xbfb8aa3b, v111
	v_mul_f32_e32 v138, 0xbfb8aa3b, v112
	v_mul_f32_e32 v139, 0xbfb8aa3b, v113
	v_mul_f32_e32 v140, 0xbfb8aa3b, v106
	v_mul_f32_e32 v141, 0xbfb8aa3b, v107
	v_mul_f32_e32 v142, 0xbfb8aa3b, v108
	v_mul_f32_e32 v143, 0xbfb8aa3b, v109
	v_mul_f32_e32 v144, 0xbfb8aa3b, v102
	v_mul_f32_e32 v145, 0xbfb8aa3b, v103
	v_mul_f32_e32 v146, 0xbfb8aa3b, v104
	v_mul_f32_e32 v147, 0xbfb8aa3b, v105
	v_mul_f32_e32 v148, 0xbfb8aa3b, v98
	v_mul_f32_e32 v149, 0xbfb8aa3b, v99
	v_mul_f32_e32 v150, 0xbfb8aa3b, v100
	v_mul_f32_e32 v151, 0xbfb8aa3b, v101
	v_exp_f32_e32 v136, v136
	v_exp_f32_e32 v137, v137
	v_exp_f32_e32 v138, v138
	v_exp_f32_e32 v139, v139
	v_exp_f32_e32 v140, v140
	v_exp_f32_e32 v141, v141
	v_exp_f32_e32 v142, v142
	v_exp_f32_e32 v143, v143
	v_exp_f32_e32 v144, v144
	v_exp_f32_e32 v145, v145
	v_exp_f32_e32 v146, v146
	v_exp_f32_e32 v147, v147
	v_exp_f32_e32 v148, v148
	v_exp_f32_e32 v149, v149
	v_exp_f32_e32 v150, v150
	v_exp_f32_e32 v151, v151
	v_add_f32_e32 v136, 1.0, v136
	v_add_f32_e32 v137, 1.0, v137
	v_add_f32_e32 v138, 1.0, v138
	v_add_f32_e32 v139, 1.0, v139
	v_add_f32_e32 v140, 1.0, v140
	v_add_f32_e32 v141, 1.0, v141
	v_add_f32_e32 v142, 1.0, v142
	v_add_f32_e32 v143, 1.0, v143
	v_add_f32_e32 v144, 1.0, v144
	v_add_f32_e32 v145, 1.0, v145
	v_add_f32_e32 v146, 1.0, v146
	v_add_f32_e32 v147, 1.0, v147
	v_add_f32_e32 v148, 1.0, v148
	v_add_f32_e32 v149, 1.0, v149
	v_add_f32_e32 v150, 1.0, v150
	v_add_f32_e32 v151, 1.0, v151
	v_rcp_f32_e32 v136, v136
	v_rcp_f32_e32 v137, v137
	v_rcp_f32_e32 v138, v138
	v_rcp_f32_e32 v139, v139
	v_rcp_f32_e32 v140, v140
	v_rcp_f32_e32 v141, v141
	v_rcp_f32_e32 v142, v142
	v_rcp_f32_e32 v143, v143
	v_rcp_f32_e32 v144, v144
	v_rcp_f32_e32 v145, v145
	v_rcp_f32_e32 v146, v146
	v_rcp_f32_e32 v147, v147
	v_rcp_f32_e32 v148, v148
	v_rcp_f32_e32 v149, v149
	v_rcp_f32_e32 v150, v150
	v_rcp_f32_e32 v151, v151
	v_mul_f32_e32 v110, v110, v136
	v_mul_f32_e32 v111, v111, v137
	v_mul_f32_e32 v112, v112, v138
	v_mul_f32_e32 v113, v113, v139
	v_mul_f32_e32 v106, v106, v140
	v_mul_f32_e32 v107, v107, v141
	v_mul_f32_e32 v108, v108, v142
	v_mul_f32_e32 v109, v109, v143
	v_mul_f32_e32 v102, v102, v144
	v_mul_f32_e32 v103, v103, v145
	v_mul_f32_e32 v104, v104, v146
	v_mul_f32_e32 v105, v105, v147
	v_mul_f32_e32 v98, v98, v148
	v_mul_f32_e32 v99, v99, v149
	v_mul_f32_e32 v100, v100, v150
	v_mul_f32_e32 v101, v101, v151
	v_mul_f32_e32 v110, s35, v110
	v_mul_f32_e32 v111, s35, v111
	v_mul_f32_e32 v112, s35, v112
	v_mul_f32_e32 v113, s35, v113
	v_mul_f32_e32 v106, s35, v106
	v_mul_f32_e32 v107, s35, v107
	v_mul_f32_e32 v108, s35, v108
	v_mul_f32_e32 v109, s35, v109
	v_mul_f32_e32 v102, s35, v102
	v_mul_f32_e32 v103, s35, v103
	v_mul_f32_e32 v104, s35, v104
	v_mul_f32_e32 v105, s35, v105
	v_mul_f32_e32 v98, s35, v98
	v_mul_f32_e32 v99, s35, v99
	v_mul_f32_e32 v100, s35, v100
	v_mul_f32_e32 v101, s35, v101
	v_cvt_pk_bf16_f32 v160, v110, v111
	v_cvt_pk_bf16_f32 v161, v112, v113
	v_cvt_pk_bf16_f32 v162, v106, v107
	v_cvt_pk_bf16_f32 v163, v108, v109
	v_cvt_pk_bf16_f32 v164, v102, v103
	v_cvt_pk_bf16_f32 v165, v104, v105
	v_cvt_pk_bf16_f32 v166, v98, v99
	v_cvt_pk_bf16_f32 v167, v100, v101
	ds_write_b64 v213, v[160:161]
	ds_write_b64 v213, v[162:163] offset:32
	ds_write_b64 v213, v[164:165] offset:64
	ds_write_b64 v213, v[166:167] offset:96
	ds_read2_b64 v[168:171], v214 offset1:1
	ds_read2_b64 v[172:175], v214 offset0:136 offset1:137
	v_add_u32_e32 v217, 0x18000, v215
	v_add_u32_e32 v218, 0x18000, v216
	s_waitcnt lgkmcnt(0)
	global_store_dwordx4 v217, v[168:171], s[16:17]
	global_store_dwordx4 v218, v[172:175], s[16:17]
	v_mul_f32_e32 v136, 0xbfb8aa3b, v94
	v_mul_f32_e32 v137, 0xbfb8aa3b, v95
	v_mul_f32_e32 v138, 0xbfb8aa3b, v96
	v_mul_f32_e32 v139, 0xbfb8aa3b, v97
	v_mul_f32_e32 v140, 0xbfb8aa3b, v90
	v_mul_f32_e32 v141, 0xbfb8aa3b, v91
	v_mul_f32_e32 v142, 0xbfb8aa3b, v92
	v_mul_f32_e32 v143, 0xbfb8aa3b, v93
	v_mul_f32_e32 v144, 0xbfb8aa3b, v86
	v_mul_f32_e32 v145, 0xbfb8aa3b, v87
	v_mul_f32_e32 v146, 0xbfb8aa3b, v88
	v_mul_f32_e32 v147, 0xbfb8aa3b, v89
	v_mul_f32_e32 v148, 0xbfb8aa3b, v82
	v_mul_f32_e32 v149, 0xbfb8aa3b, v83
	v_mul_f32_e32 v150, 0xbfb8aa3b, v84
	v_mul_f32_e32 v151, 0xbfb8aa3b, v85
	v_exp_f32_e32 v136, v136
	v_exp_f32_e32 v137, v137
	v_exp_f32_e32 v138, v138
	v_exp_f32_e32 v139, v139
	v_exp_f32_e32 v140, v140
	v_exp_f32_e32 v141, v141
	v_exp_f32_e32 v142, v142
	v_exp_f32_e32 v143, v143
	v_exp_f32_e32 v144, v144
	v_exp_f32_e32 v145, v145
	v_exp_f32_e32 v146, v146
	v_exp_f32_e32 v147, v147
	v_exp_f32_e32 v148, v148
	v_exp_f32_e32 v149, v149
	v_exp_f32_e32 v150, v150
	v_exp_f32_e32 v151, v151
	v_add_f32_e32 v136, 1.0, v136
	v_add_f32_e32 v137, 1.0, v137
	v_add_f32_e32 v138, 1.0, v138
	v_add_f32_e32 v139, 1.0, v139
	v_add_f32_e32 v140, 1.0, v140
	v_add_f32_e32 v141, 1.0, v141
	v_add_f32_e32 v142, 1.0, v142
	v_add_f32_e32 v143, 1.0, v143
	v_add_f32_e32 v144, 1.0, v144
	v_add_f32_e32 v145, 1.0, v145
	v_add_f32_e32 v146, 1.0, v146
	v_add_f32_e32 v147, 1.0, v147
	v_add_f32_e32 v148, 1.0, v148
	v_add_f32_e32 v149, 1.0, v149
	v_add_f32_e32 v150, 1.0, v150
	v_add_f32_e32 v151, 1.0, v151
	v_rcp_f32_e32 v136, v136
	v_rcp_f32_e32 v137, v137
	v_rcp_f32_e32 v138, v138
	v_rcp_f32_e32 v139, v139
	v_rcp_f32_e32 v140, v140
	v_rcp_f32_e32 v141, v141
	v_rcp_f32_e32 v142, v142
	v_rcp_f32_e32 v143, v143
	v_rcp_f32_e32 v144, v144
	v_rcp_f32_e32 v145, v145
	v_rcp_f32_e32 v146, v146
	v_rcp_f32_e32 v147, v147
	v_rcp_f32_e32 v148, v148
	v_rcp_f32_e32 v149, v149
	v_rcp_f32_e32 v150, v150
; DI bf16_t f2bf(float a) { return (bf16_t)(pk_bf16(a, 0.f) & 0xffffu); }
; DI float silu_f(float x) { return x * __builtin_amdgcn_rcpf(1.f + __expf(-x)); }
; template <int EPI>
; DI void gemm_phase(const bf16_t* __restrict__ A, const bf16_t* __restrict__ Bt, const int K, const int N, const Params& p, const int layer_j, char* lds) {
;     ...
;             } else {
;                 const int dc0 = (region == 0) ? col0 : (col0 - 3072 + 2048);
;                 const float sc = (region == 0) ? 0.08838834764831845f : 1.0f;
;                 bf16_t* dst = PROJ + (size_t)row0 * ATT_IN + dc0 + fr;
; #pragma unroll
;                 for (int ai = 0; ai < 2; ++ai)
; #pragma unroll
;                     for (int m = 0; m < 4; ++m)
; #pragma unroll
;                         for (int j = 0; j < 4; ++j)
; #pragma unroll
;                             for (int bj = 0; bj < 2; ++bj)
; #pragma unroll
;                                 for (int n = 0; n < 2; ++n) dst[(size_t)(ai * 128 + m * 16 + j) * ATT_IN + bj * 32 + n * 16] = f2bf(silu_f(acc[ai][bj][m][n][j]) * sc);
;             }
	v_rcp_f32_e32 v151, v151
	v_mul_f32_e32 v94, v94, v136
	v_mul_f32_e32 v95, v95, v137
	v_mul_f32_e32 v96, v96, v138
	v_mul_f32_e32 v97, v97, v139
	v_mul_f32_e32 v90, v90, v140
	v_mul_f32_e32 v91, v91, v141
	v_mul_f32_e32 v92, v92, v142
	v_mul_f32_e32 v93, v93, v143
	v_mul_f32_e32 v86, v86, v144
	v_mul_f32_e32 v87, v87, v145
	v_mul_f32_e32 v88, v88, v146
	v_mul_f32_e32 v89, v89, v147
	v_mul_f32_e32 v82, v82, v148
	v_mul_f32_e32 v83, v83, v149
	v_mul_f32_e32 v84, v84, v150
	v_mul_f32_e32 v85, v85, v151
	v_mul_f32_e32 v94, s35, v94
	v_mul_f32_e32 v95, s35, v95
	v_mul_f32_e32 v96, s35, v96
	v_mul_f32_e32 v97, s35, v97
	v_mul_f32_e32 v90, s35, v90
	v_mul_f32_e32 v91, s35, v91
	v_mul_f32_e32 v92, s35, v92
	v_mul_f32_e32 v93, s35, v93
	v_mul_f32_e32 v86, s35, v86
	v_mul_f32_e32 v87, s35, v87
	v_mul_f32_e32 v88, s35, v88
	v_mul_f32_e32 v89, s35, v89
	v_mul_f32_e32 v82, s35, v82
	v_mul_f32_e32 v83, s35, v83
	v_mul_f32_e32 v84, s35, v84
	v_mul_f32_e32 v85, s35, v85
	v_cvt_pk_bf16_f32 v160, v94, v95
	v_cvt_pk_bf16_f32 v161, v96, v97
	v_cvt_pk_bf16_f32 v162, v90, v91
	v_cvt_pk_bf16_f32 v163, v92, v93
	v_cvt_pk_bf16_f32 v164, v86, v87
	v_cvt_pk_bf16_f32 v165, v88, v89
	v_cvt_pk_bf16_f32 v166, v82, v83
	v_cvt_pk_bf16_f32 v167, v84, v85
	ds_write_b64 v213, v[160:161]
	ds_write_b64 v213, v[162:163] offset:32
	ds_write_b64 v213, v[164:165] offset:64
	ds_write_b64 v213, v[166:167] offset:96
	ds_read2_b64 v[168:171], v214 offset1:1
	ds_read2_b64 v[172:175], v214 offset0:136 offset1:137
	v_add_u32_e32 v217, 0x30000, v215
	v_add_u32_e32 v218, 0x30000, v216
	s_waitcnt lgkmcnt(0)
	global_store_dwordx4 v217, v[168:171], s[16:17]
	global_store_dwordx4 v218, v[172:175], s[16:17]
	v_mul_f32_e32 v136, 0xbfb8aa3b, v78
	v_mul_f32_e32 v137, 0xbfb8aa3b, v79
	v_mul_f32_e32 v138, 0xbfb8aa3b, v80
	v_mul_f32_e32 v139, 0xbfb8aa3b, v81
	v_mul_f32_e32 v140, 0xbfb8aa3b, v74
	v_mul_f32_e32 v141, 0xbfb8aa3b, v75
	v_mul_f32_e32 v142, 0xbfb8aa3b, v76
	v_mul_f32_e32 v143, 0xbfb8aa3b, v77
	v_mul_f32_e32 v144, 0xbfb8aa3b, v38
	v_mul_f32_e32 v145, 0xbfb8aa3b, v39
	v_mul_f32_e32 v146, 0xbfb8aa3b, v40
	v_mul_f32_e32 v147, 0xbfb8aa3b, v41
	v_mul_f32_e32 v148, 0xbfb8aa3b, v16
	v_mul_f32_e32 v149, 0xbfb8aa3b, v17
	v_mul_f32_e32 v150, 0xbfb8aa3b, v18
	v_mul_f32_e32 v151, 0xbfb8aa3b, v19
	v_exp_f32_e32 v136, v136
	v_exp_f32_e32 v137, v137
	v_exp_f32_e32 v138, v138
	v_exp_f32_e32 v139, v139
	v_exp_f32_e32 v140, v140
	v_exp_f32_e32 v141, v141
	v_exp_f32_e32 v142, v142
	v_exp_f32_e32 v143, v143
	v_exp_f32_e32 v144, v144
	v_exp_f32_e32 v145, v145
	v_exp_f32_e32 v146, v146
	v_exp_f32_e32 v147, v147
	v_exp_f32_e32 v148, v148
	v_exp_f32_e32 v149, v149
	v_exp_f32_e32 v150, v150
	v_exp_f32_e32 v151, v151
	v_add_f32_e32 v136, 1.0, v136
	v_add_f32_e32 v137, 1.0, v137
	v_add_f32_e32 v138, 1.0, v138
	v_add_f32_e32 v139, 1.0, v139
	v_add_f32_e32 v140, 1.0, v140
	v_add_f32_e32 v141, 1.0, v141
	v_add_f32_e32 v142, 1.0, v142
	v_add_f32_e32 v143, 1.0, v143
	v_add_f32_e32 v144, 1.0, v144
	v_add_f32_e32 v145, 1.0, v145
	v_add_f32_e32 v146, 1.0, v146
	v_add_f32_e32 v147, 1.0, v147
	v_add_f32_e32 v148, 1.0, v148
	v_add_f32_e32 v149, 1.0, v149
	v_add_f32_e32 v150, 1.0, v150
	v_add_f32_e32 v151, 1.0, v151
	v_rcp_f32_e32 v136, v136
	v_rcp_f32_e32 v137, v137
	v_rcp_f32_e32 v138, v138
	v_rcp_f32_e32 v139, v139
	v_rcp_f32_e32 v140, v140
	v_rcp_f32_e32 v141, v141
	v_rcp_f32_e32 v142, v142
	v_rcp_f32_e32 v143, v143
	v_rcp_f32_e32 v144, v144
	v_rcp_f32_e32 v145, v145
	v_rcp_f32_e32 v146, v146
	v_rcp_f32_e32 v147, v147
	v_rcp_f32_e32 v148, v148
	v_rcp_f32_e32 v149, v149
	v_rcp_f32_e32 v150, v150
	v_rcp_f32_e32 v151, v151
	v_mul_f32_e32 v78, v78, v136
	v_mul_f32_e32 v79, v79, v137
	v_mul_f32_e32 v80, v80, v138
	v_mul_f32_e32 v81, v81, v139
	v_mul_f32_e32 v74, v74, v140
	v_mul_f32_e32 v75, v75, v141
	v_mul_f32_e32 v76, v76, v142
	v_mul_f32_e32 v77, v77, v143
	v_mul_f32_e32 v38, v38, v144
	v_mul_f32_e32 v39, v39, v145
	v_mul_f32_e32 v40, v40, v146
	v_mul_f32_e32 v41, v41, v147
	v_mul_f32_e32 v16, v16, v148
	v_mul_f32_e32 v17, v17, v149
	v_mul_f32_e32 v18, v18, v150
	v_mul_f32_e32 v19, v19, v151
	v_mul_f32_e32 v78, s35, v78
	v_mul_f32_e32 v79, s35, v79
	v_mul_f32_e32 v80, s35, v80
	v_mul_f32_e32 v81, s35, v81
	v_mul_f32_e32 v74, s35, v74
	v_mul_f32_e32 v75, s35, v75
	v_mul_f32_e32 v76, s35, v76
	v_mul_f32_e32 v77, s35, v77
	v_mul_f32_e32 v38, s35, v38
	v_mul_f32_e32 v39, s35, v39
	v_mul_f32_e32 v40, s35, v40
	v_mul_f32_e32 v41, s35, v41
	v_mul_f32_e32 v16, s35, v16
	v_mul_f32_e32 v17, s35, v17
	v_mul_f32_e32 v18, s35, v18
	v_mul_f32_e32 v19, s35, v19
	v_cvt_pk_bf16_f32 v160, v78, v79
	v_cvt_pk_bf16_f32 v161, v80, v81
	v_cvt_pk_bf16_f32 v162, v74, v75
	v_cvt_pk_bf16_f32 v163, v76, v77
	v_cvt_pk_bf16_f32 v164, v38, v39
	v_cvt_pk_bf16_f32 v165, v40, v41
	v_cvt_pk_bf16_f32 v166, v16, v17
	v_cvt_pk_bf16_f32 v167, v18, v19
	ds_write_b64 v213, v[160:161]
	ds_write_b64 v213, v[162:163] offset:32
	ds_write_b64 v213, v[164:165] offset:64
	ds_write_b64 v213, v[166:167] offset:96
	ds_read2_b64 v[168:171], v214 offset1:1
	ds_read2_b64 v[172:175], v214 offset0:136 offset1:137
	v_add_u32_e32 v217, 0x48000, v215
	v_add_u32_e32 v218, 0x48000, v216
	s_waitcnt lgkmcnt(0)
; DI bf16_t f2bf(float a) { return (bf16_t)(pk_bf16(a, 0.f) & 0xffffu); }
; DI float silu_f(float x) { return x * __builtin_amdgcn_rcpf(1.f + __expf(-x)); }
; template <int EPI>
; DI void gemm_phase(const bf16_t* __restrict__ A, const bf16_t* __restrict__ Bt, const int K, const int N, const Params& p, const int layer_j, char* lds) {
;     ...
;             } else {
;                 const int dc0 = (region == 0) ? col0 : (col0 - 3072 + 2048);
;                 const float sc = (region == 0) ? 0.08838834764831845f : 1.0f;
;                 bf16_t* dst = PROJ + (size_t)row0 * ATT_IN + dc0 + fr;
; #pragma unroll
;                 for (int ai = 0; ai < 2; ++ai)
; #pragma unroll
;                     for (int m = 0; m < 4; ++m)
; #pragma unroll
;                         for (int j = 0; j < 4; ++j)
; #pragma unroll
;                             for (int bj = 0; bj < 2; ++bj)
; #pragma unroll
;                                 for (int n = 0; n < 2; ++n) dst[(size_t)(ai * 128 + m * 16 + j) * ATT_IN + bj * 32 + n * 16] = f2bf(silu_f(acc[ai][bj][m][n][j]) * sc);
;             }
	global_store_dwordx4 v217, v[168:171], s[16:17]
	global_store_dwordx4 v218, v[172:175], s[16:17]
	v_mul_f32_e32 v136, 0xbfb8aa3b, v70
	v_mul_f32_e32 v137, 0xbfb8aa3b, v71
	v_mul_f32_e32 v138, 0xbfb8aa3b, v72
	v_mul_f32_e32 v139, 0xbfb8aa3b, v73
	v_mul_f32_e32 v140, 0xbfb8aa3b, v54
	v_mul_f32_e32 v141, 0xbfb8aa3b, v55
	v_mul_f32_e32 v142, 0xbfb8aa3b, v56
	v_mul_f32_e32 v143, 0xbfb8aa3b, v57
	v_mul_f32_e32 v144, 0xbfb8aa3b, v34
	v_mul_f32_e32 v145, 0xbfb8aa3b, v35
	v_mul_f32_e32 v146, 0xbfb8aa3b, v36
	v_mul_f32_e32 v147, 0xbfb8aa3b, v37
	v_mul_f32_e32 v148, 0xbfb8aa3b, v12
	v_mul_f32_e32 v149, 0xbfb8aa3b, v13
	v_mul_f32_e32 v150, 0xbfb8aa3b, v14
	v_mul_f32_e32 v151, 0xbfb8aa3b, v15
	v_exp_f32_e32 v136, v136
	v_exp_f32_e32 v137, v137
	v_exp_f32_e32 v138, v138
	v_exp_f32_e32 v139, v139
	v_exp_f32_e32 v140, v140
	v_exp_f32_e32 v141, v141
	v_exp_f32_e32 v142, v142
	v_exp_f32_e32 v143, v143
	v_exp_f32_e32 v144, v144
	v_exp_f32_e32 v145, v145
	v_exp_f32_e32 v146, v146
	v_exp_f32_e32 v147, v147
	v_exp_f32_e32 v148, v148
	v_exp_f32_e32 v149, v149
	v_exp_f32_e32 v150, v150
	v_exp_f32_e32 v151, v151
	v_add_f32_e32 v136, 1.0, v136
	v_add_f32_e32 v137, 1.0, v137
	v_add_f32_e32 v138, 1.0, v138
	v_add_f32_e32 v139, 1.0, v139
	v_add_f32_e32 v140, 1.0, v140
	v_add_f32_e32 v141, 1.0, v141
	v_add_f32_e32 v142, 1.0, v142
	v_add_f32_e32 v143, 1.0, v143
	v_add_f32_e32 v144, 1.0, v144
	v_add_f32_e32 v145, 1.0, v145
	v_add_f32_e32 v146, 1.0, v146
	v_add_f32_e32 v147, 1.0, v147
	v_add_f32_e32 v148, 1.0, v148
	v_add_f32_e32 v149, 1.0, v149
	v_add_f32_e32 v150, 1.0, v150
	v_add_f32_e32 v151, 1.0, v151
	v_rcp_f32_e32 v136, v136
	v_rcp_f32_e32 v137, v137
	v_rcp_f32_e32 v138, v138
	v_rcp_f32_e32 v139, v139
	v_rcp_f32_e32 v140, v140
	v_rcp_f32_e32 v141, v141
	v_rcp_f32_e32 v142, v142
	v_rcp_f32_e32 v143, v143
	v_rcp_f32_e32 v144, v144
	v_rcp_f32_e32 v145, v145
	v_rcp_f32_e32 v146, v146
	v_rcp_f32_e32 v147, v147
	v_rcp_f32_e32 v148, v148
	v_rcp_f32_e32 v149, v149
	v_rcp_f32_e32 v150, v150
	v_rcp_f32_e32 v151, v151
	v_mul_f32_e32 v70, v70, v136
	v_mul_f32_e32 v71, v71, v137
	v_mul_f32_e32 v72, v72, v138
	v_mul_f32_e32 v73, v73, v139
	v_mul_f32_e32 v54, v54, v140
	v_mul_f32_e32 v55, v55, v141
	v_mul_f32_e32 v56, v56, v142
	v_mul_f32_e32 v57, v57, v143
	v_mul_f32_e32 v34, v34, v144
	v_mul_f32_e32 v35, v35, v145
	v_mul_f32_e32 v36, v36, v146
	v_mul_f32_e32 v37, v37, v147
	v_mul_f32_e32 v12, v12, v148
	v_mul_f32_e32 v13, v13, v149
	v_mul_f32_e32 v14, v14, v150
	v_mul_f32_e32 v15, v15, v151
	v_mul_f32_e32 v70, s35, v70
	v_mul_f32_e32 v71, s35, v71
	v_mul_f32_e32 v72, s35, v72
	v_mul_f32_e32 v73, s35, v73
	v_mul_f32_e32 v54, s35, v54
	v_mul_f32_e32 v55, s35, v55
	v_mul_f32_e32 v56, s35, v56
	v_mul_f32_e32 v57, s35, v57
	v_mul_f32_e32 v34, s35, v34
	v_mul_f32_e32 v35, s35, v35
	v_mul_f32_e32 v36, s35, v36
	v_mul_f32_e32 v37, s35, v37
	v_mul_f32_e32 v12, s35, v12
	v_mul_f32_e32 v13, s35, v13
	v_mul_f32_e32 v14, s35, v14
	v_mul_f32_e32 v15, s35, v15
	v_cvt_pk_bf16_f32 v160, v70, v71
	v_cvt_pk_bf16_f32 v161, v72, v73
	v_cvt_pk_bf16_f32 v162, v54, v55
	v_cvt_pk_bf16_f32 v163, v56, v57
	v_cvt_pk_bf16_f32 v164, v34, v35
	v_cvt_pk_bf16_f32 v165, v36, v37
	v_cvt_pk_bf16_f32 v166, v12, v13
	v_cvt_pk_bf16_f32 v167, v14, v15
	ds_write_b64 v213, v[160:161]
	ds_write_b64 v213, v[162:163] offset:32
	ds_write_b64 v213, v[164:165] offset:64
	ds_write_b64 v213, v[166:167] offset:96
	ds_read2_b64 v[168:171], v214 offset1:1
	ds_read2_b64 v[172:175], v214 offset0:136 offset1:137
	v_add_u32_e32 v217, 0xc0000, v215
	v_add_u32_e32 v218, 0xc0000, v216
	s_waitcnt lgkmcnt(0)
	global_store_dwordx4 v217, v[168:171], s[16:17]
	global_store_dwordx4 v218, v[172:175], s[16:17]
	v_mul_f32_e32 v136, 0xbfb8aa3b, v66
	v_mul_f32_e32 v137, 0xbfb8aa3b, v67
	v_mul_f32_e32 v138, 0xbfb8aa3b, v68
	v_mul_f32_e32 v139, 0xbfb8aa3b, v69
	v_mul_f32_e32 v140, 0xbfb8aa3b, v50
	v_mul_f32_e32 v141, 0xbfb8aa3b, v51
	v_mul_f32_e32 v142, 0xbfb8aa3b, v52
	v_mul_f32_e32 v143, 0xbfb8aa3b, v53
	v_mul_f32_e32 v144, 0xbfb8aa3b, v28
	v_mul_f32_e32 v145, 0xbfb8aa3b, v29
	v_mul_f32_e32 v146, 0xbfb8aa3b, v30
	v_mul_f32_e32 v147, 0xbfb8aa3b, v31
	v_mul_f32_e32 v148, 0xbfb8aa3b, v8
	v_mul_f32_e32 v149, 0xbfb8aa3b, v9
	v_mul_f32_e32 v150, 0xbfb8aa3b, v10
	v_mul_f32_e32 v151, 0xbfb8aa3b, v11
	v_exp_f32_e32 v136, v136
	v_exp_f32_e32 v137, v137
	v_exp_f32_e32 v138, v138
	v_exp_f32_e32 v139, v139
	v_exp_f32_e32 v140, v140
	v_exp_f32_e32 v141, v141
	v_exp_f32_e32 v142, v142
	v_exp_f32_e32 v143, v143
	v_exp_f32_e32 v144, v144
	v_exp_f32_e32 v145, v145
	v_exp_f32_e32 v146, v146
	v_exp_f32_e32 v147, v147
	v_exp_f32_e32 v148, v148
	v_exp_f32_e32 v149, v149
	v_exp_f32_e32 v150, v150
	v_exp_f32_e32 v151, v151
	v_add_f32_e32 v136, 1.0, v136
	v_add_f32_e32 v137, 1.0, v137
	v_add_f32_e32 v138, 1.0, v138
	v_add_f32_e32 v139, 1.0, v139
	v_add_f32_e32 v140, 1.0, v140
	v_add_f32_e32 v141, 1.0, v141
	v_add_f32_e32 v142, 1.0, v142
	v_add_f32_e32 v143, 1.0, v143
	v_add_f32_e32 v144, 1.0, v144
	v_add_f32_e32 v145, 1.0, v145
	v_add_f32_e32 v146, 1.0, v146
	v_add_f32_e32 v147, 1.0, v147
	v_add_f32_e32 v148, 1.0, v148
	v_add_f32_e32 v149, 1.0, v149
	v_add_f32_e32 v150, 1.0, v150
	v_add_f32_e32 v151, 1.0, v151
	v_rcp_f32_e32 v136, v136
	v_rcp_f32_e32 v137, v137
	v_rcp_f32_e32 v138, v138
	v_rcp_f32_e32 v139, v139
	v_rcp_f32_e32 v140, v140
	v_rcp_f32_e32 v141, v141
	v_rcp_f32_e32 v142, v142
	v_rcp_f32_e32 v143, v143
	v_rcp_f32_e32 v144, v144
	v_rcp_f32_e32 v145, v145
	v_rcp_f32_e32 v146, v146
	v_rcp_f32_e32 v147, v147
	v_rcp_f32_e32 v148, v148
	v_rcp_f32_e32 v149, v149
	v_rcp_f32_e32 v150, v150
	v_rcp_f32_e32 v151, v151
	v_mul_f32_e32 v66, v66, v136
	v_mul_f32_e32 v67, v67, v137
; DI bf16_t f2bf(float a) { return (bf16_t)(pk_bf16(a, 0.f) & 0xffffu); }
; DI float silu_f(float x) { return x * __builtin_amdgcn_rcpf(1.f + __expf(-x)); }
; template <int EPI>
; DI void gemm_phase(const bf16_t* __restrict__ A, const bf16_t* __restrict__ Bt, const int K, const int N, const Params& p, const int layer_j, char* lds) {
;     ...
;             } else {
;                 const int dc0 = (region == 0) ? col0 : (col0 - 3072 + 2048);
;                 const float sc = (region == 0) ? 0.08838834764831845f : 1.0f;
;                 bf16_t* dst = PROJ + (size_t)row0 * ATT_IN + dc0 + fr;
; #pragma unroll
;                 for (int ai = 0; ai < 2; ++ai)
; #pragma unroll
;                     for (int m = 0; m < 4; ++m)
; #pragma unroll
;                         for (int j = 0; j < 4; ++j)
; #pragma unroll
;                             for (int bj = 0; bj < 2; ++bj)
; #pragma unroll
;                                 for (int n = 0; n < 2; ++n) dst[(size_t)(ai * 128 + m * 16 + j) * ATT_IN + bj * 32 + n * 16] = f2bf(silu_f(acc[ai][bj][m][n][j]) * sc);
;             }
	v_mul_f32_e32 v68, v68, v138
	v_mul_f32_e32 v69, v69, v139
	v_mul_f32_e32 v50, v50, v140
	v_mul_f32_e32 v51, v51, v141
	v_mul_f32_e32 v52, v52, v142
	v_mul_f32_e32 v53, v53, v143
	v_mul_f32_e32 v28, v28, v144
	v_mul_f32_e32 v29, v29, v145
	v_mul_f32_e32 v30, v30, v146
	v_mul_f32_e32 v31, v31, v147
	v_mul_f32_e32 v8, v8, v148
	v_mul_f32_e32 v9, v9, v149
	v_mul_f32_e32 v10, v10, v150
	v_mul_f32_e32 v11, v11, v151
	v_mul_f32_e32 v66, s35, v66
	v_mul_f32_e32 v67, s35, v67
	v_mul_f32_e32 v68, s35, v68
	v_mul_f32_e32 v69, s35, v69
	v_mul_f32_e32 v50, s35, v50
	v_mul_f32_e32 v51, s35, v51
	v_mul_f32_e32 v52, s35, v52
	v_mul_f32_e32 v53, s35, v53
	v_mul_f32_e32 v28, s35, v28
	v_mul_f32_e32 v29, s35, v29
	v_mul_f32_e32 v30, s35, v30
	v_mul_f32_e32 v31, s35, v31
	v_mul_f32_e32 v8, s35, v8
	v_mul_f32_e32 v9, s35, v9
	v_mul_f32_e32 v10, s35, v10
	v_mul_f32_e32 v11, s35, v11
	v_cvt_pk_bf16_f32 v160, v66, v67
	v_cvt_pk_bf16_f32 v161, v68, v69
	v_cvt_pk_bf16_f32 v162, v50, v51
	v_cvt_pk_bf16_f32 v163, v52, v53
	v_cvt_pk_bf16_f32 v164, v28, v29
	v_cvt_pk_bf16_f32 v165, v30, v31
	v_cvt_pk_bf16_f32 v166, v8, v9
	v_cvt_pk_bf16_f32 v167, v10, v11
	ds_write_b64 v213, v[160:161]
	ds_write_b64 v213, v[162:163] offset:32
	ds_write_b64 v213, v[164:165] offset:64
	ds_write_b64 v213, v[166:167] offset:96
	ds_read2_b64 v[168:171], v214 offset1:1
	ds_read2_b64 v[172:175], v214 offset0:136 offset1:137
	v_add_u32_e32 v217, 0xd8000, v215
	v_add_u32_e32 v218, 0xd8000, v216
	s_waitcnt lgkmcnt(0)
	global_store_dwordx4 v217, v[168:171], s[16:17]
	global_store_dwordx4 v218, v[172:175], s[16:17]
	v_mul_f32_e32 v136, 0xbfb8aa3b, v62
	v_mul_f32_e32 v137, 0xbfb8aa3b, v63
	v_mul_f32_e32 v138, 0xbfb8aa3b, v64
	v_mul_f32_e32 v139, 0xbfb8aa3b, v65
	v_mul_f32_e32 v140, 0xbfb8aa3b, v46
	v_mul_f32_e32 v141, 0xbfb8aa3b, v47
	v_mul_f32_e32 v142, 0xbfb8aa3b, v48
	v_mul_f32_e32 v143, 0xbfb8aa3b, v49
	v_mul_f32_e32 v144, 0xbfb8aa3b, v24
	v_mul_f32_e32 v145, 0xbfb8aa3b, v25
	v_mul_f32_e32 v146, 0xbfb8aa3b, v26
	v_mul_f32_e32 v147, 0xbfb8aa3b, v27
	v_mul_f32_e32 v148, 0xbfb8aa3b, v4
	v_mul_f32_e32 v149, 0xbfb8aa3b, v5
	v_mul_f32_e32 v150, 0xbfb8aa3b, v6
	v_mul_f32_e32 v151, 0xbfb8aa3b, v7
	v_exp_f32_e32 v136, v136
	v_exp_f32_e32 v137, v137
	v_exp_f32_e32 v138, v138
	v_exp_f32_e32 v139, v139
	v_exp_f32_e32 v140, v140
	v_exp_f32_e32 v141, v141
	v_exp_f32_e32 v142, v142
	v_exp_f32_e32 v143, v143
	v_exp_f32_e32 v144, v144
	v_exp_f32_e32 v145, v145
	v_exp_f32_e32 v146, v146
	v_exp_f32_e32 v147, v147
	v_exp_f32_e32 v148, v148
	v_exp_f32_e32 v149, v149
	v_exp_f32_e32 v150, v150
	v_exp_f32_e32 v151, v151
	v_add_f32_e32 v136, 1.0, v136
	v_add_f32_e32 v137, 1.0, v137
	v_add_f32_e32 v138, 1.0, v138
	v_add_f32_e32 v139, 1.0, v139
	v_add_f32_e32 v140, 1.0, v140
	v_add_f32_e32 v141, 1.0, v141
	v_add_f32_e32 v142, 1.0, v142
	v_add_f32_e32 v143, 1.0, v143
	v_add_f32_e32 v144, 1.0, v144
	v_add_f32_e32 v145, 1.0, v145
	v_add_f32_e32 v146, 1.0, v146
	v_add_f32_e32 v147, 1.0, v147
	v_add_f32_e32 v148, 1.0, v148
	v_add_f32_e32 v149, 1.0, v149
	v_add_f32_e32 v150, 1.0, v150
	v_add_f32_e32 v151, 1.0, v151
	v_rcp_f32_e32 v136, v136
	v_rcp_f32_e32 v137, v137
	v_rcp_f32_e32 v138, v138
	v_rcp_f32_e32 v139, v139
	v_rcp_f32_e32 v140, v140
	v_rcp_f32_e32 v141, v141
	v_rcp_f32_e32 v142, v142
	v_rcp_f32_e32 v143, v143
	v_rcp_f32_e32 v144, v144
	v_rcp_f32_e32 v145, v145
	v_rcp_f32_e32 v146, v146
	v_rcp_f32_e32 v147, v147
	v_rcp_f32_e32 v148, v148
	v_rcp_f32_e32 v149, v149
	v_rcp_f32_e32 v150, v150
	v_rcp_f32_e32 v151, v151
	v_mul_f32_e32 v62, v62, v136
	v_mul_f32_e32 v63, v63, v137
	v_mul_f32_e32 v64, v64, v138
	v_mul_f32_e32 v65, v65, v139
	v_mul_f32_e32 v46, v46, v140
	v_mul_f32_e32 v47, v47, v141
	v_mul_f32_e32 v48, v48, v142
	v_mul_f32_e32 v49, v49, v143
	v_mul_f32_e32 v24, v24, v144
	v_mul_f32_e32 v25, v25, v145
	v_mul_f32_e32 v26, v26, v146
	v_mul_f32_e32 v27, v27, v147
	v_mul_f32_e32 v4, v4, v148
	v_mul_f32_e32 v5, v5, v149
	v_mul_f32_e32 v6, v6, v150
	v_mul_f32_e32 v7, v7, v151
	v_mul_f32_e32 v62, s35, v62
	v_mul_f32_e32 v63, s35, v63
	v_mul_f32_e32 v64, s35, v64
	v_mul_f32_e32 v65, s35, v65
	v_mul_f32_e32 v46, s35, v46
	v_mul_f32_e32 v47, s35, v47
	v_mul_f32_e32 v48, s35, v48
	v_mul_f32_e32 v49, s35, v49
	v_mul_f32_e32 v24, s35, v24
	v_mul_f32_e32 v25, s35, v25
	v_mul_f32_e32 v26, s35, v26
	v_mul_f32_e32 v27, s35, v27
	v_mul_f32_e32 v4, s35, v4
	v_mul_f32_e32 v5, s35, v5
	v_mul_f32_e32 v6, s35, v6
	v_mul_f32_e32 v7, s35, v7
	v_cvt_pk_bf16_f32 v160, v62, v63
	v_cvt_pk_bf16_f32 v161, v64, v65
	v_cvt_pk_bf16_f32 v162, v46, v47
	v_cvt_pk_bf16_f32 v163, v48, v49
	v_cvt_pk_bf16_f32 v164, v24, v25
	v_cvt_pk_bf16_f32 v165, v26, v27
	v_cvt_pk_bf16_f32 v166, v4, v5
	v_cvt_pk_bf16_f32 v167, v6, v7
	ds_write_b64 v213, v[160:161]
	ds_write_b64 v213, v[162:163] offset:32
	ds_write_b64 v213, v[164:165] offset:64
	ds_write_b64 v213, v[166:167] offset:96
	ds_read2_b64 v[168:171], v214 offset1:1
	ds_read2_b64 v[172:175], v214 offset0:136 offset1:137
	v_add_u32_e32 v217, 0xf0000, v215
	v_add_u32_e32 v218, 0xf0000, v216
	s_waitcnt lgkmcnt(0)
; DI bf16_t f2bf(float a) { return (bf16_t)(pk_bf16(a, 0.f) & 0xffffu); }
; DI float silu_f(float x) { return x * __builtin_amdgcn_rcpf(1.f + __expf(-x)); }
; template <int EPI>
; DI void gemm_phase(const bf16_t* __restrict__ A, const bf16_t* __restrict__ Bt, const int K, const int N, const Params& p, const int layer_j, char* lds) {
;     ...
;             } else {
;                 const int dc0 = (region == 0) ? col0 : (col0 - 3072 + 2048);
;                 const float sc = (region == 0) ? 0.08838834764831845f : 1.0f;
;                 bf16_t* dst = PROJ + (size_t)row0 * ATT_IN + dc0 + fr;
; #pragma unroll
;                 for (int ai = 0; ai < 2; ++ai)
; #pragma unroll
;                     for (int m = 0; m < 4; ++m)
; #pragma unroll
;                         for (int j = 0; j < 4; ++j)
; #pragma unroll
;                             for (int bj = 0; bj < 2; ++bj)
; #pragma unroll
;                                 for (int n = 0; n < 2; ++n) dst[(size_t)(ai * 128 + m * 16 + j) * ATT_IN + bj * 32 + n * 16] = f2bf(silu_f(acc[ai][bj][m][n][j]) * sc);
;             }
;         }
;         if (!has_next) break;
	global_store_dwordx4 v217, v[168:171], s[16:17]
	global_store_dwordx4 v218, v[172:175], s[16:17]
	v_mul_f32_e32 v136, 0xbfb8aa3b, v58
	v_mul_f32_e32 v137, 0xbfb8aa3b, v59
	v_mul_f32_e32 v138, 0xbfb8aa3b, v60
	v_mul_f32_e32 v139, 0xbfb8aa3b, v61
	v_mul_f32_e32 v140, 0xbfb8aa3b, v42
	v_mul_f32_e32 v141, 0xbfb8aa3b, v43
	v_mul_f32_e32 v142, 0xbfb8aa3b, v44
	v_mul_f32_e32 v143, 0xbfb8aa3b, v45
	v_mul_f32_e32 v144, 0xbfb8aa3b, v20
	v_mul_f32_e32 v145, 0xbfb8aa3b, v21
	v_mul_f32_e32 v146, 0xbfb8aa3b, v22
	v_mul_f32_e32 v147, 0xbfb8aa3b, v23
	v_mul_f32_e32 v148, 0xbfb8aa3b, v0
	v_mul_f32_e32 v149, 0xbfb8aa3b, v1
	v_mul_f32_e32 v150, 0xbfb8aa3b, v2
	v_mul_f32_e32 v151, 0xbfb8aa3b, v3
	v_exp_f32_e32 v136, v136
	v_exp_f32_e32 v137, v137
	v_exp_f32_e32 v138, v138
	v_exp_f32_e32 v139, v139
	v_exp_f32_e32 v140, v140
	v_exp_f32_e32 v141, v141
	v_exp_f32_e32 v142, v142
	v_exp_f32_e32 v143, v143
	v_exp_f32_e32 v144, v144
	v_exp_f32_e32 v145, v145
	v_exp_f32_e32 v146, v146
	v_exp_f32_e32 v147, v147
	v_exp_f32_e32 v148, v148
	v_exp_f32_e32 v149, v149
	v_exp_f32_e32 v150, v150
	v_exp_f32_e32 v151, v151
	v_add_f32_e32 v136, 1.0, v136
	v_add_f32_e32 v137, 1.0, v137
	v_add_f32_e32 v138, 1.0, v138
	v_add_f32_e32 v139, 1.0, v139
	v_add_f32_e32 v140, 1.0, v140
	v_add_f32_e32 v141, 1.0, v141
	v_add_f32_e32 v142, 1.0, v142
	v_add_f32_e32 v143, 1.0, v143
	v_add_f32_e32 v144, 1.0, v144
	v_add_f32_e32 v145, 1.0, v145
	v_add_f32_e32 v146, 1.0, v146
	v_add_f32_e32 v147, 1.0, v147
	v_add_f32_e32 v148, 1.0, v148
	v_add_f32_e32 v149, 1.0, v149
	v_add_f32_e32 v150, 1.0, v150
	v_add_f32_e32 v151, 1.0, v151
	v_rcp_f32_e32 v136, v136
	v_rcp_f32_e32 v137, v137
	v_rcp_f32_e32 v138, v138
	v_rcp_f32_e32 v139, v139
	v_rcp_f32_e32 v140, v140
	v_rcp_f32_e32 v141, v141
	v_rcp_f32_e32 v142, v142
	v_rcp_f32_e32 v143, v143
	v_rcp_f32_e32 v144, v144
	v_rcp_f32_e32 v145, v145
	v_rcp_f32_e32 v146, v146
	v_rcp_f32_e32 v147, v147
	v_rcp_f32_e32 v148, v148
	v_rcp_f32_e32 v149, v149
	v_rcp_f32_e32 v150, v150
	v_rcp_f32_e32 v151, v151
	v_mul_f32_e32 v58, v58, v136
	v_mul_f32_e32 v59, v59, v137
	v_mul_f32_e32 v60, v60, v138
	v_mul_f32_e32 v61, v61, v139
	v_mul_f32_e32 v42, v42, v140
	v_mul_f32_e32 v43, v43, v141
	v_mul_f32_e32 v44, v44, v142
	v_mul_f32_e32 v45, v45, v143
	v_mul_f32_e32 v20, v20, v144
	v_mul_f32_e32 v21, v21, v145
	v_mul_f32_e32 v22, v22, v146
	v_mul_f32_e32 v23, v23, v147
	v_mul_f32_e32 v0, v0, v148
	v_mul_f32_e32 v1, v1, v149
	v_mul_f32_e32 v2, v2, v150
	v_mul_f32_e32 v3, v3, v151
	v_mul_f32_e32 v58, s35, v58
	v_mul_f32_e32 v59, s35, v59
	v_mul_f32_e32 v60, s35, v60
	v_mul_f32_e32 v61, s35, v61
	v_mul_f32_e32 v42, s35, v42
	v_mul_f32_e32 v43, s35, v43
	v_mul_f32_e32 v44, s35, v44
	v_mul_f32_e32 v45, s35, v45
	v_mul_f32_e32 v20, s35, v20
	v_mul_f32_e32 v21, s35, v21
	v_mul_f32_e32 v22, s35, v22
	v_mul_f32_e32 v23, s35, v23
	v_mul_f32_e32 v0, s35, v0
	v_mul_f32_e32 v1, s35, v1
	v_mul_f32_e32 v2, s35, v2
	v_mul_f32_e32 v3, s35, v3
	v_cvt_pk_bf16_f32 v160, v58, v59
	v_cvt_pk_bf16_f32 v161, v60, v61
	v_cvt_pk_bf16_f32 v162, v42, v43
	v_cvt_pk_bf16_f32 v163, v44, v45
	v_cvt_pk_bf16_f32 v164, v20, v21
	v_cvt_pk_bf16_f32 v165, v22, v23
	v_cvt_pk_bf16_f32 v166, v0, v1
	v_cvt_pk_bf16_f32 v167, v2, v3
	ds_write_b64 v213, v[160:161]
	ds_write_b64 v213, v[162:163] offset:32
	ds_write_b64 v213, v[164:165] offset:64
	ds_write_b64 v213, v[166:167] offset:96
	ds_read2_b64 v[168:171], v214 offset1:1
	ds_read2_b64 v[172:175], v214 offset0:136 offset1:137
	v_add_u32_e32 v217, 0x108000, v215
	v_add_u32_e32 v218, 0x108000, v216
	s_waitcnt lgkmcnt(0)
	global_store_dwordx4 v217, v[168:171], s[16:17]
	global_store_dwordx4 v218, v[172:175], s[16:17]
	s_waitcnt vmcnt(16)
	s_branch .LBB0_349
; DI unsigned pk_bf16(float a, float b) { f32x2_t v = {a, b}; bf16x2_t r = __builtin_convertvector(v, bf16x2_t); return __builtin_bit_cast(unsigned, r); }
; template <int EPI>
; DI void gemm_phase(const bf16_t* __restrict__ A, const bf16_t* __restrict__ Bt, const int K, const int N, const Params& p, const int layer_j, char* lds) {
;     ...
;             if (region == 2) {
;                 const int vc0 = col0 - 2048;
;                 const int b = row0 >> 11, t0 = row0 & 2047;
;                 bf16_t* dst = IT + ((size_t)(b * 1024 + vc0 + fr)) * SEQ + t0;
; #pragma unroll
;                 for (int bj = 0; bj < 2; ++bj)
; #pragma unroll
;                     for (int n = 0; n < 2; ++n)
; #pragma unroll
;                         for (int ai = 0; ai < 2; ++ai)
; #pragma unroll
;                             for (int m = 0; m < 4; ++m) { u32x2 o; o[0] = pk_bf16(acc[ai][bj][m][n][0], acc[ai][bj][m][n][1]); o[1] = pk_bf16(acc[ai][bj][m][n][2], acc[ai][bj][m][n][3]);
;                                 *(u32x2*)(dst + (size_t)(bj * 32 + n * 16) * SEQ + ai * 128 + m * 16) = o; }
.Lrec_epi_tr:
	v_mbcnt_lo_u32_b32 v212, -1, 0
	v_mbcnt_hi_u32_b32 v212, -1, v212
	s_mul_i32 s16, s71, 34
	s_add_i32 s16, s16, 0x20100
	v_and_b32_e32 v213, 15, v212
	v_lshrrev_b32_e32 v214, 4, v212
	v_mul_u32_u24_e32 v213, 136, v213
	v_lshl_add_u32 v213, v214, 3, v213
	v_add_u32_e32 v213, s16, v213
	v_lshrrev_b32_e32 v215, 3, v212
	v_and_b32_e32 v216, 7, v212
	v_mul_u32_u24_e32 v214, 136, v215
	v_lshl_add_u32 v214, v216, 4, v214
	v_add_u32_e32 v214, s16, v214
	v_readlane_b32 s16, v254, 14
	v_readlane_b32 s17, v254, 7
	v_lshlrev_b32_e32 v216, 4, v216
	v_add_u32_e32 v215, s16, v215
	s_lshl_b32 s17, s17, 1
	s_mov_b32 s16, 4096
	v_mad_u32_u24 v215, v215, s16, v216
	v_add_u32_e32 v215, s17, v215
	v_add_u32_e32 v216, 0x8000, v215
	v_readlane_b32 s28, v255, 8
	v_readlane_b32 s29, v255, 9
	s_lshr_b32 s16, s8, 3
	s_lshl_b32 s16, s16, 10
	s_lshl_b32 s17, s4, 8
	s_add_i32 s16, s16, s17
	s_sub_u32 s16, s16, 0x800
	s_lshl_b32 s16, s16, 12
	s_and_b32 s17, s8, 7
	s_lshl_b32 s17, s17, 9
	s_add_u32 s16, s16, s17
	s_add_u32 s16, s16, s28
	s_addc_u32 s17, s29, 0
	v_cvt_pk_bf16_f32 v160, v126, v127
	v_cvt_pk_bf16_f32 v161, v128, v129
	v_cvt_pk_bf16_f32 v162, v110, v111
	v_cvt_pk_bf16_f32 v163, v112, v113
	v_cvt_pk_bf16_f32 v164, v94, v95
	v_cvt_pk_bf16_f32 v165, v96, v97
	v_cvt_pk_bf16_f32 v166, v78, v79
	v_cvt_pk_bf16_f32 v167, v80, v81
	ds_write_b64 v213, v[160:161]
	ds_write_b64 v213, v[162:163] offset:32
	ds_write_b64 v213, v[164:165] offset:64
	ds_write_b64 v213, v[166:167] offset:96
	ds_read2_b64 v[168:171], v214 offset1:1
	ds_read2_b64 v[172:175], v214 offset0:136 offset1:137
	s_waitcnt lgkmcnt(0)
	global_store_dwordx4 v215, v[168:171], s[16:17]
	global_store_dwordx4 v216, v[172:175], s[16:17]
	v_cvt_pk_bf16_f32 v160, v70, v71
	v_cvt_pk_bf16_f32 v161, v72, v73
	v_cvt_pk_bf16_f32 v162, v66, v67
	v_cvt_pk_bf16_f32 v163, v68, v69
	v_cvt_pk_bf16_f32 v164, v62, v63
	v_cvt_pk_bf16_f32 v165, v64, v65
	v_cvt_pk_bf16_f32 v166, v58, v59
	v_cvt_pk_bf16_f32 v167, v60, v61
	ds_write_b64 v213, v[160:161]
	ds_write_b64 v213, v[162:163] offset:32
	ds_write_b64 v213, v[164:165] offset:64
	ds_write_b64 v213, v[166:167] offset:96
	ds_read2_b64 v[168:171], v214 offset1:1
	ds_read2_b64 v[172:175], v214 offset0:136 offset1:137
	v_add_u32_e32 v217, 0x100, v215
	v_add_u32_e32 v218, 0x100, v216
	s_waitcnt lgkmcnt(0)
	global_store_dwordx4 v217, v[168:171], s[16:17]
	global_store_dwordx4 v218, v[172:175], s[16:17]
	v_cvt_pk_bf16_f32 v160, v122, v123
	v_cvt_pk_bf16_f32 v161, v124, v125
	v_cvt_pk_bf16_f32 v162, v106, v107
	v_cvt_pk_bf16_f32 v163, v108, v109
	v_cvt_pk_bf16_f32 v164, v90, v91
	v_cvt_pk_bf16_f32 v165, v92, v93
	v_cvt_pk_bf16_f32 v166, v74, v75
	v_cvt_pk_bf16_f32 v167, v76, v77
	ds_write_b64 v213, v[160:161]
	ds_write_b64 v213, v[162:163] offset:32
	ds_write_b64 v213, v[164:165] offset:64
	ds_write_b64 v213, v[166:167] offset:96
	ds_read2_b64 v[168:171], v214 offset1:1
	ds_read2_b64 v[172:175], v214 offset0:136 offset1:137
	v_add_u32_e32 v217, 0x10000, v215
	v_add_u32_e32 v218, 0x10000, v216
	s_waitcnt lgkmcnt(0)
	global_store_dwordx4 v217, v[168:171], s[16:17]
	global_store_dwordx4 v218, v[172:175], s[16:17]
	v_cvt_pk_bf16_f32 v160, v54, v55
	v_cvt_pk_bf16_f32 v161, v56, v57
	v_cvt_pk_bf16_f32 v162, v50, v51
	v_cvt_pk_bf16_f32 v163, v52, v53
	v_cvt_pk_bf16_f32 v164, v46, v47
	v_cvt_pk_bf16_f32 v165, v48, v49
	v_cvt_pk_bf16_f32 v166, v42, v43
	v_cvt_pk_bf16_f32 v167, v44, v45
	ds_write_b64 v213, v[160:161]
	ds_write_b64 v213, v[162:163] offset:32
	ds_write_b64 v213, v[164:165] offset:64
	ds_write_b64 v213, v[166:167] offset:96
	ds_read2_b64 v[168:171], v214 offset1:1
	ds_read2_b64 v[172:175], v214 offset0:136 offset1:137
	v_add_u32_e32 v217, 0x10100, v215
	v_add_u32_e32 v218, 0x10100, v216
	s_waitcnt lgkmcnt(0)
	global_store_dwordx4 v217, v[168:171], s[16:17]
	global_store_dwordx4 v218, v[172:175], s[16:17]
	v_cvt_pk_bf16_f32 v160, v118, v119
	v_cvt_pk_bf16_f32 v161, v120, v121
	v_cvt_pk_bf16_f32 v162, v102, v103
	v_cvt_pk_bf16_f32 v163, v104, v105
	v_cvt_pk_bf16_f32 v164, v86, v87
	v_cvt_pk_bf16_f32 v165, v88, v89
	v_cvt_pk_bf16_f32 v166, v38, v39
	v_cvt_pk_bf16_f32 v167, v40, v41
	ds_write_b64 v213, v[160:161]
	ds_write_b64 v213, v[162:163] offset:32
	ds_write_b64 v213, v[164:165] offset:64
	ds_write_b64 v213, v[166:167] offset:96
	ds_read2_b64 v[168:171], v214 offset1:1
	ds_read2_b64 v[172:175], v214 offset0:136 offset1:137
	v_add_u32_e32 v217, 0x20000, v215
	v_add_u32_e32 v218, 0x20000, v216
	s_waitcnt lgkmcnt(0)
	global_store_dwordx4 v217, v[168:171], s[16:17]
	global_store_dwordx4 v218, v[172:175], s[16:17]
	v_cvt_pk_bf16_f32 v160, v34, v35
	v_cvt_pk_bf16_f32 v161, v36, v37
	v_cvt_pk_bf16_f32 v162, v28, v29
	v_cvt_pk_bf16_f32 v163, v30, v31
	v_cvt_pk_bf16_f32 v164, v24, v25
	v_cvt_pk_bf16_f32 v165, v26, v27
	v_cvt_pk_bf16_f32 v166, v20, v21
	v_cvt_pk_bf16_f32 v167, v22, v23
	ds_write_b64 v213, v[160:161]
	ds_write_b64 v213, v[162:163] offset:32
	ds_write_b64 v213, v[164:165] offset:64
	ds_write_b64 v213, v[166:167] offset:96
	ds_read2_b64 v[168:171], v214 offset1:1
	ds_read2_b64 v[172:175], v214 offset0:136 offset1:137
	v_add_u32_e32 v217, 0x20100, v215
	v_add_u32_e32 v218, 0x20100, v216
	s_waitcnt lgkmcnt(0)
	global_store_dwordx4 v217, v[168:171], s[16:17]
	global_store_dwordx4 v218, v[172:175], s[16:17]
	v_cvt_pk_bf16_f32 v160, v114, v115
	v_cvt_pk_bf16_f32 v161, v116, v117
	v_cvt_pk_bf16_f32 v162, v98, v99
	v_cvt_pk_bf16_f32 v163, v100, v101
	v_cvt_pk_bf16_f32 v164, v82, v83
	v_cvt_pk_bf16_f32 v165, v84, v85
	v_cvt_pk_bf16_f32 v166, v16, v17
	v_cvt_pk_bf16_f32 v167, v18, v19
	ds_write_b64 v213, v[160:161]
	ds_write_b64 v213, v[162:163] offset:32
	ds_write_b64 v213, v[164:165] offset:64
	ds_write_b64 v213, v[166:167] offset:96
	ds_read2_b64 v[168:171], v214 offset1:1
	ds_read2_b64 v[172:175], v214 offset0:136 offset1:137
	v_add_u32_e32 v217, 0x30000, v215
	v_add_u32_e32 v218, 0x30000, v216
	s_waitcnt lgkmcnt(0)
	global_store_dwordx4 v217, v[168:171], s[16:17]
	global_store_dwordx4 v218, v[172:175], s[16:17]
	v_cvt_pk_bf16_f32 v160, v12, v13
	v_cvt_pk_bf16_f32 v161, v14, v15
	v_cvt_pk_bf16_f32 v162, v8, v9
	v_cvt_pk_bf16_f32 v163, v10, v11
	v_cvt_pk_bf16_f32 v164, v4, v5
	v_cvt_pk_bf16_f32 v165, v6, v7
	v_cvt_pk_bf16_f32 v166, v0, v1
	v_cvt_pk_bf16_f32 v167, v2, v3
	ds_write_b64 v213, v[160:161]
	ds_write_b64 v213, v[162:163] offset:32
	ds_write_b64 v213, v[164:165] offset:64
	ds_write_b64 v213, v[166:167] offset:96
	ds_read2_b64 v[168:171], v214 offset1:1
	ds_read2_b64 v[172:175], v214 offset0:136 offset1:137
	v_add_u32_e32 v217, 0x30100, v215
	v_add_u32_e32 v218, 0x30100, v216
	s_waitcnt lgkmcnt(0)
	global_store_dwordx4 v217, v[168:171], s[16:17]
	global_store_dwordx4 v218, v[172:175], s[16:17]
	s_waitcnt vmcnt(16)
	s_branch .LBB0_349

; #define STAGE(bufoff, GB) do { const char* g_ = (GB); \
;         _Pragma("unroll") for (int i_ = 0; i_ < 2; ++i_) __builtin_amdgcn_global_load_lds((const unsigned*)(g_ + voff[i_]), (LAS3 unsigned*)(L + (bufoff) + stoff + i_ * 8192), 16, 0, 0); } while (0)
; #define LDA(dst, b, h) do { _Pragma("unroll") for (int m = 0; m < 4; ++m) _Pragma("unroll") for (int k = 0; k < 2; ++k) dst[m][k] = *(const LAS3 bf16x8*)(L + SA(b, h) + aoff + m * 2048 + k * 1024); } while (0)
; #define LDB(dst, b, h) do { _Pragma("unroll") for (int n = 0; n < 2; ++n) _Pragma("unroll") for (int k = 0; k < 2; ++k) dst[n][k] = *(const LAS3 bf16x8*)(L + SB(b, h) + boff + n * 2048 + k * 1024); } while (0)
; #define WAIT_V(n) asm volatile("s_waitcnt vmcnt(" #n ")" ::: "memory")
; #define WAIT_L(n) asm volatile("s_waitcnt lgkmcnt(" #n ")" ::: "memory")
; #define BAR __builtin_amdgcn_s_barrier()
; #define SCHED __builtin_amdgcn_sched_barrier(0)
; template <int EPI>
; DI void gemm_phase(const bf16_t* __restrict__ A, const bf16_t* __restrict__ Bt, const int K, const int N, const Params& p, const int layer_j, char* lds) {
;     ...
;         for (int t = 0; t < nt; t += 2) {
;             const bool last = (t == nt - 2);
;             const char* a1 = cA + (size_t)(t + 1) * kstep;
;             const char* a2 = last ? nA : cA + (size_t)(t + 2) * kstep; const char* b2 = last ? nB : cB + (size_t)(t + 2) * kstep;
;             const char* a3 = a2 + kstep; const char* b3 = b2 + kstep;
;             LDB(B0, 0, 0); LDB(B1, 0, 1); SCHED; LDA(At, 0, 0); STAGE(SA(1, 1), a1 + hstep);
;             WAIT_V(8); WAIT_L(0); BAR; MMA(0, 0, At, B0); MMA(0, 1, At, B1); BAR; SCHED;
;             LDA(At, 0, 1); STAGE(SB(0, 0), b2); STAGE(SB(0, 1), b2 + hstep); STAGE(SA(0, 0), a2);
;             WAIT_V(8); WAIT_L(0); BAR; MMA(1, 0, At, B0); MMA(1, 1, At, B1); BAR; SCHED;
.LBB0_374:
	s_cmp_eq_u32 s39, 1
	s_cselect_b32 s100, 1, s26
	v_add_u32_e32 v136, 0x10000, v140
	ds_read_b128 v[154:157], v136
	ds_read_b128 v[158:161], v136 offset:1024
	ds_read_b128 v[162:165], v136 offset:2048
	ds_read_b128 v[166:169], v136 offset:3072
	v_add_u32_e32 v136, 0x14000, v140
	s_add_u32 s28, s67, s26
	ds_read_b128 v[170:173], v136
	ds_read_b128 v[174:177], v136 offset:1024
	ds_read_b128 v[178:181], v136 offset:2048
	ds_read_b128 v[182:185], v136 offset:3072
	s_addc_u32 s29, s86, s27
	s_add_u32 s28, s28, 0x6681100
	s_addc_u32 s29, s29, 0
	s_add_u32 s88, s65, s26
	s_addc_u32 vcc_lo, s66, s27
	s_cmpk_eq_i32 s26, 0x700
	s_cselect_b32 s31, s15, s29
	s_cselect_b32 s30, s13, s28
	s_cselect_b32 s29, s64, vcc_lo
	s_cselect_b32 s28, s23, s88
	v_add_u32_e32 v190, 0xc000, v138
	v_lshl_add_u64 v[136:137], v[134:135], 0, s[26:27]
	v_readfirstlane_b32 s88, v190
	v_add_u32_e32 v190, 0xe000, v138
	s_mov_b32 m0, s88
	v_readfirstlane_b32 s88, v190
	ds_read_b128 v[186:189], v139
	ds_read_b128 v[204:207], v139 offset:1024
	ds_read_b128 v[208:211], v139 offset:2048
	ds_read_b128 v[212:215], v139 offset:3072
	ds_read_b128 v[216:219], v139 offset:4096
	ds_read_b128 v[220:223], v139 offset:5120
	ds_read_b128 v[224:227], v139 offset:6144
	ds_read_b128 v[228:231], v139 offset:7168
	global_load_lds_dwordx4 v[136:137], off
	v_lshl_add_u64 v[136:137], v[132:133], 0, s[26:27]
	s_mov_b32 m0, s88
	s_nop 0
	global_load_lds_dwordx4 v[136:137], off
	s_cmp_eq_u32 s100, 0
	s_cbranch_scc1 .Lskipw_att_0
	s_waitcnt vmcnt(8)
.Lskipw_att_0:
	s_waitcnt lgkmcnt(0)
	s_barrier
	s_setprio 1
	s_waitcnt lgkmcnt(0)
	v_mfma_f32_16x16x32_bf16 v[126:129], v[154:157], v[186:189], v[126:129]
	v_mfma_f32_16x16x32_bf16 v[110:113], v[162:165], v[186:189], v[110:113]
	v_mfma_f32_16x16x32_bf16 v[122:125], v[154:157], v[208:211], v[122:125]
	v_mfma_f32_16x16x32_bf16 v[106:109], v[162:165], v[208:211], v[106:109]
	v_mfma_f32_16x16x32_bf16 v[118:121], v[154:157], v[216:219], v[118:121]
	v_mfma_f32_16x16x32_bf16 v[102:105], v[162:165], v[216:219], v[102:105]
	v_mfma_f32_16x16x32_bf16 v[114:117], v[154:157], v[224:227], v[114:117]
	v_mfma_f32_16x16x32_bf16 v[94:97], v[162:165], v[224:227], v[94:97]
	v_mfma_f32_16x16x32_bf16 v[126:129], v[158:161], v[204:207], v[126:129]
	v_mfma_f32_16x16x32_bf16 v[110:113], v[166:169], v[204:207], v[110:113]
	v_mfma_f32_16x16x32_bf16 v[122:125], v[158:161], v[212:215], v[122:125]
	v_mfma_f32_16x16x32_bf16 v[106:109], v[166:169], v[212:215], v[106:109]
	v_mfma_f32_16x16x32_bf16 v[118:121], v[158:161], v[220:223], v[118:121]
	v_mfma_f32_16x16x32_bf16 v[102:105], v[166:169], v[220:223], v[102:105]
	v_mfma_f32_16x16x32_bf16 v[114:117], v[158:161], v[228:231], v[114:117]
	v_mfma_f32_16x16x32_bf16 v[94:97], v[166:169], v[228:231], v[94:97]
	s_setprio 0
	s_setprio 1
	v_mfma_f32_16x16x32_bf16 v[74:77], v[170:173], v[186:189], v[74:77]
	v_mfma_f32_16x16x32_bf16 v[34:37], v[178:181], v[186:189], v[34:37]
	v_mfma_f32_16x16x32_bf16 v[62:65], v[170:173], v[208:211], v[62:65]
	v_mfma_f32_16x16x32_bf16 v[24:27], v[178:181], v[208:211], v[24:27]
	v_mfma_f32_16x16x32_bf16 v[54:57], v[170:173], v[216:219], v[54:57]
	v_mfma_f32_16x16x32_bf16 v[20:23], v[178:181], v[216:219], v[20:23]
	v_mfma_f32_16x16x32_bf16 v[38:41], v[170:173], v[224:227], v[38:41]
	v_mfma_f32_16x16x32_bf16 v[12:15], v[178:181], v[224:227], v[12:15]
	v_mfma_f32_16x16x32_bf16 v[74:77], v[174:177], v[204:207], v[74:77]
	v_mfma_f32_16x16x32_bf16 v[34:37], v[182:185], v[204:207], v[34:37]
	v_mfma_f32_16x16x32_bf16 v[62:65], v[174:177], v[212:215], v[62:65]
	v_mfma_f32_16x16x32_bf16 v[24:27], v[182:185], v[212:215], v[24:27]
	v_mfma_f32_16x16x32_bf16 v[54:57], v[174:177], v[220:223], v[54:57]
	v_mfma_f32_16x16x32_bf16 v[20:23], v[182:185], v[220:223], v[20:23]
	v_mfma_f32_16x16x32_bf16 v[38:41], v[174:177], v[228:231], v[38:41]
	v_mfma_f32_16x16x32_bf16 v[12:15], v[182:185], v[228:231], v[12:15]
	s_setprio 0
	s_barrier
	v_readfirstlane_b32 s88, v141
	v_lshl_add_u64 v[136:137], s[28:29], 0, v[32:33]
	s_mov_b32 m0, s88
	v_readfirstlane_b32 s88, v142
	s_add_u32 vcc_lo, s28, 0x40000
	ds_read_b128 v[186:189], v139 offset:16384
	ds_read_b128 v[204:207], v139 offset:17408
	ds_read_b128 v[208:211], v139 offset:18432
	ds_read_b128 v[212:215], v139 offset:19456
	ds_read_b128 v[216:219], v139 offset:20480
	ds_read_b128 v[220:223], v139 offset:21504
	ds_read_b128 v[224:227], v139 offset:22528
	ds_read_b128 v[228:231], v139 offset:23552
	global_load_lds_dwordx4 v[136:137], off
	v_lshl_add_u64 v[190:191], s[28:29], 0, v[130:131]
	s_mov_b32 m0, s88
	s_addc_u32 vcc_hi, s29, 0
	v_readfirstlane_b32 s88, v143
	global_load_lds_dwordx4 v[190:191], off
	v_lshl_add_u64 v[194:195], vcc, 0, v[32:33]
	s_mov_b32 m0, s88
	v_readfirstlane_b32 s88, v144
	global_load_lds_dwordx4 v[194:195], off
	v_lshl_add_u64 v[194:195], vcc, 0, v[130:131]
	s_mov_b32 m0, s88
	v_readfirstlane_b32 s88, v138
	global_load_lds_dwordx4 v[194:195], off
	v_lshl_add_u64 v[194:195], s[30:31], 0, v[32:33]
	s_mov_b32 m0, s88
	v_readfirstlane_b32 s88, v145
	global_load_lds_dwordx4 v[194:195], off
	v_lshl_add_u64 v[232:233], s[30:31], 0, v[130:131]
	s_mov_b32 m0, s88
	s_nop 0
	global_load_lds_dwordx4 v[232:233], off
	s_cmp_eq_u32 s100, 0
	s_cbranch_scc1 .Lskipw_att_1
	s_waitcnt vmcnt(8)
; #define STAGE(bufoff, GB) do { const char* g_ = (GB); \
;         _Pragma("unroll") for (int i_ = 0; i_ < 2; ++i_) __builtin_amdgcn_global_load_lds((const unsigned*)(g_ + voff[i_]), (LAS3 unsigned*)(L + (bufoff) + stoff + i_ * 8192), 16, 0, 0); } while (0)
; #define LDA(dst, b, h) do { _Pragma("unroll") for (int m = 0; m < 4; ++m) _Pragma("unroll") for (int k = 0; k < 2; ++k) dst[m][k] = *(const LAS3 bf16x8*)(L + SA(b, h) + aoff + m * 2048 + k * 1024); } while (0)
; #define LDB(dst, b, h) do { _Pragma("unroll") for (int n = 0; n < 2; ++n) _Pragma("unroll") for (int k = 0; k < 2; ++k) dst[n][k] = *(const LAS3 bf16x8*)(L + SB(b, h) + boff + n * 2048 + k * 1024); } while (0)
; #define WAIT_V(n) asm volatile("s_waitcnt vmcnt(" #n ")" ::: "memory")
; #define WAIT_L(n) asm volatile("s_waitcnt lgkmcnt(" #n ")" ::: "memory")
; #define BAR __builtin_amdgcn_s_barrier()
; #define SCHED __builtin_amdgcn_sched_barrier(0)
; template <int EPI>
; DI void gemm_phase(const bf16_t* __restrict__ A, const bf16_t* __restrict__ Bt, const int K, const int N, const Params& p, const int layer_j, char* lds) {
;     ...
;             WAIT_V(8); WAIT_L(0); BAR; MMA(1, 0, At, B0); MMA(1, 1, At, B1); BAR; SCHED;
;             LDB(B0, 1, 0); LDB(B1, 1, 1); SCHED; LDA(At, 1, 0); STAGE(SA(0, 1), a2 + hstep);
;             WAIT_V(8); WAIT_L(0); BAR; MMA(0, 0, At, B0); MMA(0, 1, At, B1); BAR; SCHED;
;             LDA(At, 1, 1); STAGE(SB(1, 0), b3); STAGE(SB(1, 1), b3 + hstep); STAGE(SA(1, 0), a3);
;             WAIT_V(8); WAIT_L(0); BAR; MMA(1, 0, At, B0); MMA(1, 1, At, B1); BAR; SCHED;
.Lskipw_att_1:
	s_waitcnt lgkmcnt(0)
	s_barrier
	s_setprio 1
	s_waitcnt lgkmcnt(0)
	v_mfma_f32_16x16x32_bf16 v[98:101], v[154:157], v[186:189], v[98:101]
	v_mfma_f32_16x16x32_bf16 v[66:69], v[162:165], v[186:189], v[66:69]
	v_mfma_f32_16x16x32_bf16 v[90:93], v[154:157], v[208:211], v[90:93]
	v_mfma_f32_16x16x32_bf16 v[58:61], v[162:165], v[208:211], v[58:61]
	v_mfma_f32_16x16x32_bf16 v[86:89], v[154:157], v[216:219], v[86:89]
	v_mfma_f32_16x16x32_bf16 v[42:45], v[162:165], v[216:219], v[42:45]
	v_mfma_f32_16x16x32_bf16 v[70:73], v[154:157], v[224:227], v[70:73]
	v_mfma_f32_16x16x32_bf16 v[28:31], v[162:165], v[224:227], v[28:31]
	v_mfma_f32_16x16x32_bf16 v[98:101], v[158:161], v[204:207], v[98:101]
	v_mfma_f32_16x16x32_bf16 v[66:69], v[166:169], v[204:207], v[66:69]
	v_mfma_f32_16x16x32_bf16 v[90:93], v[158:161], v[212:215], v[90:93]
	v_mfma_f32_16x16x32_bf16 v[58:61], v[166:169], v[212:215], v[58:61]
	v_mfma_f32_16x16x32_bf16 v[86:89], v[158:161], v[220:223], v[86:89]
	v_mfma_f32_16x16x32_bf16 v[42:45], v[166:169], v[220:223], v[42:45]
	v_mfma_f32_16x16x32_bf16 v[70:73], v[158:161], v[228:231], v[70:73]
	v_mfma_f32_16x16x32_bf16 v[28:31], v[166:169], v[228:231], v[28:31]
	s_setprio 0
	s_setprio 1
	v_mfma_f32_16x16x32_bf16 v[16:19], v[170:173], v[186:189], v[16:19]
	v_mfma_f32_16x16x32_bf16 v[4:7], v[178:181], v[186:189], v[4:7]
	v_mfma_f32_16x16x32_bf16 v[8:11], v[170:173], v[208:211], v[8:11]
	v_mfma_f32_16x16x32_bf16 v[0:3], v[178:181], v[208:211], v[0:3]
	v_mfma_f32_16x16x32_bf16 v[78:81], v[170:173], v[216:219], v[78:81]
	v_mfma_f32_16x16x32_bf16 v[46:49], v[178:181], v[216:219], v[46:49]
	v_mfma_f32_16x16x32_bf16 v[82:85], v[170:173], v[224:227], v[82:85]
	v_mfma_f32_16x16x32_bf16 v[50:53], v[178:181], v[224:227], v[50:53]
	v_mfma_f32_16x16x32_bf16 v[16:19], v[174:177], v[204:207], v[16:19]
	v_mfma_f32_16x16x32_bf16 v[4:7], v[182:185], v[204:207], v[4:7]
	v_mfma_f32_16x16x32_bf16 v[8:11], v[174:177], v[212:215], v[8:11]
	v_mfma_f32_16x16x32_bf16 v[0:3], v[182:185], v[212:215], v[0:3]
	v_mfma_f32_16x16x32_bf16 v[78:81], v[174:177], v[220:223], v[78:81]
	v_mfma_f32_16x16x32_bf16 v[46:49], v[182:185], v[220:223], v[46:49]
	v_mfma_f32_16x16x32_bf16 v[82:85], v[174:177], v[228:231], v[82:85]
	v_mfma_f32_16x16x32_bf16 v[50:53], v[182:185], v[228:231], v[50:53]
	s_setprio 0
	s_barrier
	v_add_u32_e32 v166, 0x18000, v140
	v_add_u32_e32 v182, 0x1c000, v140
	ds_read_b128 v[154:157], v166
	ds_read_b128 v[158:161], v166 offset:1024
	ds_read_b128 v[162:165], v166 offset:2048
	ds_read_b128 v[166:169], v166 offset:3072
	ds_read_b128 v[170:173], v182
	ds_read_b128 v[174:177], v182 offset:1024
	ds_read_b128 v[178:181], v182 offset:2048
	ds_read_b128 v[182:185], v182 offset:3072
	s_add_u32 s30, s30, 0x40000
	s_addc_u32 s31, s31, 0
	v_readfirstlane_b32 s88, v146
	v_lshl_add_u64 v[234:235], s[30:31], 0, v[32:33]
	s_mov_b32 m0, s88
	ds_read_b128 v[186:189], v139 offset:32768
	ds_read_b128 v[204:207], v139 offset:33792
	ds_read_b128 v[208:211], v139 offset:34816
	ds_read_b128 v[212:215], v139 offset:35840
	ds_read_b128 v[216:219], v139 offset:36864
	ds_read_b128 v[220:223], v139 offset:37888
	ds_read_b128 v[224:227], v139 offset:38912
	ds_read_b128 v[228:231], v139 offset:39936
	global_load_lds_dwordx4 v[234:235], off
	v_lshl_add_u64 v[234:235], s[30:31], 0, v[130:131]
	v_readfirstlane_b32 s30, v147
	s_mov_b32 m0, s30
	s_nop 0
	global_load_lds_dwordx4 v[234:235], off
	s_waitcnt vmcnt(8)
	s_waitcnt lgkmcnt(0)
	s_barrier
	s_setprio 1
	s_waitcnt lgkmcnt(0)
	v_mfma_f32_16x16x32_bf16 v[126:129], v[154:157], v[186:189], v[126:129]
	v_mfma_f32_16x16x32_bf16 v[110:113], v[162:165], v[186:189], v[110:113]
	v_mfma_f32_16x16x32_bf16 v[122:125], v[154:157], v[208:211], v[122:125]
	v_mfma_f32_16x16x32_bf16 v[106:109], v[162:165], v[208:211], v[106:109]
	v_mfma_f32_16x16x32_bf16 v[118:121], v[154:157], v[216:219], v[118:121]
	v_mfma_f32_16x16x32_bf16 v[102:105], v[162:165], v[216:219], v[102:105]
	v_mfma_f32_16x16x32_bf16 v[114:117], v[154:157], v[224:227], v[114:117]
	v_mfma_f32_16x16x32_bf16 v[94:97], v[162:165], v[224:227], v[94:97]
	v_mfma_f32_16x16x32_bf16 v[126:129], v[158:161], v[204:207], v[126:129]
	v_mfma_f32_16x16x32_bf16 v[110:113], v[166:169], v[204:207], v[110:113]
	v_mfma_f32_16x16x32_bf16 v[122:125], v[158:161], v[212:215], v[122:125]
	v_mfma_f32_16x16x32_bf16 v[106:109], v[166:169], v[212:215], v[106:109]
	v_mfma_f32_16x16x32_bf16 v[118:121], v[158:161], v[220:223], v[118:121]
	v_mfma_f32_16x16x32_bf16 v[102:105], v[166:169], v[220:223], v[102:105]
	v_mfma_f32_16x16x32_bf16 v[114:117], v[158:161], v[228:231], v[114:117]
	v_mfma_f32_16x16x32_bf16 v[94:97], v[166:169], v[228:231], v[94:97]
	s_setprio 0
	s_setprio 1
	v_mfma_f32_16x16x32_bf16 v[74:77], v[170:173], v[186:189], v[74:77]
	v_mfma_f32_16x16x32_bf16 v[34:37], v[178:181], v[186:189], v[34:37]
	v_mfma_f32_16x16x32_bf16 v[62:65], v[170:173], v[208:211], v[62:65]
	v_mfma_f32_16x16x32_bf16 v[24:27], v[178:181], v[208:211], v[24:27]
	v_mfma_f32_16x16x32_bf16 v[54:57], v[170:173], v[216:219], v[54:57]
	v_mfma_f32_16x16x32_bf16 v[20:23], v[178:181], v[216:219], v[20:23]
	v_mfma_f32_16x16x32_bf16 v[38:41], v[170:173], v[224:227], v[38:41]
	v_mfma_f32_16x16x32_bf16 v[12:15], v[178:181], v[224:227], v[12:15]
	v_mfma_f32_16x16x32_bf16 v[74:77], v[174:177], v[204:207], v[74:77]
	v_mfma_f32_16x16x32_bf16 v[34:37], v[182:185], v[204:207], v[34:37]
	v_mfma_f32_16x16x32_bf16 v[62:65], v[174:177], v[212:215], v[62:65]
	v_mfma_f32_16x16x32_bf16 v[24:27], v[182:185], v[212:215], v[24:27]
	v_mfma_f32_16x16x32_bf16 v[54:57], v[174:177], v[220:223], v[54:57]
	v_mfma_f32_16x16x32_bf16 v[20:23], v[182:185], v[220:223], v[20:23]
	v_mfma_f32_16x16x32_bf16 v[38:41], v[174:177], v[228:231], v[38:41]
	v_mfma_f32_16x16x32_bf16 v[12:15], v[182:185], v[228:231], v[12:15]
	s_setprio 0
	s_barrier
; #define STAGE(bufoff, GB) do { const char* g_ = (GB); \
;         _Pragma("unroll") for (int i_ = 0; i_ < 2; ++i_) __builtin_amdgcn_global_load_lds((const unsigned*)(g_ + voff[i_]), (LAS3 unsigned*)(L + (bufoff) + stoff + i_ * 8192), 16, 0, 0); } while (0)
; #define LDA(dst, b, h) do { _Pragma("unroll") for (int m = 0; m < 4; ++m) _Pragma("unroll") for (int k = 0; k < 2; ++k) dst[m][k] = *(const LAS3 bf16x8*)(L + SA(b, h) + aoff + m * 2048 + k * 1024); } while (0)
; #define WAIT_V(n) asm volatile("s_waitcnt vmcnt(" #n ")" ::: "memory")
; #define WAIT_L(n) asm volatile("s_waitcnt lgkmcnt(" #n ")" ::: "memory")
; #define BAR __builtin_amdgcn_s_barrier()
; #define SCHED __builtin_amdgcn_sched_barrier(0)
; template <int EPI>
; DI void gemm_phase(const bf16_t* __restrict__ A, const bf16_t* __restrict__ Bt, const int K, const int N, const Params& p, const int layer_j, char* lds) {
;     ...
;             LDA(At, 1, 1); STAGE(SB(1, 0), b3); STAGE(SB(1, 1), b3 + hstep); STAGE(SA(1, 0), a3);
;             WAIT_V(8); WAIT_L(0); BAR; MMA(1, 0, At, B0); MMA(1, 1, At, B1); BAR; SCHED;
;         }
	v_readfirstlane_b32 s30, v148
	v_lshl_add_u64 v[136:137], v[136:137], 0, s[94:95]
	s_mov_b32 m0, s30
	v_readfirstlane_b32 s30, v149
	s_add_u32 s28, s28, 0x40080
	ds_read_b128 v[186:189], v139 offset:49152
	ds_read_b128 v[204:207], v139 offset:50176
	ds_read_b128 v[208:211], v139 offset:51200
	ds_read_b128 v[212:215], v139 offset:52224
	ds_read_b128 v[216:219], v139 offset:53248
	ds_read_b128 v[220:223], v139 offset:54272
	ds_read_b128 v[224:227], v139 offset:55296
	ds_read_b128 v[228:231], v139 offset:56320
	global_load_lds_dwordx4 v[136:137], off
	v_lshl_add_u64 v[136:137], v[190:191], 0, s[94:95]
	s_mov_b32 m0, s30
	s_addc_u32 s29, s29, 0
	v_readfirstlane_b32 s30, v152
	global_load_lds_dwordx4 v[136:137], off
	v_lshl_add_u64 v[136:137], s[28:29], 0, v[32:33]
	s_mov_b32 m0, s30
	s_nop 0
	global_load_lds_dwordx4 v[136:137], off
	v_lshl_add_u64 v[136:137], s[28:29], 0, v[130:131]
	v_readfirstlane_b32 s28, v153
	s_mov_b32 m0, s28
	v_readfirstlane_b32 s28, v150
	global_load_lds_dwordx4 v[136:137], off
	v_lshl_add_u64 v[136:137], v[194:195], 0, s[94:95]
	s_mov_b32 m0, s28
	v_readfirstlane_b32 s28, v151
	global_load_lds_dwordx4 v[136:137], off
	v_lshl_add_u64 v[136:137], v[232:233], 0, s[94:95]
	s_mov_b32 m0, s28
	s_nop 0
	global_load_lds_dwordx4 v[136:137], off
	s_waitcnt vmcnt(8)
	s_waitcnt lgkmcnt(0)
	s_barrier
	s_setprio 1
	s_waitcnt lgkmcnt(0)
	v_mfma_f32_16x16x32_bf16 v[98:101], v[154:157], v[186:189], v[98:101]
	v_mfma_f32_16x16x32_bf16 v[66:69], v[162:165], v[186:189], v[66:69]
	v_mfma_f32_16x16x32_bf16 v[90:93], v[154:157], v[208:211], v[90:93]
	v_mfma_f32_16x16x32_bf16 v[58:61], v[162:165], v[208:211], v[58:61]
	v_mfma_f32_16x16x32_bf16 v[86:89], v[154:157], v[216:219], v[86:89]
	v_mfma_f32_16x16x32_bf16 v[42:45], v[162:165], v[216:219], v[42:45]
	v_mfma_f32_16x16x32_bf16 v[70:73], v[154:157], v[224:227], v[70:73]
	v_mfma_f32_16x16x32_bf16 v[28:31], v[162:165], v[224:227], v[28:31]
	v_mfma_f32_16x16x32_bf16 v[98:101], v[158:161], v[204:207], v[98:101]
	v_mfma_f32_16x16x32_bf16 v[66:69], v[166:169], v[204:207], v[66:69]
	v_mfma_f32_16x16x32_bf16 v[90:93], v[158:161], v[212:215], v[90:93]
	v_mfma_f32_16x16x32_bf16 v[58:61], v[166:169], v[212:215], v[58:61]
	v_mfma_f32_16x16x32_bf16 v[86:89], v[158:161], v[220:223], v[86:89]
	v_mfma_f32_16x16x32_bf16 v[42:45], v[166:169], v[220:223], v[42:45]
	v_mfma_f32_16x16x32_bf16 v[70:73], v[158:161], v[228:231], v[70:73]
	v_mfma_f32_16x16x32_bf16 v[28:31], v[166:169], v[228:231], v[28:31]
	s_setprio 0
	s_setprio 1
	v_mfma_f32_16x16x32_bf16 v[16:19], v[170:173], v[186:189], v[16:19]
	v_mfma_f32_16x16x32_bf16 v[4:7], v[178:181], v[186:189], v[4:7]
	v_mfma_f32_16x16x32_bf16 v[8:11], v[170:173], v[208:211], v[8:11]
	v_mfma_f32_16x16x32_bf16 v[0:3], v[178:181], v[208:211], v[0:3]
	v_mfma_f32_16x16x32_bf16 v[78:81], v[170:173], v[216:219], v[78:81]
	v_mfma_f32_16x16x32_bf16 v[46:49], v[178:181], v[216:219], v[46:49]
	v_mfma_f32_16x16x32_bf16 v[82:85], v[170:173], v[224:227], v[82:85]
	v_mfma_f32_16x16x32_bf16 v[50:53], v[178:181], v[224:227], v[50:53]
	v_mfma_f32_16x16x32_bf16 v[16:19], v[174:177], v[204:207], v[16:19]
	v_mfma_f32_16x16x32_bf16 v[4:7], v[182:185], v[204:207], v[4:7]
	v_mfma_f32_16x16x32_bf16 v[8:11], v[174:177], v[212:215], v[8:11]
	v_mfma_f32_16x16x32_bf16 v[0:3], v[182:185], v[212:215], v[0:3]
	v_mfma_f32_16x16x32_bf16 v[78:81], v[174:177], v[220:223], v[78:81]
	v_mfma_f32_16x16x32_bf16 v[46:49], v[182:185], v[220:223], v[46:49]
	v_mfma_f32_16x16x32_bf16 v[82:85], v[174:177], v[228:231], v[82:85]
	v_mfma_f32_16x16x32_bf16 v[50:53], v[182:185], v[228:231], v[50:53]
	s_setprio 0
	s_barrier
	s_add_i32 s87, s87, 2
	s_add_u32 s26, s26, 0x100
	s_addc_u32 s27, s27, 0
	s_cmp_gt_u32 s87, 13
	s_cbranch_scc0 .LBB0_374
	s_branch .Latt_kloop_done

; #define STAGE(bufoff, GB) do { const char* g_ = (GB); \
;         _Pragma("unroll") for (int i_ = 0; i_ < 2; ++i_) __builtin_amdgcn_global_load_lds((const unsigned*)(g_ + voff[i_]), (LAS3 unsigned*)(L + (bufoff) + stoff + i_ * 8192), 16, 0, 0); } while (0)
; #define LDA(dst, b, h) do { _Pragma("unroll") for (int m = 0; m < 4; ++m) _Pragma("unroll") for (int k = 0; k < 2; ++k) dst[m][k] = *(const LAS3 bf16x8*)(L + SA(b, h) + aoff + m * 2048 + k * 1024); } while (0)
; #define LDB(dst, b, h) do { _Pragma("unroll") for (int n = 0; n < 2; ++n) _Pragma("unroll") for (int k = 0; k < 2; ++k) dst[n][k] = *(const LAS3 bf16x8*)(L + SB(b, h) + boff + n * 2048 + k * 1024); } while (0)
; #define WAIT_V(n) asm volatile("s_waitcnt vmcnt(" #n ")" ::: "memory")
; #define WAIT_L(n) asm volatile("s_waitcnt lgkmcnt(" #n ")" ::: "memory")
; #define BAR __builtin_amdgcn_s_barrier()
; #define SCHED __builtin_amdgcn_sched_barrier(0)
; template <int EPI>
; DI void gemm_phase(const bf16_t* __restrict__ A, const bf16_t* __restrict__ Bt, const int K, const int N, const Params& p, const int layer_j, char* lds) {
;     ...
;             WAIT_V(8); WAIT_L(0); BAR; MMA(0, 0, At, B0); MMA(0, 1, At, B1); BAR; SCHED;
;             LDA(At, 0, 1); STAGE(SB(0, 0), b2); STAGE(SB(0, 1), b2 + hstep); STAGE(SA(0, 0), a2);
;             WAIT_V(8); WAIT_L(0); BAR; MMA(1, 0, At, B0); MMA(1, 1, At, B1); BAR; SCHED;
;             LDB(B0, 1, 0); LDB(B1, 1, 1); SCHED; LDA(At, 1, 0); STAGE(SA(0, 1), a2 + hstep);
;             WAIT_V(8); WAIT_L(0); BAR; MMA(0, 0, At, B0); MMA(0, 1, At, B1); BAR; SCHED;
.Lskipw_attns_0:
	s_waitcnt lgkmcnt(0)
	s_barrier
	s_setprio 1
	s_waitcnt lgkmcnt(0)
	v_mfma_f32_16x16x32_bf16 v[126:129], v[186:189], v[154:157], v[126:129]
	v_mfma_f32_16x16x32_bf16 v[110:113], v[186:189], v[162:165], v[110:113]
	v_mfma_f32_16x16x32_bf16 v[122:125], v[208:211], v[154:157], v[122:125]
	v_mfma_f32_16x16x32_bf16 v[106:109], v[208:211], v[162:165], v[106:109]
	v_mfma_f32_16x16x32_bf16 v[118:121], v[216:219], v[154:157], v[118:121]
	v_mfma_f32_16x16x32_bf16 v[102:105], v[216:219], v[162:165], v[102:105]
	v_mfma_f32_16x16x32_bf16 v[114:117], v[224:227], v[154:157], v[114:117]
	v_mfma_f32_16x16x32_bf16 v[94:97], v[224:227], v[162:165], v[94:97]
	v_mfma_f32_16x16x32_bf16 v[126:129], v[204:207], v[158:161], v[126:129]
	v_mfma_f32_16x16x32_bf16 v[110:113], v[204:207], v[166:169], v[110:113]
	v_mfma_f32_16x16x32_bf16 v[122:125], v[212:215], v[158:161], v[122:125]
	v_mfma_f32_16x16x32_bf16 v[106:109], v[212:215], v[166:169], v[106:109]
	v_mfma_f32_16x16x32_bf16 v[118:121], v[220:223], v[158:161], v[118:121]
	v_mfma_f32_16x16x32_bf16 v[102:105], v[220:223], v[166:169], v[102:105]
	v_mfma_f32_16x16x32_bf16 v[114:117], v[228:231], v[158:161], v[114:117]
	v_mfma_f32_16x16x32_bf16 v[94:97], v[228:231], v[166:169], v[94:97]
	s_setprio 0
	s_setprio 1
	v_mfma_f32_16x16x32_bf16 v[74:77], v[186:189], v[170:173], v[74:77]
	v_mfma_f32_16x16x32_bf16 v[34:37], v[186:189], v[178:181], v[34:37]
	v_mfma_f32_16x16x32_bf16 v[62:65], v[208:211], v[170:173], v[62:65]
	v_mfma_f32_16x16x32_bf16 v[24:27], v[208:211], v[178:181], v[24:27]
	v_mfma_f32_16x16x32_bf16 v[54:57], v[216:219], v[170:173], v[54:57]
	v_mfma_f32_16x16x32_bf16 v[20:23], v[216:219], v[178:181], v[20:23]
	v_mfma_f32_16x16x32_bf16 v[38:41], v[224:227], v[170:173], v[38:41]
	v_mfma_f32_16x16x32_bf16 v[12:15], v[224:227], v[178:181], v[12:15]
	v_mfma_f32_16x16x32_bf16 v[74:77], v[204:207], v[174:177], v[74:77]
	v_mfma_f32_16x16x32_bf16 v[34:37], v[204:207], v[182:185], v[34:37]
	v_mfma_f32_16x16x32_bf16 v[62:65], v[212:215], v[174:177], v[62:65]
	v_mfma_f32_16x16x32_bf16 v[24:27], v[212:215], v[182:185], v[24:27]
	v_mfma_f32_16x16x32_bf16 v[54:57], v[220:223], v[174:177], v[54:57]
	v_mfma_f32_16x16x32_bf16 v[20:23], v[220:223], v[182:185], v[20:23]
	v_mfma_f32_16x16x32_bf16 v[38:41], v[228:231], v[174:177], v[38:41]
	v_mfma_f32_16x16x32_bf16 v[12:15], v[228:231], v[182:185], v[12:15]
	s_setprio 0
	s_barrier
	v_readfirstlane_b32 s88, v141
	v_lshl_add_u64 v[136:137], s[28:29], 0, v[32:33]
	s_mov_b32 m0, s88
	v_readfirstlane_b32 s88, v142
	s_add_u32 vcc_lo, s28, 0x40000
	ds_read_b128 v[186:189], v139 offset:16384
	ds_read_b128 v[204:207], v139 offset:17408
	ds_read_b128 v[208:211], v139 offset:18432
	ds_read_b128 v[212:215], v139 offset:19456
	ds_read_b128 v[216:219], v139 offset:20480
	ds_read_b128 v[220:223], v139 offset:21504
	ds_read_b128 v[224:227], v139 offset:22528
	ds_read_b128 v[228:231], v139 offset:23552
	global_load_lds_dwordx4 v[136:137], off
	v_lshl_add_u64 v[190:191], s[28:29], 0, v[130:131]
	s_mov_b32 m0, s88
	s_addc_u32 vcc_hi, s29, 0
	v_readfirstlane_b32 s88, v143
	global_load_lds_dwordx4 v[190:191], off
	v_lshl_add_u64 v[194:195], vcc, 0, v[32:33]
	s_mov_b32 m0, s88
	v_readfirstlane_b32 s88, v144
	global_load_lds_dwordx4 v[194:195], off
	v_lshl_add_u64 v[194:195], vcc, 0, v[130:131]
	s_mov_b32 m0, s88
	v_readfirstlane_b32 s88, v138
	global_load_lds_dwordx4 v[194:195], off
	v_lshl_add_u64 v[194:195], s[30:31], 0, v[32:33]
	s_mov_b32 m0, s88
	v_readfirstlane_b32 s88, v145
	global_load_lds_dwordx4 v[194:195], off
	v_lshl_add_u64 v[232:233], s[30:31], 0, v[130:131]
	s_mov_b32 m0, s88
	s_nop 0
	global_load_lds_dwordx4 v[232:233], off
	s_cmp_eq_u32 s100, 0
	s_cbranch_scc1 .Lskipw_attns_1
	s_waitcnt vmcnt(8)
.Lskipw_attns_1:
	s_waitcnt lgkmcnt(0)
	s_barrier
	s_setprio 1
	s_waitcnt lgkmcnt(0)
	v_mfma_f32_16x16x32_bf16 v[98:101], v[186:189], v[154:157], v[98:101]
	v_mfma_f32_16x16x32_bf16 v[66:69], v[186:189], v[162:165], v[66:69]
	v_mfma_f32_16x16x32_bf16 v[90:93], v[208:211], v[154:157], v[90:93]
	v_mfma_f32_16x16x32_bf16 v[58:61], v[208:211], v[162:165], v[58:61]
	v_mfma_f32_16x16x32_bf16 v[86:89], v[216:219], v[154:157], v[86:89]
	v_mfma_f32_16x16x32_bf16 v[42:45], v[216:219], v[162:165], v[42:45]
	v_mfma_f32_16x16x32_bf16 v[70:73], v[224:227], v[154:157], v[70:73]
	v_mfma_f32_16x16x32_bf16 v[28:31], v[224:227], v[162:165], v[28:31]
	v_mfma_f32_16x16x32_bf16 v[98:101], v[204:207], v[158:161], v[98:101]
	v_mfma_f32_16x16x32_bf16 v[66:69], v[204:207], v[166:169], v[66:69]
	v_mfma_f32_16x16x32_bf16 v[90:93], v[212:215], v[158:161], v[90:93]
	v_mfma_f32_16x16x32_bf16 v[58:61], v[212:215], v[166:169], v[58:61]
	v_mfma_f32_16x16x32_bf16 v[86:89], v[220:223], v[158:161], v[86:89]
	v_mfma_f32_16x16x32_bf16 v[42:45], v[220:223], v[166:169], v[42:45]
	v_mfma_f32_16x16x32_bf16 v[70:73], v[228:231], v[158:161], v[70:73]
	v_mfma_f32_16x16x32_bf16 v[28:31], v[228:231], v[166:169], v[28:31]
	s_setprio 0
	s_setprio 1
	v_mfma_f32_16x16x32_bf16 v[16:19], v[186:189], v[170:173], v[16:19]
	v_mfma_f32_16x16x32_bf16 v[4:7], v[186:189], v[178:181], v[4:7]
	v_mfma_f32_16x16x32_bf16 v[8:11], v[208:211], v[170:173], v[8:11]
	v_mfma_f32_16x16x32_bf16 v[0:3], v[208:211], v[178:181], v[0:3]
	v_mfma_f32_16x16x32_bf16 v[78:81], v[216:219], v[170:173], v[78:81]
	v_mfma_f32_16x16x32_bf16 v[46:49], v[216:219], v[178:181], v[46:49]
	v_mfma_f32_16x16x32_bf16 v[82:85], v[224:227], v[170:173], v[82:85]
	v_mfma_f32_16x16x32_bf16 v[50:53], v[224:227], v[178:181], v[50:53]
	v_mfma_f32_16x16x32_bf16 v[16:19], v[204:207], v[174:177], v[16:19]
	v_mfma_f32_16x16x32_bf16 v[4:7], v[204:207], v[182:185], v[4:7]
	v_mfma_f32_16x16x32_bf16 v[8:11], v[212:215], v[174:177], v[8:11]
	v_mfma_f32_16x16x32_bf16 v[0:3], v[212:215], v[182:185], v[0:3]
	v_mfma_f32_16x16x32_bf16 v[78:81], v[220:223], v[174:177], v[78:81]
	v_mfma_f32_16x16x32_bf16 v[46:49], v[220:223], v[182:185], v[46:49]
	v_mfma_f32_16x16x32_bf16 v[82:85], v[228:231], v[174:177], v[82:85]
	v_mfma_f32_16x16x32_bf16 v[50:53], v[228:231], v[182:185], v[50:53]
	s_setprio 0
	s_barrier
; #define STAGE(bufoff, GB) do { const char* g_ = (GB); \
;         _Pragma("unroll") for (int i_ = 0; i_ < 2; ++i_) __builtin_amdgcn_global_load_lds((const unsigned*)(g_ + voff[i_]), (LAS3 unsigned*)(L + (bufoff) + stoff + i_ * 8192), 16, 0, 0); } while (0)
; #define LDA(dst, b, h) do { _Pragma("unroll") for (int m = 0; m < 4; ++m) _Pragma("unroll") for (int k = 0; k < 2; ++k) dst[m][k] = *(const LAS3 bf16x8*)(L + SA(b, h) + aoff + m * 2048 + k * 1024); } while (0)
; #define LDB(dst, b, h) do { _Pragma("unroll") for (int n = 0; n < 2; ++n) _Pragma("unroll") for (int k = 0; k < 2; ++k) dst[n][k] = *(const LAS3 bf16x8*)(L + SB(b, h) + boff + n * 2048 + k * 1024); } while (0)
; #define WAIT_V(n) asm volatile("s_waitcnt vmcnt(" #n ")" ::: "memory")
; #define WAIT_L(n) asm volatile("s_waitcnt lgkmcnt(" #n ")" ::: "memory")
; #define BAR __builtin_amdgcn_s_barrier()
; #define SCHED __builtin_amdgcn_sched_barrier(0)
; template <int EPI>
; DI void gemm_phase(const bf16_t* __restrict__ A, const bf16_t* __restrict__ Bt, const int K, const int N, const Params& p, const int layer_j, char* lds) {
;     ...
;             LDB(B0, 1, 0); LDB(B1, 1, 1); SCHED; LDA(At, 1, 0); STAGE(SA(0, 1), a2 + hstep);
;             WAIT_V(8); WAIT_L(0); BAR; MMA(0, 0, At, B0); MMA(0, 1, At, B1); BAR; SCHED;
	v_add_u32_e32 v166, 0x18000, v140
	v_add_u32_e32 v182, 0x1c000, v140
	ds_read_b128 v[154:157], v166
	ds_read_b128 v[158:161], v166 offset:1024
	ds_read_b128 v[162:165], v166 offset:2048
	ds_read_b128 v[166:169], v166 offset:3072
	ds_read_b128 v[170:173], v182
	ds_read_b128 v[174:177], v182 offset:1024
	ds_read_b128 v[178:181], v182 offset:2048
	ds_read_b128 v[182:185], v182 offset:3072
	s_add_u32 s30, s30, 0x40000
	s_addc_u32 s31, s31, 0
	v_readfirstlane_b32 s88, v146
	v_lshl_add_u64 v[234:235], s[30:31], 0, v[32:33]
	s_mov_b32 m0, s88
	ds_read_b128 v[186:189], v139 offset:32768
	ds_read_b128 v[204:207], v139 offset:33792
	ds_read_b128 v[208:211], v139 offset:34816
	ds_read_b128 v[212:215], v139 offset:35840
	ds_read_b128 v[216:219], v139 offset:36864
	ds_read_b128 v[220:223], v139 offset:37888
	ds_read_b128 v[224:227], v139 offset:38912
	ds_read_b128 v[228:231], v139 offset:39936
	global_load_lds_dwordx4 v[234:235], off
	v_lshl_add_u64 v[234:235], s[30:31], 0, v[130:131]
	v_readfirstlane_b32 s30, v147
	s_mov_b32 m0, s30
	s_nop 0
	global_load_lds_dwordx4 v[234:235], off
	s_waitcnt vmcnt(8)
	s_waitcnt lgkmcnt(0)
	s_barrier
	s_setprio 1
	s_waitcnt lgkmcnt(0)
	v_mfma_f32_16x16x32_bf16 v[126:129], v[186:189], v[154:157], v[126:129]
	v_mfma_f32_16x16x32_bf16 v[110:113], v[186:189], v[162:165], v[110:113]
	v_mfma_f32_16x16x32_bf16 v[122:125], v[208:211], v[154:157], v[122:125]
	v_mfma_f32_16x16x32_bf16 v[106:109], v[208:211], v[162:165], v[106:109]
	v_mfma_f32_16x16x32_bf16 v[118:121], v[216:219], v[154:157], v[118:121]
	v_mfma_f32_16x16x32_bf16 v[102:105], v[216:219], v[162:165], v[102:105]
	v_mfma_f32_16x16x32_bf16 v[114:117], v[224:227], v[154:157], v[114:117]
	v_mfma_f32_16x16x32_bf16 v[94:97], v[224:227], v[162:165], v[94:97]
	v_mfma_f32_16x16x32_bf16 v[126:129], v[204:207], v[158:161], v[126:129]
	v_mfma_f32_16x16x32_bf16 v[110:113], v[204:207], v[166:169], v[110:113]
	v_mfma_f32_16x16x32_bf16 v[122:125], v[212:215], v[158:161], v[122:125]
	v_mfma_f32_16x16x32_bf16 v[106:109], v[212:215], v[166:169], v[106:109]
	v_mfma_f32_16x16x32_bf16 v[118:121], v[220:223], v[158:161], v[118:121]
	v_mfma_f32_16x16x32_bf16 v[102:105], v[220:223], v[166:169], v[102:105]
	v_mfma_f32_16x16x32_bf16 v[114:117], v[228:231], v[158:161], v[114:117]
	v_mfma_f32_16x16x32_bf16 v[94:97], v[228:231], v[166:169], v[94:97]
	s_setprio 0
	s_setprio 1
	v_mfma_f32_16x16x32_bf16 v[74:77], v[186:189], v[170:173], v[74:77]
	v_mfma_f32_16x16x32_bf16 v[34:37], v[186:189], v[178:181], v[34:37]
	v_mfma_f32_16x16x32_bf16 v[62:65], v[208:211], v[170:173], v[62:65]
	v_mfma_f32_16x16x32_bf16 v[24:27], v[208:211], v[178:181], v[24:27]
	v_mfma_f32_16x16x32_bf16 v[54:57], v[216:219], v[170:173], v[54:57]
	v_mfma_f32_16x16x32_bf16 v[20:23], v[216:219], v[178:181], v[20:23]
	v_mfma_f32_16x16x32_bf16 v[38:41], v[224:227], v[170:173], v[38:41]
	v_mfma_f32_16x16x32_bf16 v[12:15], v[224:227], v[178:181], v[12:15]
	v_mfma_f32_16x16x32_bf16 v[74:77], v[204:207], v[174:177], v[74:77]
	v_mfma_f32_16x16x32_bf16 v[34:37], v[204:207], v[182:185], v[34:37]
	v_mfma_f32_16x16x32_bf16 v[62:65], v[212:215], v[174:177], v[62:65]
	v_mfma_f32_16x16x32_bf16 v[24:27], v[212:215], v[182:185], v[24:27]
	v_mfma_f32_16x16x32_bf16 v[54:57], v[220:223], v[174:177], v[54:57]
	v_mfma_f32_16x16x32_bf16 v[20:23], v[220:223], v[182:185], v[20:23]
	v_mfma_f32_16x16x32_bf16 v[38:41], v[228:231], v[174:177], v[38:41]
	v_mfma_f32_16x16x32_bf16 v[12:15], v[228:231], v[182:185], v[12:15]
	s_setprio 0
	s_barrier
; #define STAGE(bufoff, GB) do { const char* g_ = (GB); \
;         _Pragma("unroll") for (int i_ = 0; i_ < 2; ++i_) __builtin_amdgcn_global_load_lds((const unsigned*)(g_ + voff[i_]), (LAS3 unsigned*)(L + (bufoff) + stoff + i_ * 8192), 16, 0, 0); } while (0)
; #define LDA(dst, b, h) do { _Pragma("unroll") for (int m = 0; m < 4; ++m) _Pragma("unroll") for (int k = 0; k < 2; ++k) dst[m][k] = *(const LAS3 bf16x8*)(L + SA(b, h) + aoff + m * 2048 + k * 1024); } while (0)
; #define WAIT_V(n) asm volatile("s_waitcnt vmcnt(" #n ")" ::: "memory")
; #define WAIT_L(n) asm volatile("s_waitcnt lgkmcnt(" #n ")" ::: "memory")
; #define BAR __builtin_amdgcn_s_barrier()
; #define SCHED __builtin_amdgcn_sched_barrier(0)
; template <int EPI>
; DI void gemm_phase(const bf16_t* __restrict__ A, const bf16_t* __restrict__ Bt, const int K, const int N, const Params& p, const int layer_j, char* lds) {
;     ...
;             LDA(At, 1, 1); STAGE(SB(1, 0), b3); STAGE(SB(1, 1), b3 + hstep); STAGE(SA(1, 0), a3);
;             WAIT_V(8); WAIT_L(0); BAR; MMA(1, 0, At, B0); MMA(1, 1, At, B1); BAR; SCHED;
;         }
	v_readfirstlane_b32 s30, v148
	v_lshl_add_u64 v[136:137], v[136:137], 0, s[94:95]
	s_mov_b32 m0, s30
	v_readfirstlane_b32 s30, v149
	s_add_u32 s28, s28, 0x40080
	ds_read_b128 v[186:189], v139 offset:49152
	ds_read_b128 v[204:207], v139 offset:50176
	ds_read_b128 v[208:211], v139 offset:51200
	ds_read_b128 v[212:215], v139 offset:52224
	ds_read_b128 v[216:219], v139 offset:53248
	ds_read_b128 v[220:223], v139 offset:54272
	ds_read_b128 v[224:227], v139 offset:55296
	ds_read_b128 v[228:231], v139 offset:56320
	global_load_lds_dwordx4 v[136:137], off
	v_lshl_add_u64 v[136:137], v[190:191], 0, s[94:95]
	s_mov_b32 m0, s30
	s_addc_u32 s29, s29, 0
	v_readfirstlane_b32 s30, v152
	global_load_lds_dwordx4 v[136:137], off
	v_lshl_add_u64 v[136:137], s[28:29], 0, v[32:33]
	s_mov_b32 m0, s30
	s_nop 0
	global_load_lds_dwordx4 v[136:137], off
	v_lshl_add_u64 v[136:137], s[28:29], 0, v[130:131]
	v_readfirstlane_b32 s28, v153
	s_mov_b32 m0, s28
	v_readfirstlane_b32 s28, v150
	global_load_lds_dwordx4 v[136:137], off
	v_lshl_add_u64 v[136:137], v[194:195], 0, s[94:95]
	s_mov_b32 m0, s28
	v_readfirstlane_b32 s28, v151
	global_load_lds_dwordx4 v[136:137], off
	v_lshl_add_u64 v[136:137], v[232:233], 0, s[94:95]
	s_mov_b32 m0, s28
	s_nop 0
	global_load_lds_dwordx4 v[136:137], off
	s_waitcnt vmcnt(8)
	s_waitcnt lgkmcnt(0)
	s_barrier
	s_setprio 1
	s_waitcnt lgkmcnt(0)
	v_mfma_f32_16x16x32_bf16 v[98:101], v[186:189], v[154:157], v[98:101]
	v_mfma_f32_16x16x32_bf16 v[66:69], v[186:189], v[162:165], v[66:69]
	v_mfma_f32_16x16x32_bf16 v[90:93], v[208:211], v[154:157], v[90:93]
	v_mfma_f32_16x16x32_bf16 v[58:61], v[208:211], v[162:165], v[58:61]
	v_mfma_f32_16x16x32_bf16 v[86:89], v[216:219], v[154:157], v[86:89]
	v_mfma_f32_16x16x32_bf16 v[42:45], v[216:219], v[162:165], v[42:45]
	v_mfma_f32_16x16x32_bf16 v[70:73], v[224:227], v[154:157], v[70:73]
	v_mfma_f32_16x16x32_bf16 v[28:31], v[224:227], v[162:165], v[28:31]
	v_mfma_f32_16x16x32_bf16 v[98:101], v[204:207], v[158:161], v[98:101]
	v_mfma_f32_16x16x32_bf16 v[66:69], v[204:207], v[166:169], v[66:69]
	v_mfma_f32_16x16x32_bf16 v[90:93], v[212:215], v[158:161], v[90:93]
	v_mfma_f32_16x16x32_bf16 v[58:61], v[212:215], v[166:169], v[58:61]
	v_mfma_f32_16x16x32_bf16 v[86:89], v[220:223], v[158:161], v[86:89]
	v_mfma_f32_16x16x32_bf16 v[42:45], v[220:223], v[166:169], v[42:45]
	v_mfma_f32_16x16x32_bf16 v[70:73], v[228:231], v[158:161], v[70:73]
	v_mfma_f32_16x16x32_bf16 v[28:31], v[228:231], v[166:169], v[28:31]
	s_setprio 0
	s_setprio 1
	v_mfma_f32_16x16x32_bf16 v[16:19], v[186:189], v[170:173], v[16:19]
	v_mfma_f32_16x16x32_bf16 v[4:7], v[186:189], v[178:181], v[4:7]
	v_mfma_f32_16x16x32_bf16 v[8:11], v[208:211], v[170:173], v[8:11]
	v_mfma_f32_16x16x32_bf16 v[0:3], v[208:211], v[178:181], v[0:3]
	v_mfma_f32_16x16x32_bf16 v[78:81], v[216:219], v[170:173], v[78:81]
	v_mfma_f32_16x16x32_bf16 v[46:49], v[216:219], v[178:181], v[46:49]
	v_mfma_f32_16x16x32_bf16 v[82:85], v[224:227], v[170:173], v[82:85]
	v_mfma_f32_16x16x32_bf16 v[50:53], v[224:227], v[178:181], v[50:53]
	v_mfma_f32_16x16x32_bf16 v[16:19], v[204:207], v[174:177], v[16:19]
	v_mfma_f32_16x16x32_bf16 v[4:7], v[204:207], v[182:185], v[4:7]
	v_mfma_f32_16x16x32_bf16 v[8:11], v[212:215], v[174:177], v[8:11]
	v_mfma_f32_16x16x32_bf16 v[0:3], v[212:215], v[182:185], v[0:3]
	v_mfma_f32_16x16x32_bf16 v[78:81], v[220:223], v[174:177], v[78:81]
	v_mfma_f32_16x16x32_bf16 v[46:49], v[220:223], v[182:185], v[46:49]
	v_mfma_f32_16x16x32_bf16 v[82:85], v[228:231], v[174:177], v[82:85]
	v_mfma_f32_16x16x32_bf16 v[50:53], v[228:231], v[182:185], v[50:53]
	s_setprio 0
	s_barrier
	s_add_i32 s87, s87, 2
	s_add_u32 s26, s26, 0x100
	s_addc_u32 s27, s27, 0
	s_cmp_gt_u32 s87, 13
	s_cbranch_scc0 .Latt_kloop_ns

; DI bf16_t f2bf(float a) { return (bf16_t)(pk_bf16(a, 0.f) & 0xffffu); }
; template <int EPI>
; DI void gemm_phase(const bf16_t* __restrict__ A, const bf16_t* __restrict__ Bt, const int K, const int N, const Params& p, const int layer_j, char* lds) {
;     ...
;             } else {
;                 const float sc = (region == 0 || region == 3) ? 0.125f * LOG2E : 1.0f;
;                 const float* cb = (const float*)(ws + OFF_ROPE) + (row0 & 2047) * 32 + fr;
;                 bf16_t* dst = PROJ + (size_t)row0 * ATT_IN + col0 + fr;
; #pragma unroll
;                 for (int ai = 0; ai < 2; ++ai)
; #pragma unroll
;                     for (int m = 0; m < 4; ++m)
; #pragma unroll
;                         for (int j = 0; j < 4; ++j)
; #pragma unroll
;                             for (int n = 0; n < 2; ++n) {
;                                 const int ro = ai * 128 + m * 16 + j;
;                                 const float c = cb[ro * 32 + n * 16], sn = cb[2048 * 32 + ro * 32 + n * 16];
;                                 const float x1 = acc[ai][0][m][n][j], x2 = acc[ai][1][m][n][j];
;                                 dst[(size_t)ro * ATT_IN + n * 16] = f2bf((x1 * c - x2 * sn) * sc); dst[(size_t)ro * ATT_IN + 32 + n * 16] = f2bf((x2 * c + x1 * sn) * sc);
;                                 if (n == 1 && (j & 1)) __builtin_amdgcn_sched_barrier(0); }
.Latt_epi_rope:
	v_mbcnt_lo_u32_b32 v204, -1, 0
	v_mbcnt_hi_u32_b32 v204, -1, v204
	s_mul_i32 s26, s71, 34
	s_add_i32 s26, s26, 0x20100
	v_and_b32_e32 v205, 15, v204
	v_lshrrev_b32_e32 v206, 4, v204
	v_mul_u32_u24_e32 v205, 136, v205
	v_lshl_add_u32 v205, v206, 3, v205
	v_add_u32_e32 v205, s26, v205
	v_lshrrev_b32_e32 v207, 3, v204
	v_and_b32_e32 v208, 7, v204
	v_mul_u32_u24_e32 v206, 136, v207
	v_lshl_add_u32 v206, v208, 4, v206
	v_add_u32_e32 v206, s26, v206
	v_readlane_b32 s26, v254, 7
	v_readlane_b32 s27, v254, 14
	v_lshlrev_b32_e32 v208, 4, v208
	v_add_u32_e32 v207, s26, v207
	s_lshl_b32 s27, s27, 1
	s_mov_b32 s26, 6144
	v_mad_u32_u24 v207, v207, s26, v208
	v_add_u32_e32 v207, s27, v207
	v_add_u32_e32 v208, 0xc000, v207
	v_readlane_b32 s26, v254, 7
	v_and_b32_e32 v211, 15, v204
	v_lshrrev_b32_e32 v212, 4, v204
	v_add_u32_e32 v211, s26, v211
	v_lshlrev_b32_e32 v211, 7, v211
	v_lshl_add_u32 v211, v212, 4, v211
	s_and_b32 s26, s22, 7
	s_lshl_b32 s26, s26, 15
	s_add_u32 s26, s10, s26
	s_addc_u32 s27, s11, 0
	s_add_u32 s28, s26, 0x40000
	s_addc_u32 s29, s27, 0
	s_mul_i32 s30, s22, 0x180000
	s_mul_hi_u32 s31, s22, 0x180000
	s_lshl_b32 s13, s24, 9
	s_add_u32 s30, s30, s13
	s_addc_u32 s31, s31, 0
	s_add_u32 s30, s30, s8
	s_addc_u32 s31, s31, s9
	s_cmp_lt_u32 s24, 2
	s_cselect_b32 s13, 0x3e38aa3b, 1.0
	s_cmp_eq_u32 s15, 3
	s_cselect_b32 s13, 0x3e38aa3b, s13
	global_load_dwordx4 v[154:157], v211, s[26:27]
	global_load_dwordx4 v[158:161], v211, s[26:27] offset:64
	global_load_dwordx4 v[162:165], v211, s[28:29]
	global_load_dwordx4 v[166:169], v211, s[28:29] offset:64
	v_add_u32_e32 v212, 0x800, v211
	global_load_dwordx4 v[170:173], v212, s[26:27]
	global_load_dwordx4 v[174:177], v212, s[26:27] offset:64
	global_load_dwordx4 v[178:181], v212, s[28:29]
	global_load_dwordx4 v[182:185], v212, s[28:29] offset:64
	s_waitcnt vmcnt(4)
	v_mul_f32_e32 v186, v74, v162
	v_mul_f32_e32 v187, v75, v163
	v_mul_f32_e32 v188, v76, v164
	v_mul_f32_e32 v189, v77, v165
	v_mul_f32_e32 v190, v74, v154
	v_mul_f32_e32 v136, v75, v155
	v_mul_f32_e32 v137, v76, v156
	v_mul_f32_e32 v213, v77, v157
	v_fma_f32 v74, v126, v162, v190
	v_fma_f32 v75, v127, v163, v136
	v_fma_f32 v76, v128, v164, v137
	v_fma_f32 v77, v129, v165, v213
	v_fma_f32 v126, v126, v154, -v186
	v_fma_f32 v127, v127, v155, -v187
	v_fma_f32 v128, v128, v156, -v188
	v_fma_f32 v129, v129, v157, -v189
	v_mul_f32_e32 v126, s13, v126
	v_mul_f32_e32 v127, s13, v127
	v_mul_f32_e32 v128, s13, v128
	v_mul_f32_e32 v129, s13, v129
	v_mul_f32_e32 v74, s13, v74
	v_mul_f32_e32 v75, s13, v75
	v_mul_f32_e32 v76, s13, v76
	v_mul_f32_e32 v77, s13, v77
	v_mul_f32_e32 v186, v34, v166
	v_mul_f32_e32 v187, v35, v167
	v_mul_f32_e32 v188, v36, v168
	v_mul_f32_e32 v189, v37, v169
	v_mul_f32_e32 v190, v34, v158
	v_mul_f32_e32 v136, v35, v159
	v_mul_f32_e32 v137, v36, v160
	v_mul_f32_e32 v213, v37, v161
	v_fma_f32 v34, v110, v166, v190
	v_fma_f32 v35, v111, v167, v136
	v_fma_f32 v36, v112, v168, v137
	v_fma_f32 v37, v113, v169, v213
	v_fma_f32 v110, v110, v158, -v186
	v_fma_f32 v111, v111, v159, -v187
	v_fma_f32 v112, v112, v160, -v188
	v_fma_f32 v113, v113, v161, -v189
	v_mul_f32_e32 v110, s13, v110
	v_mul_f32_e32 v111, s13, v111
	v_mul_f32_e32 v112, s13, v112
	v_mul_f32_e32 v113, s13, v113
	v_mul_f32_e32 v34, s13, v34
	v_mul_f32_e32 v35, s13, v35
	v_mul_f32_e32 v36, s13, v36
	v_mul_f32_e32 v37, s13, v37
	v_add_u32_e32 v212, 0x1000, v211
	global_load_dwordx4 v[154:157], v212, s[26:27]
	global_load_dwordx4 v[158:161], v212, s[26:27] offset:64
	global_load_dwordx4 v[162:165], v212, s[28:29]
	global_load_dwordx4 v[166:169], v212, s[28:29] offset:64
	s_waitcnt vmcnt(4)
	v_mul_f32_e32 v186, v62, v178
	v_mul_f32_e32 v187, v63, v179
	v_mul_f32_e32 v188, v64, v180
	v_mul_f32_e32 v189, v65, v181
	v_mul_f32_e32 v190, v62, v170
	v_mul_f32_e32 v136, v63, v171
	v_mul_f32_e32 v137, v64, v172
	v_mul_f32_e32 v213, v65, v173
	v_fma_f32 v62, v122, v178, v190
	v_fma_f32 v63, v123, v179, v136
	v_fma_f32 v64, v124, v180, v137
	v_fma_f32 v65, v125, v181, v213
	v_fma_f32 v122, v122, v170, -v186
	v_fma_f32 v123, v123, v171, -v187
	v_fma_f32 v124, v124, v172, -v188
	v_fma_f32 v125, v125, v173, -v189
	v_mul_f32_e32 v122, s13, v122
	v_mul_f32_e32 v123, s13, v123
	v_mul_f32_e32 v124, s13, v124
	v_mul_f32_e32 v125, s13, v125
	v_mul_f32_e32 v62, s13, v62
	v_mul_f32_e32 v63, s13, v63
	v_mul_f32_e32 v64, s13, v64
	v_mul_f32_e32 v65, s13, v65
	v_mul_f32_e32 v186, v24, v182
	v_mul_f32_e32 v187, v25, v183
	v_mul_f32_e32 v188, v26, v184
	v_mul_f32_e32 v189, v27, v185
	v_mul_f32_e32 v190, v24, v174
	v_mul_f32_e32 v136, v25, v175
	v_mul_f32_e32 v137, v26, v176
	v_mul_f32_e32 v213, v27, v177
	v_fma_f32 v24, v106, v182, v190
	v_fma_f32 v25, v107, v183, v136
	v_fma_f32 v26, v108, v184, v137
	v_fma_f32 v27, v109, v185, v213
	v_fma_f32 v106, v106, v174, -v186
	v_fma_f32 v107, v107, v175, -v187
	v_fma_f32 v108, v108, v176, -v188
	v_fma_f32 v109, v109, v177, -v189
	v_mul_f32_e32 v106, s13, v106
	v_mul_f32_e32 v107, s13, v107
	v_mul_f32_e32 v108, s13, v108
	v_mul_f32_e32 v109, s13, v109
	v_mul_f32_e32 v24, s13, v24
	v_mul_f32_e32 v25, s13, v25
	v_mul_f32_e32 v26, s13, v26
	v_mul_f32_e32 v27, s13, v27
	v_add_u32_e32 v212, 0x1800, v211
	global_load_dwordx4 v[170:173], v212, s[26:27]
	global_load_dwordx4 v[174:177], v212, s[26:27] offset:64
	global_load_dwordx4 v[178:181], v212, s[28:29]
	global_load_dwordx4 v[182:185], v212, s[28:29] offset:64
	s_waitcnt vmcnt(4)
; DI bf16_t f2bf(float a) { return (bf16_t)(pk_bf16(a, 0.f) & 0xffffu); }
; template <int EPI>
; DI void gemm_phase(const bf16_t* __restrict__ A, const bf16_t* __restrict__ Bt, const int K, const int N, const Params& p, const int layer_j, char* lds) {
;     ...
; #pragma unroll
;                 for (int ai = 0; ai < 2; ++ai)
; #pragma unroll
;                     for (int m = 0; m < 4; ++m)
; #pragma unroll
;                         for (int j = 0; j < 4; ++j)
; #pragma unroll
;                             for (int n = 0; n < 2; ++n) {
;                                 const int ro = ai * 128 + m * 16 + j;
;                                 const float c = cb[ro * 32 + n * 16], sn = cb[2048 * 32 + ro * 32 + n * 16];
;                                 const float x1 = acc[ai][0][m][n][j], x2 = acc[ai][1][m][n][j];
;                                 dst[(size_t)ro * ATT_IN + n * 16] = f2bf((x1 * c - x2 * sn) * sc); dst[(size_t)ro * ATT_IN + 32 + n * 16] = f2bf((x2 * c + x1 * sn) * sc);
;                                 if (n == 1 && (j & 1)) __builtin_amdgcn_sched_barrier(0); }
	v_mul_f32_e32 v186, v54, v162
	v_mul_f32_e32 v187, v55, v163
	v_mul_f32_e32 v188, v56, v164
	v_mul_f32_e32 v189, v57, v165
	v_mul_f32_e32 v190, v54, v154
	v_mul_f32_e32 v136, v55, v155
	v_mul_f32_e32 v137, v56, v156
	v_mul_f32_e32 v213, v57, v157
	v_fma_f32 v54, v118, v162, v190
	v_fma_f32 v55, v119, v163, v136
	v_fma_f32 v56, v120, v164, v137
	v_fma_f32 v57, v121, v165, v213
	v_fma_f32 v118, v118, v154, -v186
	v_fma_f32 v119, v119, v155, -v187
	v_fma_f32 v120, v120, v156, -v188
	v_fma_f32 v121, v121, v157, -v189
	v_mul_f32_e32 v118, s13, v118
	v_mul_f32_e32 v119, s13, v119
	v_mul_f32_e32 v120, s13, v120
	v_mul_f32_e32 v121, s13, v121
	v_mul_f32_e32 v54, s13, v54
	v_mul_f32_e32 v55, s13, v55
	v_mul_f32_e32 v56, s13, v56
	v_mul_f32_e32 v57, s13, v57
	v_mul_f32_e32 v186, v20, v166
	v_mul_f32_e32 v187, v21, v167
	v_mul_f32_e32 v188, v22, v168
	v_mul_f32_e32 v189, v23, v169
	v_mul_f32_e32 v190, v20, v158
	v_mul_f32_e32 v136, v21, v159
	v_mul_f32_e32 v137, v22, v160
	v_mul_f32_e32 v213, v23, v161
	v_fma_f32 v20, v102, v166, v190
	v_fma_f32 v21, v103, v167, v136
	v_fma_f32 v22, v104, v168, v137
	v_fma_f32 v23, v105, v169, v213
	v_fma_f32 v102, v102, v158, -v186
	v_fma_f32 v103, v103, v159, -v187
	v_fma_f32 v104, v104, v160, -v188
	v_fma_f32 v105, v105, v161, -v189
	v_mul_f32_e32 v102, s13, v102
	v_mul_f32_e32 v103, s13, v103
	v_mul_f32_e32 v104, s13, v104
	v_mul_f32_e32 v105, s13, v105
	v_mul_f32_e32 v20, s13, v20
	v_mul_f32_e32 v21, s13, v21
	v_mul_f32_e32 v22, s13, v22
	v_mul_f32_e32 v23, s13, v23
	v_add_u32_e32 v212, 0x4000, v211
	global_load_dwordx4 v[154:157], v212, s[26:27]
	global_load_dwordx4 v[158:161], v212, s[26:27] offset:64
	global_load_dwordx4 v[162:165], v212, s[28:29]
	global_load_dwordx4 v[166:169], v212, s[28:29] offset:64
	s_waitcnt vmcnt(4)
	v_mul_f32_e32 v186, v38, v178
	v_mul_f32_e32 v187, v39, v179
	v_mul_f32_e32 v188, v40, v180
	v_mul_f32_e32 v189, v41, v181
	v_mul_f32_e32 v190, v38, v170
	v_mul_f32_e32 v136, v39, v171
	v_mul_f32_e32 v137, v40, v172
	v_mul_f32_e32 v213, v41, v173
	v_fma_f32 v38, v114, v178, v190
	v_fma_f32 v39, v115, v179, v136
	v_fma_f32 v40, v116, v180, v137
	v_fma_f32 v41, v117, v181, v213
	v_fma_f32 v114, v114, v170, -v186
	v_fma_f32 v115, v115, v171, -v187
	v_fma_f32 v116, v116, v172, -v188
	v_fma_f32 v117, v117, v173, -v189
	v_mul_f32_e32 v114, s13, v114
	v_mul_f32_e32 v115, s13, v115
	v_mul_f32_e32 v116, s13, v116
	v_mul_f32_e32 v117, s13, v117
	v_mul_f32_e32 v38, s13, v38
	v_mul_f32_e32 v39, s13, v39
	v_mul_f32_e32 v40, s13, v40
	v_mul_f32_e32 v41, s13, v41
	v_mul_f32_e32 v186, v12, v182
	v_mul_f32_e32 v187, v13, v183
	v_mul_f32_e32 v188, v14, v184
	v_mul_f32_e32 v189, v15, v185
	v_mul_f32_e32 v190, v12, v174
	v_mul_f32_e32 v136, v13, v175
	v_mul_f32_e32 v137, v14, v176
	v_mul_f32_e32 v213, v15, v177
	v_fma_f32 v12, v94, v182, v190
	v_fma_f32 v13, v95, v183, v136
	v_fma_f32 v14, v96, v184, v137
	v_fma_f32 v15, v97, v185, v213
	v_fma_f32 v94, v94, v174, -v186
	v_fma_f32 v95, v95, v175, -v187
	v_fma_f32 v96, v96, v176, -v188
	v_fma_f32 v97, v97, v177, -v189
	v_mul_f32_e32 v94, s13, v94
	v_mul_f32_e32 v95, s13, v95
	v_mul_f32_e32 v96, s13, v96
	v_mul_f32_e32 v97, s13, v97
	v_mul_f32_e32 v12, s13, v12
	v_mul_f32_e32 v13, s13, v13
	v_mul_f32_e32 v14, s13, v14
	v_mul_f32_e32 v15, s13, v15
	v_add_u32_e32 v212, 0x4800, v211
	global_load_dwordx4 v[170:173], v212, s[26:27]
	global_load_dwordx4 v[174:177], v212, s[26:27] offset:64
	global_load_dwordx4 v[178:181], v212, s[28:29]
	global_load_dwordx4 v[182:185], v212, s[28:29] offset:64
	s_waitcnt vmcnt(4)
	v_mul_f32_e32 v186, v16, v162
	v_mul_f32_e32 v187, v17, v163
	v_mul_f32_e32 v188, v18, v164
	v_mul_f32_e32 v189, v19, v165
	v_mul_f32_e32 v190, v16, v154
	v_mul_f32_e32 v136, v17, v155
	v_mul_f32_e32 v137, v18, v156
	v_mul_f32_e32 v213, v19, v157
	v_fma_f32 v16, v98, v162, v190
	v_fma_f32 v17, v99, v163, v136
	v_fma_f32 v18, v100, v164, v137
	v_fma_f32 v19, v101, v165, v213
	v_fma_f32 v98, v98, v154, -v186
	v_fma_f32 v99, v99, v155, -v187
	v_fma_f32 v100, v100, v156, -v188
	v_fma_f32 v101, v101, v157, -v189
	v_mul_f32_e32 v98, s13, v98
	v_mul_f32_e32 v99, s13, v99
	v_mul_f32_e32 v100, s13, v100
	v_mul_f32_e32 v101, s13, v101
	v_mul_f32_e32 v16, s13, v16
	v_mul_f32_e32 v17, s13, v17
	v_mul_f32_e32 v18, s13, v18
	v_mul_f32_e32 v19, s13, v19
	v_mul_f32_e32 v186, v4, v166
	v_mul_f32_e32 v187, v5, v167
	v_mul_f32_e32 v188, v6, v168
	v_mul_f32_e32 v189, v7, v169
	v_mul_f32_e32 v190, v4, v158
	v_mul_f32_e32 v136, v5, v159
	v_mul_f32_e32 v137, v6, v160
	v_mul_f32_e32 v213, v7, v161
	v_fma_f32 v4, v66, v166, v190
	v_fma_f32 v5, v67, v167, v136
	v_fma_f32 v6, v68, v168, v137
	v_fma_f32 v7, v69, v169, v213
	v_fma_f32 v66, v66, v158, -v186
	v_fma_f32 v67, v67, v159, -v187
	v_fma_f32 v68, v68, v160, -v188
	v_fma_f32 v69, v69, v161, -v189
	v_mul_f32_e32 v66, s13, v66
	v_mul_f32_e32 v67, s13, v67
	v_mul_f32_e32 v68, s13, v68
	v_mul_f32_e32 v69, s13, v69
	v_mul_f32_e32 v4, s13, v4
	v_mul_f32_e32 v5, s13, v5
	v_mul_f32_e32 v6, s13, v6
	v_mul_f32_e32 v7, s13, v7
	v_add_u32_e32 v212, 0x5000, v211
	global_load_dwordx4 v[154:157], v212, s[26:27]
	global_load_dwordx4 v[158:161], v212, s[26:27] offset:64
	global_load_dwordx4 v[162:165], v212, s[28:29]
	global_load_dwordx4 v[166:169], v212, s[28:29] offset:64
	s_waitcnt vmcnt(4)
; DI bf16_t f2bf(float a) { return (bf16_t)(pk_bf16(a, 0.f) & 0xffffu); }
; template <int EPI>
; DI void gemm_phase(const bf16_t* __restrict__ A, const bf16_t* __restrict__ Bt, const int K, const int N, const Params& p, const int layer_j, char* lds) {
;     ...
; #pragma unroll
;                 for (int ai = 0; ai < 2; ++ai)
; #pragma unroll
;                     for (int m = 0; m < 4; ++m)
; #pragma unroll
;                         for (int j = 0; j < 4; ++j)
; #pragma unroll
;                             for (int n = 0; n < 2; ++n) {
;                                 const int ro = ai * 128 + m * 16 + j;
;                                 const float c = cb[ro * 32 + n * 16], sn = cb[2048 * 32 + ro * 32 + n * 16];
;                                 const float x1 = acc[ai][0][m][n][j], x2 = acc[ai][1][m][n][j];
;                                 dst[(size_t)ro * ATT_IN + n * 16] = f2bf((x1 * c - x2 * sn) * sc); dst[(size_t)ro * ATT_IN + 32 + n * 16] = f2bf((x2 * c + x1 * sn) * sc);
;                                 if (n == 1 && (j & 1)) __builtin_amdgcn_sched_barrier(0); }
	v_mul_f32_e32 v186, v8, v178
	v_mul_f32_e32 v187, v9, v179
	v_mul_f32_e32 v188, v10, v180
	v_mul_f32_e32 v189, v11, v181
	v_mul_f32_e32 v190, v8, v170
	v_mul_f32_e32 v136, v9, v171
	v_mul_f32_e32 v137, v10, v172
	v_mul_f32_e32 v213, v11, v173
	v_fma_f32 v8, v90, v178, v190
	v_fma_f32 v9, v91, v179, v136
	v_fma_f32 v10, v92, v180, v137
	v_fma_f32 v11, v93, v181, v213
	v_fma_f32 v90, v90, v170, -v186
	v_fma_f32 v91, v91, v171, -v187
	v_fma_f32 v92, v92, v172, -v188
	v_fma_f32 v93, v93, v173, -v189
	v_mul_f32_e32 v90, s13, v90
	v_mul_f32_e32 v91, s13, v91
	v_mul_f32_e32 v92, s13, v92
	v_mul_f32_e32 v93, s13, v93
	v_mul_f32_e32 v8, s13, v8
	v_mul_f32_e32 v9, s13, v9
	v_mul_f32_e32 v10, s13, v10
	v_mul_f32_e32 v11, s13, v11
	v_mul_f32_e32 v186, v0, v182
	v_mul_f32_e32 v187, v1, v183
	v_mul_f32_e32 v188, v2, v184
	v_mul_f32_e32 v189, v3, v185
	v_mul_f32_e32 v190, v0, v174
	v_mul_f32_e32 v136, v1, v175
	v_mul_f32_e32 v137, v2, v176
	v_mul_f32_e32 v213, v3, v177
	v_fma_f32 v0, v58, v182, v190
	v_fma_f32 v1, v59, v183, v136
	v_fma_f32 v2, v60, v184, v137
	v_fma_f32 v3, v61, v185, v213
	v_fma_f32 v58, v58, v174, -v186
	v_fma_f32 v59, v59, v175, -v187
	v_fma_f32 v60, v60, v176, -v188
	v_fma_f32 v61, v61, v177, -v189
	v_mul_f32_e32 v58, s13, v58
	v_mul_f32_e32 v59, s13, v59
	v_mul_f32_e32 v60, s13, v60
	v_mul_f32_e32 v61, s13, v61
	v_mul_f32_e32 v0, s13, v0
	v_mul_f32_e32 v1, s13, v1
	v_mul_f32_e32 v2, s13, v2
	v_mul_f32_e32 v3, s13, v3
	v_add_u32_e32 v212, 0x5800, v211
	global_load_dwordx4 v[170:173], v212, s[26:27]
	global_load_dwordx4 v[174:177], v212, s[26:27] offset:64
	global_load_dwordx4 v[178:181], v212, s[28:29]
	global_load_dwordx4 v[182:185], v212, s[28:29] offset:64
	s_waitcnt vmcnt(4)
	v_mul_f32_e32 v186, v78, v162
	v_mul_f32_e32 v187, v79, v163
	v_mul_f32_e32 v188, v80, v164
	v_mul_f32_e32 v189, v81, v165
	v_mul_f32_e32 v190, v78, v154
	v_mul_f32_e32 v136, v79, v155
	v_mul_f32_e32 v137, v80, v156
	v_mul_f32_e32 v213, v81, v157
	v_fma_f32 v78, v86, v162, v190
	v_fma_f32 v79, v87, v163, v136
	v_fma_f32 v80, v88, v164, v137
	v_fma_f32 v81, v89, v165, v213
	v_fma_f32 v86, v86, v154, -v186
	v_fma_f32 v87, v87, v155, -v187
	v_fma_f32 v88, v88, v156, -v188
	v_fma_f32 v89, v89, v157, -v189
	v_mul_f32_e32 v86, s13, v86
	v_mul_f32_e32 v87, s13, v87
	v_mul_f32_e32 v88, s13, v88
	v_mul_f32_e32 v89, s13, v89
	v_mul_f32_e32 v78, s13, v78
	v_mul_f32_e32 v79, s13, v79
	v_mul_f32_e32 v80, s13, v80
	v_mul_f32_e32 v81, s13, v81
	v_mul_f32_e32 v186, v46, v166
	v_mul_f32_e32 v187, v47, v167
	v_mul_f32_e32 v188, v48, v168
	v_mul_f32_e32 v189, v49, v169
	v_mul_f32_e32 v190, v46, v158
	v_mul_f32_e32 v136, v47, v159
	v_mul_f32_e32 v137, v48, v160
	v_mul_f32_e32 v213, v49, v161
	v_fma_f32 v46, v42, v166, v190
	v_fma_f32 v47, v43, v167, v136
	v_fma_f32 v48, v44, v168, v137
	v_fma_f32 v49, v45, v169, v213
	v_fma_f32 v42, v42, v158, -v186
	v_fma_f32 v43, v43, v159, -v187
	v_fma_f32 v44, v44, v160, -v188
	v_fma_f32 v45, v45, v161, -v189
	v_mul_f32_e32 v42, s13, v42
	v_mul_f32_e32 v43, s13, v43
	v_mul_f32_e32 v44, s13, v44
	v_mul_f32_e32 v45, s13, v45
	v_mul_f32_e32 v46, s13, v46
	v_mul_f32_e32 v47, s13, v47
	v_mul_f32_e32 v48, s13, v48
	v_mul_f32_e32 v49, s13, v49
	s_waitcnt vmcnt(0)
	v_mul_f32_e32 v186, v82, v178
	v_mul_f32_e32 v187, v83, v179
	v_mul_f32_e32 v188, v84, v180
	v_mul_f32_e32 v189, v85, v181
	v_mul_f32_e32 v190, v82, v170
	v_mul_f32_e32 v136, v83, v171
	v_mul_f32_e32 v137, v84, v172
	v_mul_f32_e32 v213, v85, v173
	v_fma_f32 v82, v70, v178, v190
	v_fma_f32 v83, v71, v179, v136
	v_fma_f32 v84, v72, v180, v137
	v_fma_f32 v85, v73, v181, v213
	v_fma_f32 v70, v70, v170, -v186
	v_fma_f32 v71, v71, v171, -v187
	v_fma_f32 v72, v72, v172, -v188
	v_fma_f32 v73, v73, v173, -v189
	v_mul_f32_e32 v70, s13, v70
	v_mul_f32_e32 v71, s13, v71
	v_mul_f32_e32 v72, s13, v72
	v_mul_f32_e32 v73, s13, v73
	v_mul_f32_e32 v82, s13, v82
	v_mul_f32_e32 v83, s13, v83
	v_mul_f32_e32 v84, s13, v84
	v_mul_f32_e32 v85, s13, v85
	v_mul_f32_e32 v186, v50, v182
	v_mul_f32_e32 v187, v51, v183
	v_mul_f32_e32 v188, v52, v184
	v_mul_f32_e32 v189, v53, v185
	v_mul_f32_e32 v190, v50, v174
	v_mul_f32_e32 v136, v51, v175
	v_mul_f32_e32 v137, v52, v176
	v_mul_f32_e32 v213, v53, v177
	v_fma_f32 v50, v28, v182, v190
	v_fma_f32 v51, v29, v183, v136
	v_fma_f32 v52, v30, v184, v137
	v_fma_f32 v53, v31, v185, v213
	v_fma_f32 v28, v28, v174, -v186
	v_fma_f32 v29, v29, v175, -v187
	v_fma_f32 v30, v30, v176, -v188
	v_fma_f32 v31, v31, v177, -v189
	v_mul_f32_e32 v28, s13, v28
	v_mul_f32_e32 v29, s13, v29
	v_mul_f32_e32 v30, s13, v30
	v_mul_f32_e32 v31, s13, v31
	v_mul_f32_e32 v50, s13, v50
	v_mul_f32_e32 v51, s13, v51
	v_mul_f32_e32 v52, s13, v52
	v_mul_f32_e32 v53, s13, v53
	v_cvt_pk_bf16_f32 v214, v126, v127
	v_cvt_pk_bf16_f32 v215, v128, v129
	v_cvt_pk_bf16_f32 v216, v110, v111
	v_cvt_pk_bf16_f32 v217, v112, v113
	v_cvt_pk_bf16_f32 v218, v74, v75
	v_cvt_pk_bf16_f32 v219, v76, v77
	v_cvt_pk_bf16_f32 v220, v34, v35
	v_cvt_pk_bf16_f32 v221, v36, v37
	ds_write_b64 v205, v[214:215]
	ds_write_b64 v205, v[216:217] offset:32
	ds_write_b64 v205, v[218:219] offset:64
	ds_write_b64 v205, v[220:221] offset:96
	ds_read2_b64 v[222:225], v206 offset1:1
	ds_read2_b64 v[226:229], v206 offset0:136 offset1:137
	s_waitcnt lgkmcnt(0)
	global_store_dwordx4 v207, v[222:225], s[30:31]
	global_store_dwordx4 v208, v[226:229], s[30:31]
	v_cvt_pk_bf16_f32 v214, v122, v123
	v_cvt_pk_bf16_f32 v215, v124, v125
	v_cvt_pk_bf16_f32 v216, v106, v107
	v_cvt_pk_bf16_f32 v217, v108, v109
	v_cvt_pk_bf16_f32 v218, v62, v63
	v_cvt_pk_bf16_f32 v219, v64, v65
	v_cvt_pk_bf16_f32 v220, v24, v25
	v_cvt_pk_bf16_f32 v221, v26, v27
	ds_write_b64 v205, v[214:215]
	ds_write_b64 v205, v[216:217] offset:32
	ds_write_b64 v205, v[218:219] offset:64
	ds_write_b64 v205, v[220:221] offset:96
	ds_read2_b64 v[222:225], v206 offset1:1
	ds_read2_b64 v[226:229], v206 offset0:136 offset1:137
	v_add_u32_e32 v209, 0x18000, v207
	v_add_u32_e32 v210, 0x18000, v208
	s_waitcnt lgkmcnt(0)
; DI bf16_t f2bf(float a) { return (bf16_t)(pk_bf16(a, 0.f) & 0xffffu); }
; template <int EPI>
; DI void gemm_phase(const bf16_t* __restrict__ A, const bf16_t* __restrict__ Bt, const int K, const int N, const Params& p, const int layer_j, char* lds) {
;     ...
;                 bf16_t* dst = PROJ + (size_t)row0 * ATT_IN + col0 + fr;
; #pragma unroll
;                 for (int ai = 0; ai < 2; ++ai)
; #pragma unroll
;                     for (int m = 0; m < 4; ++m)
; #pragma unroll
;                         for (int j = 0; j < 4; ++j)
; #pragma unroll
;                             for (int n = 0; n < 2; ++n) {
;                                 const int ro = ai * 128 + m * 16 + j;
;                                 const float c = cb[ro * 32 + n * 16], sn = cb[2048 * 32 + ro * 32 + n * 16];
;                                 const float x1 = acc[ai][0][m][n][j], x2 = acc[ai][1][m][n][j];
;                                 dst[(size_t)ro * ATT_IN + n * 16] = f2bf((x1 * c - x2 * sn) * sc); dst[(size_t)ro * ATT_IN + 32 + n * 16] = f2bf((x2 * c + x1 * sn) * sc);
;                                 if (n == 1 && (j & 1)) __builtin_amdgcn_sched_barrier(0); }
	global_store_dwordx4 v209, v[222:225], s[30:31]
	global_store_dwordx4 v210, v[226:229], s[30:31]
	v_cvt_pk_bf16_f32 v214, v118, v119
	v_cvt_pk_bf16_f32 v215, v120, v121
	v_cvt_pk_bf16_f32 v216, v102, v103
	v_cvt_pk_bf16_f32 v217, v104, v105
	v_cvt_pk_bf16_f32 v218, v54, v55
	v_cvt_pk_bf16_f32 v219, v56, v57
	v_cvt_pk_bf16_f32 v220, v20, v21
	v_cvt_pk_bf16_f32 v221, v22, v23
	ds_write_b64 v205, v[214:215]
	ds_write_b64 v205, v[216:217] offset:32
	ds_write_b64 v205, v[218:219] offset:64
	ds_write_b64 v205, v[220:221] offset:96
	ds_read2_b64 v[222:225], v206 offset1:1
	ds_read2_b64 v[226:229], v206 offset0:136 offset1:137
	v_add_u32_e32 v209, 0x30000, v207
	v_add_u32_e32 v210, 0x30000, v208
	s_waitcnt lgkmcnt(0)
	global_store_dwordx4 v209, v[222:225], s[30:31]
	global_store_dwordx4 v210, v[226:229], s[30:31]
	v_cvt_pk_bf16_f32 v214, v114, v115
	v_cvt_pk_bf16_f32 v215, v116, v117
	v_cvt_pk_bf16_f32 v216, v94, v95
	v_cvt_pk_bf16_f32 v217, v96, v97
	v_cvt_pk_bf16_f32 v218, v38, v39
	v_cvt_pk_bf16_f32 v219, v40, v41
	v_cvt_pk_bf16_f32 v220, v12, v13
	v_cvt_pk_bf16_f32 v221, v14, v15
	ds_write_b64 v205, v[214:215]
	ds_write_b64 v205, v[216:217] offset:32
	ds_write_b64 v205, v[218:219] offset:64
	ds_write_b64 v205, v[220:221] offset:96
	ds_read2_b64 v[222:225], v206 offset1:1
	ds_read2_b64 v[226:229], v206 offset0:136 offset1:137
	v_add_u32_e32 v209, 0x48000, v207
	v_add_u32_e32 v210, 0x48000, v208
	s_waitcnt lgkmcnt(0)
	global_store_dwordx4 v209, v[222:225], s[30:31]
	global_store_dwordx4 v210, v[226:229], s[30:31]
	v_cvt_pk_bf16_f32 v214, v98, v99
	v_cvt_pk_bf16_f32 v215, v100, v101
	v_cvt_pk_bf16_f32 v216, v66, v67
	v_cvt_pk_bf16_f32 v217, v68, v69
	v_cvt_pk_bf16_f32 v218, v16, v17
	v_cvt_pk_bf16_f32 v219, v18, v19
	v_cvt_pk_bf16_f32 v220, v4, v5
	v_cvt_pk_bf16_f32 v221, v6, v7
	ds_write_b64 v205, v[214:215]
	ds_write_b64 v205, v[216:217] offset:32
	ds_write_b64 v205, v[218:219] offset:64
	ds_write_b64 v205, v[220:221] offset:96
	ds_read2_b64 v[222:225], v206 offset1:1
	ds_read2_b64 v[226:229], v206 offset0:136 offset1:137
	v_add_u32_e32 v209, 0xc0000, v207
	v_add_u32_e32 v210, 0xc0000, v208
	s_waitcnt lgkmcnt(0)
	global_store_dwordx4 v209, v[222:225], s[30:31]
	global_store_dwordx4 v210, v[226:229], s[30:31]
	v_cvt_pk_bf16_f32 v214, v90, v91
	v_cvt_pk_bf16_f32 v215, v92, v93
	v_cvt_pk_bf16_f32 v216, v58, v59
	v_cvt_pk_bf16_f32 v217, v60, v61
	v_cvt_pk_bf16_f32 v218, v8, v9
	v_cvt_pk_bf16_f32 v219, v10, v11
	v_cvt_pk_bf16_f32 v220, v0, v1
	v_cvt_pk_bf16_f32 v221, v2, v3
	ds_write_b64 v205, v[214:215]
	ds_write_b64 v205, v[216:217] offset:32
	ds_write_b64 v205, v[218:219] offset:64
	ds_write_b64 v205, v[220:221] offset:96
	ds_read2_b64 v[222:225], v206 offset1:1
	ds_read2_b64 v[226:229], v206 offset0:136 offset1:137
	v_add_u32_e32 v209, 0xd8000, v207
	v_add_u32_e32 v210, 0xd8000, v208
	s_waitcnt lgkmcnt(0)
	global_store_dwordx4 v209, v[222:225], s[30:31]
	global_store_dwordx4 v210, v[226:229], s[30:31]
	v_cvt_pk_bf16_f32 v214, v86, v87
	v_cvt_pk_bf16_f32 v215, v88, v89
	v_cvt_pk_bf16_f32 v216, v42, v43
	v_cvt_pk_bf16_f32 v217, v44, v45
	v_cvt_pk_bf16_f32 v218, v78, v79
	v_cvt_pk_bf16_f32 v219, v80, v81
	v_cvt_pk_bf16_f32 v220, v46, v47
	v_cvt_pk_bf16_f32 v221, v48, v49
	ds_write_b64 v205, v[214:215]
	ds_write_b64 v205, v[216:217] offset:32
	ds_write_b64 v205, v[218:219] offset:64
	ds_write_b64 v205, v[220:221] offset:96
	ds_read2_b64 v[222:225], v206 offset1:1
	ds_read2_b64 v[226:229], v206 offset0:136 offset1:137
	v_add_u32_e32 v209, 0xf0000, v207
	v_add_u32_e32 v210, 0xf0000, v208
	s_waitcnt lgkmcnt(0)
	global_store_dwordx4 v209, v[222:225], s[30:31]
	global_store_dwordx4 v210, v[226:229], s[30:31]
	v_cvt_pk_bf16_f32 v214, v70, v71
	v_cvt_pk_bf16_f32 v215, v72, v73
	v_cvt_pk_bf16_f32 v216, v28, v29
	v_cvt_pk_bf16_f32 v217, v30, v31
	v_cvt_pk_bf16_f32 v218, v82, v83
	v_cvt_pk_bf16_f32 v219, v84, v85
	v_cvt_pk_bf16_f32 v220, v50, v51
	v_cvt_pk_bf16_f32 v221, v52, v53
	ds_write_b64 v205, v[214:215]
	ds_write_b64 v205, v[216:217] offset:32
	ds_write_b64 v205, v[218:219] offset:64
	ds_write_b64 v205, v[220:221] offset:96
	ds_read2_b64 v[222:225], v206 offset1:1
	ds_read2_b64 v[226:229], v206 offset0:136 offset1:137
	v_add_u32_e32 v209, 0x108000, v207
	v_add_u32_e32 v210, 0x108000, v208
	s_waitcnt lgkmcnt(0)
	global_store_dwordx4 v209, v[222:225], s[30:31]
	global_store_dwordx4 v210, v[226:229], s[30:31]
	s_waitcnt vmcnt(16)
	s_branch .LBB0_385
; DI unsigned pk_bf16(float a, float b) { f32x2_t v = {a, b}; bf16x2_t r = __builtin_convertvector(v, bf16x2_t); return __builtin_bit_cast(unsigned, r); }
; template <int EPI>
; DI void gemm_phase(const bf16_t* __restrict__ A, const bf16_t* __restrict__ Bt, const int K, const int N, const Params& p, const int layer_j, char* lds) {
;     ...
;             const int region = col0 >> 9;
;             if (region == 2 || region == 5) {
;                 const int vc0 = (region == 2 ? col0 - 1024 : 512 + col0 - 2560);
;                 const int b = row0 >> 11, t0 = row0 & 2047;
;                 bf16_t* dst = VT + ((size_t)(b * 1024 + vc0 + fr)) * SEQ + t0;
; #pragma unroll
;                 for (int bj = 0; bj < 2; ++bj)
; #pragma unroll
;                     for (int n = 0; n < 2; ++n)
; #pragma unroll
;                         for (int ai = 0; ai < 2; ++ai)
; #pragma unroll
;                             for (int m = 0; m < 4; ++m) { u32x2 o; o[0] = pk_bf16(acc[ai][bj][m][n][0], acc[ai][bj][m][n][1]); o[1] = pk_bf16(acc[ai][bj][m][n][2], acc[ai][bj][m][n][3]);
;                                 *(u32x2*)(dst + (size_t)(bj * 32 + n * 16) * SEQ + ai * 128 + m * 16) = o; }
.Latt_epi_tr:
	v_mbcnt_lo_u32_b32 v204, -1, 0
	v_mbcnt_hi_u32_b32 v204, -1, v204
	s_mul_i32 s26, s71, 34
	s_add_i32 s26, s26, 0x20100
	v_and_b32_e32 v205, 15, v204
	v_lshrrev_b32_e32 v206, 4, v204
	v_mul_u32_u24_e32 v205, 136, v205
	v_lshl_add_u32 v205, v206, 3, v205
	v_add_u32_e32 v205, s26, v205
	v_lshrrev_b32_e32 v207, 3, v204
	v_and_b32_e32 v208, 7, v204
	v_mul_u32_u24_e32 v206, 136, v207
	v_lshl_add_u32 v206, v208, 4, v206
	v_add_u32_e32 v206, s26, v206
	v_readlane_b32 s26, v254, 14
	v_readlane_b32 s27, v254, 7
	v_lshlrev_b32_e32 v208, 4, v208
	v_add_u32_e32 v207, s26, v207
	s_lshl_b32 s27, s27, 1
	s_mov_b32 s26, 4096
	v_mad_u32_u24 v207, v207, s26, v208
	v_add_u32_e32 v207, s27, v207
	v_add_u32_e32 v208, 0x8000, v207
	s_lshr_b32 s26, s22, 3
	s_lshl_b32 s26, s26, 10
	s_lshl_b32 s27, s24, 8
	s_add_i32 s26, s26, s27
	s_movk_i32 s27, 0x800
	s_cmp_eq_u32 s15, 2
	s_cselect_b32 s27, 0x400, s27
	s_sub_u32 s26, s26, s27
	s_lshl_b32 s26, s26, 12
	s_and_b32 s27, s22, 7
	s_lshl_b32 s27, s27, 9
	s_add_u32 s26, s26, s27
	s_add_u32 s30, s26, s6
	s_addc_u32 s31, s7, 0
	v_cvt_pk_bf16_f32 v214, v126, v127
	v_cvt_pk_bf16_f32 v215, v128, v129
	v_cvt_pk_bf16_f32 v216, v122, v123
	v_cvt_pk_bf16_f32 v217, v124, v125
	v_cvt_pk_bf16_f32 v218, v118, v119
	v_cvt_pk_bf16_f32 v219, v120, v121
	v_cvt_pk_bf16_f32 v220, v114, v115
	v_cvt_pk_bf16_f32 v221, v116, v117
	ds_write_b64 v205, v[214:215]
	ds_write_b64 v205, v[216:217] offset:32
	ds_write_b64 v205, v[218:219] offset:64
	ds_write_b64 v205, v[220:221] offset:96
	ds_read2_b64 v[222:225], v206 offset1:1
	ds_read2_b64 v[226:229], v206 offset0:136 offset1:137
	s_waitcnt lgkmcnt(0)
	global_store_dwordx4 v207, v[222:225], s[30:31]
	global_store_dwordx4 v208, v[226:229], s[30:31]
	v_cvt_pk_bf16_f32 v214, v98, v99
	v_cvt_pk_bf16_f32 v215, v100, v101
	v_cvt_pk_bf16_f32 v216, v90, v91
	v_cvt_pk_bf16_f32 v217, v92, v93
	v_cvt_pk_bf16_f32 v218, v86, v87
	v_cvt_pk_bf16_f32 v219, v88, v89
	v_cvt_pk_bf16_f32 v220, v70, v71
	v_cvt_pk_bf16_f32 v221, v72, v73
	ds_write_b64 v205, v[214:215]
	ds_write_b64 v205, v[216:217] offset:32
	ds_write_b64 v205, v[218:219] offset:64
	ds_write_b64 v205, v[220:221] offset:96
	ds_read2_b64 v[222:225], v206 offset1:1
	ds_read2_b64 v[226:229], v206 offset0:136 offset1:137
	v_add_u32_e32 v209, 0x100, v207
	v_add_u32_e32 v210, 0x100, v208
	s_waitcnt lgkmcnt(0)
	global_store_dwordx4 v209, v[222:225], s[30:31]
	global_store_dwordx4 v210, v[226:229], s[30:31]
	v_cvt_pk_bf16_f32 v214, v110, v111
	v_cvt_pk_bf16_f32 v215, v112, v113
	v_cvt_pk_bf16_f32 v216, v106, v107
	v_cvt_pk_bf16_f32 v217, v108, v109
	v_cvt_pk_bf16_f32 v218, v102, v103
	v_cvt_pk_bf16_f32 v219, v104, v105
	v_cvt_pk_bf16_f32 v220, v94, v95
	v_cvt_pk_bf16_f32 v221, v96, v97
	ds_write_b64 v205, v[214:215]
	ds_write_b64 v205, v[216:217] offset:32
	ds_write_b64 v205, v[218:219] offset:64
	ds_write_b64 v205, v[220:221] offset:96
	ds_read2_b64 v[222:225], v206 offset1:1
	ds_read2_b64 v[226:229], v206 offset0:136 offset1:137
	v_add_u32_e32 v209, 0x10000, v207
	v_add_u32_e32 v210, 0x10000, v208
	s_waitcnt lgkmcnt(0)
	global_store_dwordx4 v209, v[222:225], s[30:31]
	global_store_dwordx4 v210, v[226:229], s[30:31]
	v_cvt_pk_bf16_f32 v214, v66, v67
	v_cvt_pk_bf16_f32 v215, v68, v69
	v_cvt_pk_bf16_f32 v216, v58, v59
	v_cvt_pk_bf16_f32 v217, v60, v61
	v_cvt_pk_bf16_f32 v218, v42, v43
	v_cvt_pk_bf16_f32 v219, v44, v45
	v_cvt_pk_bf16_f32 v220, v28, v29
	v_cvt_pk_bf16_f32 v221, v30, v31
	ds_write_b64 v205, v[214:215]
	ds_write_b64 v205, v[216:217] offset:32
	ds_write_b64 v205, v[218:219] offset:64
	ds_write_b64 v205, v[220:221] offset:96
	ds_read2_b64 v[222:225], v206 offset1:1
	ds_read2_b64 v[226:229], v206 offset0:136 offset1:137
	v_add_u32_e32 v209, 0x10100, v207
	v_add_u32_e32 v210, 0x10100, v208
	s_waitcnt lgkmcnt(0)
	global_store_dwordx4 v209, v[222:225], s[30:31]
	global_store_dwordx4 v210, v[226:229], s[30:31]
	v_cvt_pk_bf16_f32 v214, v74, v75
	v_cvt_pk_bf16_f32 v215, v76, v77
	v_cvt_pk_bf16_f32 v216, v62, v63
	v_cvt_pk_bf16_f32 v217, v64, v65
	v_cvt_pk_bf16_f32 v218, v54, v55
	v_cvt_pk_bf16_f32 v219, v56, v57
	v_cvt_pk_bf16_f32 v220, v38, v39
	v_cvt_pk_bf16_f32 v221, v40, v41
	ds_write_b64 v205, v[214:215]
	ds_write_b64 v205, v[216:217] offset:32
	ds_write_b64 v205, v[218:219] offset:64
	ds_write_b64 v205, v[220:221] offset:96
	ds_read2_b64 v[222:225], v206 offset1:1
	ds_read2_b64 v[226:229], v206 offset0:136 offset1:137
	v_add_u32_e32 v209, 0x20000, v207
	v_add_u32_e32 v210, 0x20000, v208
	s_waitcnt lgkmcnt(0)
	global_store_dwordx4 v209, v[222:225], s[30:31]
	global_store_dwordx4 v210, v[226:229], s[30:31]
	v_cvt_pk_bf16_f32 v214, v16, v17
	v_cvt_pk_bf16_f32 v215, v18, v19
	v_cvt_pk_bf16_f32 v216, v8, v9
	v_cvt_pk_bf16_f32 v217, v10, v11
	v_cvt_pk_bf16_f32 v218, v78, v79
	v_cvt_pk_bf16_f32 v219, v80, v81
	v_cvt_pk_bf16_f32 v220, v82, v83
	v_cvt_pk_bf16_f32 v221, v84, v85
	ds_write_b64 v205, v[214:215]
	ds_write_b64 v205, v[216:217] offset:32
	ds_write_b64 v205, v[218:219] offset:64
	ds_write_b64 v205, v[220:221] offset:96
	ds_read2_b64 v[222:225], v206 offset1:1
	ds_read2_b64 v[226:229], v206 offset0:136 offset1:137
	v_add_u32_e32 v209, 0x20100, v207
	v_add_u32_e32 v210, 0x20100, v208
	s_waitcnt lgkmcnt(0)
	global_store_dwordx4 v209, v[222:225], s[30:31]
	global_store_dwordx4 v210, v[226:229], s[30:31]
	v_cvt_pk_bf16_f32 v214, v34, v35
	v_cvt_pk_bf16_f32 v215, v36, v37
	v_cvt_pk_bf16_f32 v216, v24, v25
	v_cvt_pk_bf16_f32 v217, v26, v27
	v_cvt_pk_bf16_f32 v218, v20, v21
	v_cvt_pk_bf16_f32 v219, v22, v23
	v_cvt_pk_bf16_f32 v220, v12, v13
	v_cvt_pk_bf16_f32 v221, v14, v15
	ds_write_b64 v205, v[214:215]
	ds_write_b64 v205, v[216:217] offset:32
	ds_write_b64 v205, v[218:219] offset:64
	ds_write_b64 v205, v[220:221] offset:96
	ds_read2_b64 v[222:225], v206 offset1:1
	ds_read2_b64 v[226:229], v206 offset0:136 offset1:137
	v_add_u32_e32 v209, 0x30000, v207
	v_add_u32_e32 v210, 0x30000, v208
	s_waitcnt lgkmcnt(0)
	global_store_dwordx4 v209, v[222:225], s[30:31]
	global_store_dwordx4 v210, v[226:229], s[30:31]
	v_cvt_pk_bf16_f32 v214, v4, v5
	v_cvt_pk_bf16_f32 v215, v6, v7
	v_cvt_pk_bf16_f32 v216, v0, v1
	v_cvt_pk_bf16_f32 v217, v2, v3
	v_cvt_pk_bf16_f32 v218, v46, v47
	v_cvt_pk_bf16_f32 v219, v48, v49
	v_cvt_pk_bf16_f32 v220, v50, v51
	v_cvt_pk_bf16_f32 v221, v52, v53
	ds_write_b64 v205, v[214:215]
	ds_write_b64 v205, v[216:217] offset:32
	ds_write_b64 v205, v[218:219] offset:64
	ds_write_b64 v205, v[220:221] offset:96
	ds_read2_b64 v[222:225], v206 offset1:1
	ds_read2_b64 v[226:229], v206 offset0:136 offset1:137
	v_add_u32_e32 v209, 0x30100, v207
	v_add_u32_e32 v210, 0x30100, v208
	s_waitcnt lgkmcnt(0)
	global_store_dwordx4 v209, v[222:225], s[30:31]
	global_store_dwordx4 v210, v[226:229], s[30:31]
	s_waitcnt vmcnt(16)
	s_branch .LBB0_385

; #define LAS __attribute__((address_space(3)))
; __global__ void __launch_bounds__(NTHREADS) fwd_kernel(Params p) {
;     __shared__ __attribute__((aligned(16))) char lds[LDS_BYTES];
;     cg::grid_group grid = cg::this_grid();
;     __shared__ __attribute__((aligned(16))) unsigned xb_words[4];
;     if (threadIdx.x < 4) xb_words[threadIdx.x] = 0u;
;     __syncthreads();
;     const int g_wave = __builtin_amdgcn_readfirstlane((int)(threadIdx.x >> 6));
;     (void)xcd_barrier_post((unsigned*)(p.ws + OFF_BAR), (volatile LAS unsigned*)&xb_words, g_wave);
	.amdhsa_kernel _Z10fwd_kernel6Params
		.amdhsa_group_segment_fixed_size 163840
		.amdhsa_private_segment_fixed_size 0
		.amdhsa_kernarg_size 384
		.amdhsa_user_sgpr_count 2
		.amdhsa_user_sgpr_dispatch_ptr 0
		.amdhsa_user_sgpr_queue_ptr 0
		.amdhsa_user_sgpr_kernarg_segment_ptr 1
		.amdhsa_user_sgpr_dispatch_id 0
		.amdhsa_user_sgpr_kernarg_preload_length 0
		.amdhsa_user_sgpr_kernarg_preload_offset 0
		.amdhsa_user_sgpr_private_segment_size 0
		.amdhsa_uses_dynamic_stack 0
		.amdhsa_enable_private_segment 0
		.amdhsa_system_sgpr_workgroup_id_x 1
		.amdhsa_system_sgpr_workgroup_id_y 0
		.amdhsa_system_sgpr_workgroup_id_z 0
		.amdhsa_system_sgpr_workgroup_info 0
		.amdhsa_system_vgpr_workitem_id 2
		.amdhsa_next_free_vgpr 256
		.amdhsa_next_free_sgpr 102
		.amdhsa_accum_offset 256
		.amdhsa_reserve_vcc 1
		.amdhsa_float_round_mode_32 0
		.amdhsa_float_round_mode_16_64 0
		.amdhsa_float_denorm_mode_32 3
		.amdhsa_float_denorm_mode_16_64 3
		.amdhsa_dx10_clamp 1
		.amdhsa_ieee_mode 1
		.amdhsa_fp16_overflow 0
		.amdhsa_tg_split 0
		.amdhsa_exception_fp_ieee_invalid_op 0
		.amdhsa_exception_fp_denorm_src 0
		.amdhsa_exception_fp_ieee_div_zero 0
		.amdhsa_exception_fp_ieee_overflow 0
		.amdhsa_exception_fp_ieee_underflow 0
		.amdhsa_exception_fp_ieee_inexact 0
		.amdhsa_exception_int_div_zero 0
	.end_amdhsa_kernel

; #define LAS __attribute__((address_space(3)))
; __global__ void __launch_bounds__(NTHREADS) fwd_kernel(Params p) {
;     __shared__ __attribute__((aligned(16))) char lds[LDS_BYTES];
;     cg::grid_group grid = cg::this_grid();
;     __shared__ __attribute__((aligned(16))) unsigned xb_words[4];
;     if (threadIdx.x < 4) xb_words[threadIdx.x] = 0u;
;     __syncthreads();
;     const int g_wave = __builtin_amdgcn_readfirstlane((int)(threadIdx.x >> 6));
;     (void)xcd_barrier_post((unsigned*)(p.ws + OFF_BAR), (volatile LAS unsigned*)&xb_words, g_wave);
amdhsa.kernels:
  - .agpr_count:     0
    .args:
      - .offset:         0
        .size:           128
        .value_kind:     by_value
      - .offset:         128
        .size:           4
        .value_kind:     hidden_block_count_x
      - .offset:         132
        .size:           4
        .value_kind:     hidden_block_count_y
      - .offset:         136
        .size:           4
        .value_kind:     hidden_block_count_z
      - .offset:         140
        .size:           2
        .value_kind:     hidden_group_size_x
      - .offset:         142
        .size:           2
        .value_kind:     hidden_group_size_y
      - .offset:         144
        .size:           2
        .value_kind:     hidden_group_size_z
      - .offset:         146
        .size:           2
        .value_kind:     hidden_remainder_x
      - .offset:         148
        .size:           2
        .value_kind:     hidden_remainder_y
      - .offset:         150
        .size:           2
        .value_kind:     hidden_remainder_z
      - .offset:         168
        .size:           8
        .value_kind:     hidden_global_offset_x
      - .offset:         176
        .size:           8
        .value_kind:     hidden_global_offset_y
      - .offset:         184
        .size:           8
        .value_kind:     hidden_global_offset_z
      - .offset:         192
        .size:           2
        .value_kind:     hidden_grid_dims
      - .offset:         216
        .size:           8
        .value_kind:     hidden_multigrid_sync_arg
    .group_segment_fixed_size: 163840
    .kernarg_segment_align: 8
    .kernarg_segment_size: 384
    .language:       OpenCL C
    .language_version:
      - 2
      - 0
    .max_flat_workgroup_size: 512
    .name:           _Z10fwd_kernel6Params
    .private_segment_fixed_size: 0
    .sgpr_count:     108
    .sgpr_spill_count: 98
    .symbol:         _Z10fwd_kernel6Params.kd
    .uniform_work_group_size: 1
    .uses_dynamic_stack: false
    .vgpr_count:     256
    .vgpr_spill_count: 0
    .wavefront_size: 64
